# GEMM loops: 69 LDS-DMA loads use SGPR base + 32-bit lane offset (saddr form) instead of a v_lshl_add_u64 per load
# baseline (speedup 1.0000x reference)
.LBB0_72:
	s_ashr_i32 s5, s22, 31
	v_writelane_b32 v242, s5, 10
	s_ashr_i32 s5, s2, 31
	s_add_u32 s6, s28, 0x1ae40000
	v_writelane_b32 v242, s5, 11
	s_addc_u32 s7, s29, 0
	v_writelane_b32 v242, s6, 12
	s_waitcnt lgkmcnt(0)
	s_mov_b64 s[68:69], 0x80
	v_lshl_add_u64 v[6:7], v[6:7], 0, s[68:69]
	v_writelane_b32 v242, s7, 13
	s_add_u32 s6, s28, 0x19e00000
	s_addc_u32 s7, s29, 0
	v_writelane_b32 v242, s6, 14
	s_waitcnt vmcnt(2)
	s_barrier
	v_lshl_add_u64 v[4:5], v[4:5], 0, s[68:69]
	v_writelane_b32 v242, s7, 15
	s_add_u32 s6, s28, 0x1be80000
	s_addc_u32 s7, s29, 0
	v_writelane_b32 v242, s6, 16
	v_lshl_add_u64 v[2:3], v[2:3], 0, s[68:69]
	v_lshl_add_u64 v[0:1], v[0:1], 0, s[68:69]
	v_writelane_b32 v242, s7, 17
	s_add_u32 s6, s28, 0xfb00000
	s_addc_u32 s7, s29, 0
	v_writelane_b32 v242, s6, 18
	v_mov_b32_e32 v151, v149
	v_mov_b32_e32 v153, v149
	v_writelane_b32 v242, s7, 19
	s_add_u32 s6, s28, 0xda00000
	s_addc_u32 s7, s29, 0
	v_writelane_b32 v242, s6, 20
	v_mov_b64_e32 v[154:155], 0xa0e
	v_mov_b64_e32 v[156:157], 0xa0d
	v_writelane_b32 v242, s7, 21
	s_add_u32 s6, s28, 0x15d00000
	s_addc_u32 s7, s29, 0
	v_writelane_b32 v242, s6, 22
	s_movk_i32 s65, 0x420
	v_mov_b32_e32 v166, 0x358637bd
	v_writelane_b32 v242, s7, 23
	s_add_u32 s6, s28, 0x11c00000
	s_addc_u32 s7, s29, 0
	v_writelane_b32 v242, s6, 24
	s_mov_b32 s63, 0x800000
	s_nop 0
	v_writelane_b32 v242, s7, 25
	s_add_u32 s6, s28, 0xb900000
	s_addc_u32 s7, s29, 0
	v_writelane_b32 v242, s6, 26
	s_and_b32 s8, s4, 3
	s_add_i32 m0, s58, 0x18000
	v_writelane_b32 v242, s7, 27
	s_lshl_b32 s6, s1, 13
	s_lshl_b32 s7, s8, 12
	global_load_lds_dwordx4 v[6:7], off
	s_add_i32 m0, s58, 0x1a000
	s_add_i32 s42, s58, 0x8000
	s_add_i32 s43, s58, 0xa000
	global_load_lds_dwordx4 v[4:5], off
	s_mov_b32 m0, s42
	s_add_u32 s4, s12, 0x80080
	global_load_lds_dwordx4 v[2:3], off
	s_mov_b32 m0, s43
	s_addc_u32 s5, s13, 0
	global_load_lds_dwordx4 v[0:1], off
	s_add_i32 m0, s58, 0x1c000
	s_nop 0
	global_load_lds_dwordx4 v142, s[4:5]
	s_add_i32 m0, s58, 0x1e000
	v_lshlrev_b32_e32 v4, 6, v194
	global_load_lds_dwordx4 v146, s[4:5]
	v_and_b32_e32 v0, 15, v194
	v_lshl_or_b32 v160, s1, 6, v0
	s_or_b32 s1, s8, 0x80
	v_writelane_b32 v242, s1, 28
	s_or_b32 s1, s8, 0x100
	v_bfe_u32 v1, v194, 4, 2
	v_writelane_b32 v242, s1, 29
	s_or_b32 s1, s8, 0x180
	v_lshlrev_b32_e32 v3, 4, v1
	s_movk_i32 s4, 0x3c0
	v_writelane_b32 v242, s1, 30
	s_or_b32 s1, s8, 0x400
	v_lshlrev_b32_e32 v2, 3, v1
	v_and_or_b32 v4, v4, s4, v3
	v_cmp_eq_u32_e64 s[4:5], 0, v1
	v_writelane_b32 v242, s1, 31
	s_or_b32 s1, s8, 0x480
	v_lshlrev_b32_e32 v1, 9, v194
	v_writelane_b32 v242, s1, 32
	s_or_b32 s1, s8, 0x500
	v_lshl_or_b32 v162, s8, 5, v2
	v_and_b32_e32 v1, 0x70000, v1
	v_lshlrev_b32_e32 v2, 12, v10
	v_lshlrev_b32_e32 v5, 2, v194
	v_writelane_b32 v242, s1, 33
	s_or_b32 s1, s8, 0x580
	v_or3_b32 v1, v8, v1, v2
	v_and_b32_e32 v5, 32, v5
	v_lshl_or_b32 v0, v0, 6, v3
	s_cmpk_lt_u32 s0, 0x100
	v_add_u32_e32 v150, v1, v9
	v_lshlrev_b32_e32 v1, 5, v11
	v_bitop3_b32 v0, v0, s6, v5 bitop3:0xde
	s_waitcnt vmcnt(6)
	s_cselect_b64 s[70:71], -1, 0
	s_cmp_lt_u32 s8, 2
	v_and_b32_e32 v1, 0xf0000, v1
	v_bitop3_b32 v161, s7, v4, v5 bitop3:0xf6
	v_writelane_b32 v242, s1, 34
	s_cselect_b64 s[6:7], -1, 0
	v_or3_b32 v1, v8, v1, v2
	s_add_i32 s1, 0, 0x10000
	s_add_i32 s64, 0, 0x14000
	v_add_u32_e32 v165, 0, v0
	v_mbcnt_lo_u32_b32 v0, -1, 0
	v_add_u32_e32 v152, v1, v9
	v_add_u32_e32 v163, s1, v161
	v_add_u32_e32 v164, s64, v161
	v_mbcnt_hi_u32_b32 v167, -1, v0
	s_mov_b32 s0, 0
	s_barrier
	v_writelane_b32 v242, s8, 35
	s_branch .LBB0_75

.LBB0_82:
	s_waitcnt vmcnt(0)
	ds_read_b128 v[48:51], v163
	ds_read_b128 v[52:55], v163 offset:1024
	ds_read_b128 v[136:139], v163 offset:2048
	ds_read_b128 v[168:171], v163 offset:3072
	ds_read_b128 v[172:175], v164
	ds_read_b128 v[176:179], v164 offset:1024
	ds_read_b128 v[180:183], v164 offset:2048
	ds_read_b128 v[184:187], v164 offset:3072
	s_add_u32 s12, s10, 0xfff80080
	s_addc_u32 s13, s11, -1
	s_cmp_eq_u32 s34, 28
	s_cselect_b32 s15, s17, s13
	s_cselect_b32 s14, s19, s12
	s_cselect_b32 s13, s20, s25
	s_cselect_b32 s12, s21, s24
	s_add_i32 m0, s58, 0xc000
	ds_read_b128 v[188:191], v165
	ds_read_b128 v[196:199], v165 offset:1024
	ds_read_b128 v[200:203], v165 offset:2048
	ds_read_b128 v[204:207], v165 offset:3072
	ds_read_b128 v[212:215], v165 offset:4096
	ds_read_b128 v[216:219], v165 offset:5120
	ds_read_b128 v[220:223], v165 offset:6144
	ds_read_b128 v[224:227], v165 offset:7168
	global_load_lds_dwordx4 v150, s[10:11]
	s_add_i32 m0, s58, 0xe000
	s_nop 0
	global_load_lds_dwordx4 v152, s[10:11]
	s_waitcnt vmcnt(8)
	s_waitcnt lgkmcnt(0)
	s_barrier
	s_setprio 1
	s_waitcnt lgkmcnt(0)
	v_mfma_f32_16x16x32_bf16 v[132:135], v[48:51], v[188:191], v[132:135]
	v_mfma_f32_16x16x32_bf16 v[128:131], v[136:139], v[188:191], v[128:131]
	v_mfma_f32_16x16x32_bf16 v[116:119], v[48:51], v[200:203], v[116:119]
	v_mfma_f32_16x16x32_bf16 v[112:115], v[136:139], v[200:203], v[112:115]
	v_mfma_f32_16x16x32_bf16 v[100:103], v[48:51], v[212:215], v[100:103]
	v_mfma_f32_16x16x32_bf16 v[96:99], v[136:139], v[212:215], v[96:99]
	v_mfma_f32_16x16x32_bf16 v[84:87], v[48:51], v[220:223], v[84:87]
	v_mfma_f32_16x16x32_bf16 v[80:83], v[136:139], v[220:223], v[80:83]
	v_mfma_f32_16x16x32_bf16 v[132:135], v[52:55], v[196:199], v[132:135]
	v_mfma_f32_16x16x32_bf16 v[128:131], v[168:171], v[196:199], v[128:131]
	v_mfma_f32_16x16x32_bf16 v[116:119], v[52:55], v[204:207], v[116:119]
	v_mfma_f32_16x16x32_bf16 v[112:115], v[168:171], v[204:207], v[112:115]
	v_mfma_f32_16x16x32_bf16 v[100:103], v[52:55], v[216:219], v[100:103]
	v_mfma_f32_16x16x32_bf16 v[96:99], v[168:171], v[216:219], v[96:99]
	v_mfma_f32_16x16x32_bf16 v[84:87], v[52:55], v[224:227], v[84:87]
	v_mfma_f32_16x16x32_bf16 v[80:83], v[168:171], v[224:227], v[80:83]
	s_setprio 0
	s_setprio 1
	v_mfma_f32_16x16x32_bf16 v[124:127], v[172:175], v[188:191], v[124:127]
	v_mfma_f32_16x16x32_bf16 v[120:123], v[180:183], v[188:191], v[120:123]
	v_mfma_f32_16x16x32_bf16 v[108:111], v[172:175], v[200:203], v[108:111]
	v_mfma_f32_16x16x32_bf16 v[104:107], v[180:183], v[200:203], v[104:107]
	v_mfma_f32_16x16x32_bf16 v[92:95], v[172:175], v[212:215], v[92:95]
	v_mfma_f32_16x16x32_bf16 v[88:91], v[180:183], v[212:215], v[88:91]
	v_mfma_f32_16x16x32_bf16 v[76:79], v[172:175], v[220:223], v[76:79]
	v_mfma_f32_16x16x32_bf16 v[72:75], v[180:183], v[220:223], v[72:75]
	v_mfma_f32_16x16x32_bf16 v[124:127], v[176:179], v[196:199], v[124:127]
	v_mfma_f32_16x16x32_bf16 v[120:123], v[184:187], v[196:199], v[120:123]
	v_mfma_f32_16x16x32_bf16 v[108:111], v[176:179], v[204:207], v[108:111]
	v_mfma_f32_16x16x32_bf16 v[104:107], v[184:187], v[204:207], v[104:107]
	v_mfma_f32_16x16x32_bf16 v[92:95], v[176:179], v[216:219], v[92:95]
	v_mfma_f32_16x16x32_bf16 v[88:91], v[184:187], v[216:219], v[88:91]
	v_mfma_f32_16x16x32_bf16 v[76:79], v[176:179], v[224:227], v[76:79]
	v_mfma_f32_16x16x32_bf16 v[72:75], v[184:187], v[224:227], v[72:75]
	s_setprio 0
	s_barrier
	s_add_i32 s35, s1, s33
	v_lshl_add_u64 v[158:159], s[12:13], 0, v[142:143]
	s_mov_b32 m0, s35
	ds_read_b128 v[188:191], v165 offset:16384
	ds_read_b128 v[196:199], v165 offset:17408
	ds_read_b128 v[200:203], v165 offset:18432
	ds_read_b128 v[204:207], v165 offset:19456
	ds_read_b128 v[212:215], v165 offset:20480
	ds_read_b128 v[216:219], v165 offset:21504
	ds_read_b128 v[220:223], v165 offset:22528
	ds_read_b128 v[224:227], v165 offset:23552
	global_load_lds_dwordx4 v[158:159], off
	s_add_i32 m0, s35, 0x2000
	s_add_u32 s44, s12, 0x80000
	v_lshl_add_u64 v[192:193], s[12:13], 0, v[146:147]
	s_addc_u32 s45, s13, 0
	s_add_i32 s35, s64, s33
	global_load_lds_dwordx4 v[192:193], off
	s_mov_b32 m0, s35
	v_lshl_add_u64 v[228:229], s[14:15], 0, v[144:145]
	global_load_lds_dwordx4 v142, s[44:45]
	s_add_i32 m0, s35, 0x2000
	s_nop 0
	global_load_lds_dwordx4 v146, s[44:45]
	v_lshl_add_u64 v[208:209], s[14:15], 0, v[140:141]
	s_mov_b32 m0, s58
	s_nop 0
	global_load_lds_dwordx4 v[208:209], off
	s_mov_b32 m0, s59
	s_nop 0
	global_load_lds_dwordx4 v[228:229], off
	s_waitcnt vmcnt(8)
	s_waitcnt lgkmcnt(0)
	s_barrier
	s_setprio 1
	s_waitcnt lgkmcnt(0)
	v_mfma_f32_16x16x32_bf16 v[68:71], v[48:51], v[188:191], v[68:71]
	v_mfma_f32_16x16x32_bf16 v[64:67], v[136:139], v[188:191], v[64:67]
	v_mfma_f32_16x16x32_bf16 v[44:47], v[48:51], v[200:203], v[44:47]
	v_mfma_f32_16x16x32_bf16 v[40:43], v[136:139], v[200:203], v[40:43]
	v_mfma_f32_16x16x32_bf16 v[28:31], v[48:51], v[212:215], v[28:31]
	v_mfma_f32_16x16x32_bf16 v[24:27], v[136:139], v[212:215], v[24:27]
	v_mfma_f32_16x16x32_bf16 v[12:15], v[48:51], v[220:223], v[12:15]
	v_mfma_f32_16x16x32_bf16 v[8:11], v[136:139], v[220:223], v[8:11]
	v_mfma_f32_16x16x32_bf16 v[68:71], v[52:55], v[196:199], v[68:71]
	v_mfma_f32_16x16x32_bf16 v[64:67], v[168:171], v[196:199], v[64:67]
	v_mfma_f32_16x16x32_bf16 v[44:47], v[52:55], v[204:207], v[44:47]
	v_mfma_f32_16x16x32_bf16 v[40:43], v[168:171], v[204:207], v[40:43]
	v_mfma_f32_16x16x32_bf16 v[28:31], v[52:55], v[216:219], v[28:31]
	v_mfma_f32_16x16x32_bf16 v[24:27], v[168:171], v[216:219], v[24:27]
	v_mfma_f32_16x16x32_bf16 v[12:15], v[52:55], v[224:227], v[12:15]
	v_mfma_f32_16x16x32_bf16 v[8:11], v[168:171], v[224:227], v[8:11]
	s_setprio 0
	s_setprio 1
	v_mfma_f32_16x16x32_bf16 v[36:39], v[172:175], v[200:203], v[36:39]
	v_mfma_f32_16x16x32_bf16 v[32:35], v[180:183], v[200:203], v[32:35]
	v_mfma_f32_16x16x32_bf16 v[20:23], v[172:175], v[212:215], v[20:23]
	v_mfma_f32_16x16x32_bf16 v[16:19], v[180:183], v[212:215], v[16:19]
	v_mfma_f32_16x16x32_bf16 v[4:7], v[172:175], v[220:223], v[4:7]
	v_mfma_f32_16x16x32_bf16 v[0:3], v[180:183], v[220:223], v[0:3]
	v_mfma_f32_16x16x32_bf16 v[48:51], v[172:175], v[188:191], v[60:63]
	v_mfma_f32_16x16x32_bf16 v[52:55], v[180:183], v[188:191], v[56:59]
	v_mfma_f32_16x16x32_bf16 v[36:39], v[176:179], v[204:207], v[36:39]
	v_mfma_f32_16x16x32_bf16 v[32:35], v[184:187], v[204:207], v[32:35]
	v_mfma_f32_16x16x32_bf16 v[20:23], v[176:179], v[216:219], v[20:23]
	v_mfma_f32_16x16x32_bf16 v[16:19], v[184:187], v[216:219], v[16:19]
	v_mfma_f32_16x16x32_bf16 v[4:7], v[176:179], v[224:227], v[4:7]
	v_mfma_f32_16x16x32_bf16 v[0:3], v[184:187], v[224:227], v[0:3]
	v_mfma_f32_16x16x32_bf16 v[48:51], v[176:179], v[196:199], v[48:51]
	v_mfma_f32_16x16x32_bf16 v[52:55], v[184:187], v[196:199], v[52:55]
	s_setprio 0
	s_barrier
	s_add_i32 s35, 0, 0x18000
	v_add_u32_e32 v148, s35, v161
	s_add_i32 s44, 0, 0x1c000
	ds_read_b128 v[56:59], v148
	ds_read_b128 v[60:63], v148 offset:1024
	ds_read_b128 v[136:139], v148 offset:2048
	ds_read_b128 v[168:171], v148 offset:3072
	v_add_u32_e32 v148, s44, v161
	ds_read_b128 v[172:175], v148
	ds_read_b128 v[176:179], v148 offset:1024
	ds_read_b128 v[180:183], v148 offset:2048
	ds_read_b128 v[184:187], v148 offset:3072
	s_add_u32 s14, s14, 0x80000
	s_addc_u32 s15, s15, 0
	s_mov_b32 m0, s60
	ds_read_b128 v[188:191], v165 offset:32768
	ds_read_b128 v[196:199], v165 offset:33792
	ds_read_b128 v[200:203], v165 offset:34816
	ds_read_b128 v[204:207], v165 offset:35840
	ds_read_b128 v[212:215], v165 offset:36864
	ds_read_b128 v[216:219], v165 offset:37888
	ds_read_b128 v[220:223], v165 offset:38912
	ds_read_b128 v[224:227], v165 offset:39936
	global_load_lds_dwordx4 v140, s[14:15]
	v_lshl_add_u64 v[230:231], s[14:15], 0, v[144:145]
	s_mov_b32 m0, s61
	s_nop 0
	global_load_lds_dwordx4 v[230:231], off
	s_waitcnt vmcnt(8)
	s_waitcnt lgkmcnt(0)
	s_barrier
	s_setprio 1
	s_waitcnt lgkmcnt(0)
	v_mfma_f32_16x16x32_bf16 v[132:135], v[56:59], v[188:191], v[132:135]
	v_mfma_f32_16x16x32_bf16 v[128:131], v[136:139], v[188:191], v[128:131]
	v_mfma_f32_16x16x32_bf16 v[116:119], v[56:59], v[200:203], v[116:119]
	v_mfma_f32_16x16x32_bf16 v[112:115], v[136:139], v[200:203], v[112:115]
	v_mfma_f32_16x16x32_bf16 v[100:103], v[56:59], v[212:215], v[100:103]
	v_mfma_f32_16x16x32_bf16 v[96:99], v[136:139], v[212:215], v[96:99]
	v_mfma_f32_16x16x32_bf16 v[84:87], v[56:59], v[220:223], v[84:87]
	v_mfma_f32_16x16x32_bf16 v[80:83], v[136:139], v[220:223], v[80:83]
	v_mfma_f32_16x16x32_bf16 v[132:135], v[60:63], v[196:199], v[132:135]
	v_mfma_f32_16x16x32_bf16 v[128:131], v[168:171], v[196:199], v[128:131]
	v_mfma_f32_16x16x32_bf16 v[116:119], v[60:63], v[204:207], v[116:119]
	v_mfma_f32_16x16x32_bf16 v[112:115], v[168:171], v[204:207], v[112:115]
	v_mfma_f32_16x16x32_bf16 v[100:103], v[60:63], v[216:219], v[100:103]
	v_mfma_f32_16x16x32_bf16 v[96:99], v[168:171], v[216:219], v[96:99]
	v_mfma_f32_16x16x32_bf16 v[84:87], v[60:63], v[224:227], v[84:87]
	v_mfma_f32_16x16x32_bf16 v[80:83], v[168:171], v[224:227], v[80:83]
	s_setprio 0
	s_setprio 1
	v_mfma_f32_16x16x32_bf16 v[124:127], v[172:175], v[188:191], v[124:127]
	v_mfma_f32_16x16x32_bf16 v[120:123], v[180:183], v[188:191], v[120:123]
	v_mfma_f32_16x16x32_bf16 v[108:111], v[172:175], v[200:203], v[108:111]
	v_mfma_f32_16x16x32_bf16 v[104:107], v[180:183], v[200:203], v[104:107]
	v_mfma_f32_16x16x32_bf16 v[92:95], v[172:175], v[212:215], v[92:95]
	v_mfma_f32_16x16x32_bf16 v[88:91], v[180:183], v[212:215], v[88:91]
	v_mfma_f32_16x16x32_bf16 v[76:79], v[172:175], v[220:223], v[76:79]
	v_mfma_f32_16x16x32_bf16 v[72:75], v[180:183], v[220:223], v[72:75]
	v_mfma_f32_16x16x32_bf16 v[124:127], v[176:179], v[196:199], v[124:127]
	v_mfma_f32_16x16x32_bf16 v[120:123], v[184:187], v[196:199], v[120:123]
	v_mfma_f32_16x16x32_bf16 v[108:111], v[176:179], v[204:207], v[108:111]
	v_mfma_f32_16x16x32_bf16 v[104:107], v[184:187], v[204:207], v[104:107]
	v_mfma_f32_16x16x32_bf16 v[92:95], v[176:179], v[216:219], v[92:95]
	v_mfma_f32_16x16x32_bf16 v[88:91], v[184:187], v[216:219], v[88:91]
	v_mfma_f32_16x16x32_bf16 v[76:79], v[176:179], v[224:227], v[76:79]
	v_mfma_f32_16x16x32_bf16 v[72:75], v[184:187], v[224:227], v[72:75]
	s_setprio 0
	s_barrier
	s_add_i32 s14, s35, s33
	v_lshl_add_u64 v[158:159], v[158:159], 0, s[68:69]
	s_mov_b32 m0, s14
	ds_read_b128 v[188:191], v165 offset:49152
	ds_read_b128 v[196:199], v165 offset:50176
	ds_read_b128 v[200:203], v165 offset:51200
	ds_read_b128 v[204:207], v165 offset:52224
	ds_read_b128 v[212:215], v165 offset:53248
	ds_read_b128 v[216:219], v165 offset:54272
	ds_read_b128 v[220:223], v165 offset:55296
	ds_read_b128 v[224:227], v165 offset:56320
	global_load_lds_dwordx4 v[158:159], off
	s_add_i32 m0, s14, 0x2000
	s_add_u32 s12, s12, 0x80080
	v_lshl_add_u64 v[158:159], v[192:193], 0, s[68:69]
	s_addc_u32 s13, s13, 0
	s_add_i32 s14, s44, s33
	global_load_lds_dwordx4 v[158:159], off
	s_mov_b32 m0, s14
	s_nop 0
	global_load_lds_dwordx4 v142, s[12:13]
	s_add_i32 m0, s14, 0x2000
	s_nop 0
	global_load_lds_dwordx4 v146, s[12:13]
	v_lshl_add_u64 v[158:159], v[208:209], 0, s[68:69]
	s_mov_b32 m0, s42
	s_nop 0
	global_load_lds_dwordx4 v[158:159], off
	v_lshl_add_u64 v[158:159], v[228:229], 0, s[68:69]
	s_mov_b32 m0, s43
	s_nop 0
	global_load_lds_dwordx4 v[158:159], off
	s_waitcnt vmcnt(8)
	s_waitcnt lgkmcnt(0)
	s_barrier
	s_setprio 1
	s_waitcnt lgkmcnt(0)
	v_mfma_f32_16x16x32_bf16 v[68:71], v[56:59], v[188:191], v[68:71]
	v_mfma_f32_16x16x32_bf16 v[64:67], v[136:139], v[188:191], v[64:67]
	v_mfma_f32_16x16x32_bf16 v[44:47], v[56:59], v[200:203], v[44:47]
	v_mfma_f32_16x16x32_bf16 v[40:43], v[136:139], v[200:203], v[40:43]
	v_mfma_f32_16x16x32_bf16 v[28:31], v[56:59], v[212:215], v[28:31]
	v_mfma_f32_16x16x32_bf16 v[24:27], v[136:139], v[212:215], v[24:27]
	v_mfma_f32_16x16x32_bf16 v[12:15], v[56:59], v[220:223], v[12:15]
	v_mfma_f32_16x16x32_bf16 v[8:11], v[136:139], v[220:223], v[8:11]
	v_mfma_f32_16x16x32_bf16 v[68:71], v[60:63], v[196:199], v[68:71]
	v_mfma_f32_16x16x32_bf16 v[64:67], v[168:171], v[196:199], v[64:67]
	v_mfma_f32_16x16x32_bf16 v[44:47], v[60:63], v[204:207], v[44:47]
	v_mfma_f32_16x16x32_bf16 v[40:43], v[168:171], v[204:207], v[40:43]
	v_mfma_f32_16x16x32_bf16 v[28:31], v[60:63], v[216:219], v[28:31]
	v_mfma_f32_16x16x32_bf16 v[24:27], v[168:171], v[216:219], v[24:27]
	v_mfma_f32_16x16x32_bf16 v[12:15], v[60:63], v[224:227], v[12:15]
	v_mfma_f32_16x16x32_bf16 v[8:11], v[168:171], v[224:227], v[8:11]
	s_setprio 0
	s_setprio 1
	v_mfma_f32_16x16x32_bf16 v[48:51], v[172:175], v[188:191], v[48:51]
	v_mfma_f32_16x16x32_bf16 v[60:63], v[176:179], v[196:199], v[48:51]
	v_mfma_f32_16x16x32_bf16 v[48:51], v[180:183], v[188:191], v[52:55]
	v_mfma_f32_16x16x32_bf16 v[36:39], v[172:175], v[200:203], v[36:39]
	v_mfma_f32_16x16x32_bf16 v[32:35], v[180:183], v[200:203], v[32:35]
	v_mfma_f32_16x16x32_bf16 v[20:23], v[172:175], v[212:215], v[20:23]
	v_mfma_f32_16x16x32_bf16 v[16:19], v[180:183], v[212:215], v[16:19]
	v_mfma_f32_16x16x32_bf16 v[4:7], v[172:175], v[220:223], v[4:7]
	v_mfma_f32_16x16x32_bf16 v[0:3], v[180:183], v[220:223], v[0:3]
	v_mfma_f32_16x16x32_bf16 v[56:59], v[184:187], v[196:199], v[48:51]
	v_mfma_f32_16x16x32_bf16 v[36:39], v[176:179], v[204:207], v[36:39]
	v_mfma_f32_16x16x32_bf16 v[32:35], v[184:187], v[204:207], v[32:35]
	v_mfma_f32_16x16x32_bf16 v[20:23], v[176:179], v[216:219], v[20:23]
	v_mfma_f32_16x16x32_bf16 v[16:19], v[184:187], v[216:219], v[16:19]
	v_mfma_f32_16x16x32_bf16 v[4:7], v[176:179], v[224:227], v[4:7]
	v_mfma_f32_16x16x32_bf16 v[0:3], v[184:187], v[224:227], v[0:3]
	s_setprio 0
	s_barrier
	s_add_i32 s34, s34, 2
	s_add_u32 s10, s10, 0x100
	s_addc_u32 s11, s11, 0
	s_add_u32 s24, s24, 0x100
	s_addc_u32 s25, s25, 0
	s_cmp_gt_u32 s34, 29
	s_cbranch_scc0 .LBB0_82
	s_and_b64 vcc, exec, s[70:71]
	s_cbranch_vccz .LBB0_85
	s_barrier

.Lqk_fast:
	v_lshlrev_b32_e32 v24, 4, v55
	v_lshl_add_u32 v25, v56, 2, s66
	ds_read_b32 v16, v25 offset:6400
	ds_read_b32 v17, v25 offset:6464
	ds_read_b32 v18, v25 offset:6528
	ds_read_b32 v19, v25 offset:6592
	s_waitcnt lgkmcnt(3)
	v_add_u32_e32 v26, s42, v16
	v_lshl_add_u32 v26, v26, 9, v24
	global_load_dwordx4 v[130:133], v26, s[44:45]
	global_load_dwordx4 v[134:137], v26, s[44:45] offset:64
	global_load_dwordx4 v[138:141], v26, s[44:45] offset:128
	global_load_dwordx4 v[142:145], v26, s[44:45] offset:192
	s_waitcnt lgkmcnt(2)
	v_add_u32_e32 v27, s42, v17
	v_lshl_add_u32 v27, v27, 9, v24
	global_load_dwordx4 v[146:149], v27, s[44:45]
	global_load_dwordx4 v[150:153], v27, s[44:45] offset:64
	global_load_dwordx4 v[154:157], v27, s[44:45] offset:128
	global_load_dwordx4 v[158:161], v27, s[44:45] offset:192
	s_waitcnt lgkmcnt(1)
	v_add_u32_e32 v28, s42, v18
	v_lshl_add_u32 v28, v28, 9, v24
	global_load_dwordx4 v[162:165], v28, s[44:45]
	global_load_dwordx4 v[166:169], v28, s[44:45] offset:64
	global_load_dwordx4 v[170:173], v28, s[44:45] offset:128
	global_load_dwordx4 v[174:177], v28, s[44:45] offset:192
	s_waitcnt lgkmcnt(0)
	v_add_u32_e32 v29, s42, v19
	v_lshl_add_u32 v29, v29, 9, v24
	global_load_dwordx4 v[178:181], v29, s[44:45]
	global_load_dwordx4 v[182:185], v29, s[44:45] offset:64
	global_load_dwordx4 v[186:189], v29, s[44:45] offset:128
	global_load_dwordx4 v[190:193], v29, s[44:45] offset:192
	ds_read_b32 v20, v25 offset:6656
	ds_read_b32 v21, v25 offset:6720
	ds_read_b32 v22, v25 offset:6784
	ds_read_b32 v23, v25 offset:6848
	s_waitcnt lgkmcnt(3)
	v_add_u32_e32 v26, s42, v20
	v_lshl_add_u32 v26, v26, 9, v24
	global_load_dwordx4 v[210:213], v26, s[44:45]
	global_load_dwordx4 v[214:217], v26, s[44:45] offset:64
	global_load_dwordx4 v[218:221], v26, s[44:45] offset:128
	global_load_dwordx4 v[222:225], v26, s[44:45] offset:192
	s_waitcnt lgkmcnt(2)
	v_add_u32_e32 v27, s42, v21
	v_lshl_add_u32 v27, v27, 9, v24
	global_load_dwordx4 v[226:229], v27, s[44:45]
	global_load_dwordx4 v[230:233], v27, s[44:45] offset:64
	global_load_dwordx4 v[234:237], v27, s[44:45] offset:128
	global_load_dwordx4 v[238:241], v27, s[44:45] offset:192
	s_waitcnt lgkmcnt(1)
	v_add_u32_e32 v28, s42, v22
	v_lshl_add_u32 v28, v28, 9, v24
	global_load_dwordx4 v[70:73], v28, s[44:45]
	global_load_dwordx4 v[74:77], v28, s[44:45] offset:64
	global_load_dwordx4 v[78:81], v28, s[44:45] offset:128
	global_load_dwordx4 v[82:85], v28, s[44:45] offset:192
	s_waitcnt lgkmcnt(0)
	v_add_u32_e32 v29, s42, v23
	v_lshl_add_u32 v29, v29, 9, v24
	global_load_dwordx4 v[196:199], v29, s[44:45]
	global_load_dwordx4 v[200:203], v29, s[44:45] offset:64
	global_load_dwordx4 v[244:247], v29, s[44:45] offset:128
	global_load_dwordx4 v[248:251], v29, s[44:45] offset:192
	v_subrev_u32_e32 v30, s80, v16
	v_max_i32_e32 v30, 0xffffff80, v30
	v_lshl_add_u32 v30, v30, 2, s72
	ds_read2st64_b32 v[40:41], v30 offset0:2 offset1:5
	ds_read2st64_b32 v[42:43], v30 offset0:8 offset1:11
	s_waitcnt vmcnt(31)
	v_mfma_f32_16x16x32_bf16 v[32:35], v[4:7], v[130:133], 0
	s_waitcnt vmcnt(30)
	v_mfma_f32_16x16x32_bf16 v[32:35], v[0:3], v[134:137], v[32:35]
	s_waitcnt vmcnt(29)
	v_mfma_f32_16x16x32_bf16 v[32:35], v[12:15], v[138:141], v[32:35]
	s_waitcnt vmcnt(28)
	v_mfma_f32_16x16x32_bf16 v[32:35], v[8:11], v[142:145], v[32:35]
	s_nop 7
	v_add_u32_e32 v31, 0, v87
	s_waitcnt lgkmcnt(0)
	v_fmamk_f32 v32, v32, 0x3db504f3, v40
	v_fmac_f32_e32 v41, 0x3db504f3, v33
	v_fmamk_f32 v34, v34, 0x3db504f3, v42
	v_fmac_f32_e32 v43, 0x3db504f3, v35
	v_mov_b32_e32 v33, v41
	v_mov_b32_e32 v35, v43
	s_mov_b64 exec, s[6:7]
	ds_write_b128 v31, v[32:35]
	s_mov_b64 exec, -1
	v_subrev_u32_e32 v30, s80, v17
	v_max_i32_e32 v30, 0xffffff80, v30
	v_lshl_add_u32 v30, v30, 2, s72
	ds_read2st64_b32 v[44:45], v30 offset0:2 offset1:5
	ds_read2st64_b32 v[46:47], v30 offset0:8 offset1:11
	s_waitcnt vmcnt(27)
	v_mfma_f32_16x16x32_bf16 v[36:39], v[4:7], v[146:149], 0
	s_waitcnt vmcnt(26)
	v_mfma_f32_16x16x32_bf16 v[36:39], v[0:3], v[150:153], v[36:39]
	s_waitcnt vmcnt(25)
	v_mfma_f32_16x16x32_bf16 v[36:39], v[12:15], v[154:157], v[36:39]
	s_waitcnt vmcnt(24)
	v_mfma_f32_16x16x32_bf16 v[36:39], v[8:11], v[158:161], v[36:39]
	s_nop 7
	v_add_u32_e32 v31, 256, v87
	s_waitcnt lgkmcnt(0)
	v_fmamk_f32 v36, v36, 0x3db504f3, v44
	v_fmac_f32_e32 v45, 0x3db504f3, v37
	v_fmamk_f32 v38, v38, 0x3db504f3, v46
	v_fmac_f32_e32 v47, 0x3db504f3, v39
	v_mov_b32_e32 v37, v45
	v_mov_b32_e32 v39, v47
	s_mov_b64 exec, s[6:7]
	ds_write_b128 v31, v[36:39]
	s_mov_b64 exec, -1
	v_subrev_u32_e32 v30, s80, v18
	v_max_i32_e32 v30, 0xffffff80, v30
	v_lshl_add_u32 v30, v30, 2, s72
	ds_read2st64_b32 v[40:41], v30 offset0:2 offset1:5
	ds_read2st64_b32 v[42:43], v30 offset0:8 offset1:11
	s_waitcnt vmcnt(23)
	v_mfma_f32_16x16x32_bf16 v[32:35], v[4:7], v[162:165], 0
	s_waitcnt vmcnt(22)
	v_mfma_f32_16x16x32_bf16 v[32:35], v[0:3], v[166:169], v[32:35]
	s_waitcnt vmcnt(21)
	v_mfma_f32_16x16x32_bf16 v[32:35], v[12:15], v[170:173], v[32:35]
	s_waitcnt vmcnt(20)
	v_mfma_f32_16x16x32_bf16 v[32:35], v[8:11], v[174:177], v[32:35]
	s_nop 7
	v_add_u32_e32 v31, 512, v87
	s_waitcnt lgkmcnt(0)
	v_fmamk_f32 v32, v32, 0x3db504f3, v40
	v_fmac_f32_e32 v41, 0x3db504f3, v33
	v_fmamk_f32 v34, v34, 0x3db504f3, v42
	v_fmac_f32_e32 v43, 0x3db504f3, v35
	v_mov_b32_e32 v33, v41
	v_mov_b32_e32 v35, v43
	s_mov_b64 exec, s[6:7]
	ds_write_b128 v31, v[32:35]
	s_mov_b64 exec, -1
	v_subrev_u32_e32 v30, s80, v19
	v_max_i32_e32 v30, 0xffffff80, v30
	v_lshl_add_u32 v30, v30, 2, s72
	ds_read2st64_b32 v[44:45], v30 offset0:2 offset1:5
	ds_read2st64_b32 v[46:47], v30 offset0:8 offset1:11
	s_waitcnt vmcnt(19)
	v_mfma_f32_16x16x32_bf16 v[36:39], v[4:7], v[178:181], 0
	s_waitcnt vmcnt(18)
	v_mfma_f32_16x16x32_bf16 v[36:39], v[0:3], v[182:185], v[36:39]
	s_waitcnt vmcnt(17)
	v_mfma_f32_16x16x32_bf16 v[36:39], v[12:15], v[186:189], v[36:39]
	s_waitcnt vmcnt(16)
	v_mfma_f32_16x16x32_bf16 v[36:39], v[8:11], v[190:193], v[36:39]
	s_nop 7
	v_add_u32_e32 v31, 768, v87
	s_waitcnt lgkmcnt(0)
	v_fmamk_f32 v36, v36, 0x3db504f3, v44
	v_fmac_f32_e32 v45, 0x3db504f3, v37
	v_fmamk_f32 v38, v38, 0x3db504f3, v46
	v_fmac_f32_e32 v47, 0x3db504f3, v39
	v_mov_b32_e32 v37, v45
	v_mov_b32_e32 v39, v47
	s_mov_b64 exec, s[6:7]
	ds_write_b128 v31, v[36:39]
	s_mov_b64 exec, -1
	ds_read_b32 v16, v25 offset:6912
	ds_read_b32 v17, v25 offset:6976
	ds_read_b32 v18, v25 offset:7040
	ds_read_b32 v19, v25 offset:7104
	s_waitcnt lgkmcnt(3)
	v_add_u32_e32 v26, s42, v16
	v_lshl_add_u32 v26, v26, 9, v24
	global_load_dwordx4 v[130:133], v26, s[44:45]
	global_load_dwordx4 v[134:137], v26, s[44:45] offset:64
	global_load_dwordx4 v[138:141], v26, s[44:45] offset:128
	global_load_dwordx4 v[142:145], v26, s[44:45] offset:192
	s_waitcnt lgkmcnt(2)
	v_add_u32_e32 v27, s42, v17
	v_lshl_add_u32 v27, v27, 9, v24
	global_load_dwordx4 v[146:149], v27, s[44:45]
	global_load_dwordx4 v[150:153], v27, s[44:45] offset:64
	global_load_dwordx4 v[154:157], v27, s[44:45] offset:128
	global_load_dwordx4 v[158:161], v27, s[44:45] offset:192
	s_waitcnt lgkmcnt(1)
	v_add_u32_e32 v28, s42, v18
	v_lshl_add_u32 v28, v28, 9, v24
	global_load_dwordx4 v[162:165], v28, s[44:45]
	global_load_dwordx4 v[166:169], v28, s[44:45] offset:64
	global_load_dwordx4 v[170:173], v28, s[44:45] offset:128
	global_load_dwordx4 v[174:177], v28, s[44:45] offset:192
	s_waitcnt lgkmcnt(0)
	v_add_u32_e32 v29, s42, v19
	v_lshl_add_u32 v29, v29, 9, v24
	global_load_dwordx4 v[178:181], v29, s[44:45]
	global_load_dwordx4 v[182:185], v29, s[44:45] offset:64
	global_load_dwordx4 v[186:189], v29, s[44:45] offset:128
	global_load_dwordx4 v[190:193], v29, s[44:45] offset:192
	v_subrev_u32_e32 v30, s80, v20
	v_max_i32_e32 v30, 0xffffff80, v30
	v_lshl_add_u32 v30, v30, 2, s72
	ds_read2st64_b32 v[40:41], v30 offset0:2 offset1:5
	ds_read2st64_b32 v[42:43], v30 offset0:8 offset1:11
	s_waitcnt vmcnt(31)
	v_mfma_f32_16x16x32_bf16 v[32:35], v[4:7], v[210:213], 0
	s_waitcnt vmcnt(30)
	v_mfma_f32_16x16x32_bf16 v[32:35], v[0:3], v[214:217], v[32:35]
	s_waitcnt vmcnt(29)
	v_mfma_f32_16x16x32_bf16 v[32:35], v[12:15], v[218:221], v[32:35]
	s_waitcnt vmcnt(28)
	v_mfma_f32_16x16x32_bf16 v[32:35], v[8:11], v[222:225], v[32:35]
	s_nop 7
	v_add_u32_e32 v31, 1024, v87
	s_waitcnt lgkmcnt(0)
	v_fmamk_f32 v32, v32, 0x3db504f3, v40
	v_fmac_f32_e32 v41, 0x3db504f3, v33
	v_fmamk_f32 v34, v34, 0x3db504f3, v42
	v_fmac_f32_e32 v43, 0x3db504f3, v35
	v_mov_b32_e32 v33, v41
	v_mov_b32_e32 v35, v43
	s_mov_b64 exec, s[6:7]
	ds_write_b128 v31, v[32:35]
	s_mov_b64 exec, -1
	v_subrev_u32_e32 v30, s80, v21
	v_max_i32_e32 v30, 0xffffff80, v30
	v_lshl_add_u32 v30, v30, 2, s72
	ds_read2st64_b32 v[44:45], v30 offset0:2 offset1:5
	ds_read2st64_b32 v[46:47], v30 offset0:8 offset1:11
	s_waitcnt vmcnt(27)
	v_mfma_f32_16x16x32_bf16 v[36:39], v[4:7], v[226:229], 0
	s_waitcnt vmcnt(26)
	v_mfma_f32_16x16x32_bf16 v[36:39], v[0:3], v[230:233], v[36:39]
	s_waitcnt vmcnt(25)
	v_mfma_f32_16x16x32_bf16 v[36:39], v[12:15], v[234:237], v[36:39]
	s_waitcnt vmcnt(24)
	v_mfma_f32_16x16x32_bf16 v[36:39], v[8:11], v[238:241], v[36:39]
	s_nop 7
	v_add_u32_e32 v31, 1280, v87
	s_waitcnt lgkmcnt(0)
	v_fmamk_f32 v36, v36, 0x3db504f3, v44
	v_fmac_f32_e32 v45, 0x3db504f3, v37
	v_fmamk_f32 v38, v38, 0x3db504f3, v46
	v_fmac_f32_e32 v47, 0x3db504f3, v39
	v_mov_b32_e32 v37, v45
	v_mov_b32_e32 v39, v47
	s_mov_b64 exec, s[6:7]
	ds_write_b128 v31, v[36:39]
	s_mov_b64 exec, -1
	v_subrev_u32_e32 v30, s80, v22
	v_max_i32_e32 v30, 0xffffff80, v30
	v_lshl_add_u32 v30, v30, 2, s72
	ds_read2st64_b32 v[40:41], v30 offset0:2 offset1:5
	ds_read2st64_b32 v[42:43], v30 offset0:8 offset1:11
	s_waitcnt vmcnt(23)
	v_mfma_f32_16x16x32_bf16 v[32:35], v[4:7], v[70:73], 0
	s_waitcnt vmcnt(22)
	v_mfma_f32_16x16x32_bf16 v[32:35], v[0:3], v[74:77], v[32:35]
	s_waitcnt vmcnt(21)
	v_mfma_f32_16x16x32_bf16 v[32:35], v[12:15], v[78:81], v[32:35]
	s_waitcnt vmcnt(20)
	v_mfma_f32_16x16x32_bf16 v[32:35], v[8:11], v[82:85], v[32:35]
	s_nop 7
	v_add_u32_e32 v31, 1536, v87
	s_waitcnt lgkmcnt(0)
	v_fmamk_f32 v32, v32, 0x3db504f3, v40
	v_fmac_f32_e32 v41, 0x3db504f3, v33
	v_fmamk_f32 v34, v34, 0x3db504f3, v42
	v_fmac_f32_e32 v43, 0x3db504f3, v35
	v_mov_b32_e32 v33, v41
	v_mov_b32_e32 v35, v43
	s_mov_b64 exec, s[6:7]
	ds_write_b128 v31, v[32:35]
	s_mov_b64 exec, -1
	v_subrev_u32_e32 v30, s80, v23
	v_max_i32_e32 v30, 0xffffff80, v30
	v_lshl_add_u32 v30, v30, 2, s72
	ds_read2st64_b32 v[44:45], v30 offset0:2 offset1:5
	ds_read2st64_b32 v[46:47], v30 offset0:8 offset1:11
	s_waitcnt vmcnt(19)
	v_mfma_f32_16x16x32_bf16 v[36:39], v[4:7], v[196:199], 0
	s_waitcnt vmcnt(18)
	v_mfma_f32_16x16x32_bf16 v[36:39], v[0:3], v[200:203], v[36:39]
	s_waitcnt vmcnt(17)
	v_mfma_f32_16x16x32_bf16 v[36:39], v[12:15], v[244:247], v[36:39]
	s_waitcnt vmcnt(16)
	v_mfma_f32_16x16x32_bf16 v[36:39], v[8:11], v[248:251], v[36:39]
	s_nop 7
	v_add_u32_e32 v31, 1792, v87
	s_waitcnt lgkmcnt(0)
	v_fmamk_f32 v36, v36, 0x3db504f3, v44
	v_fmac_f32_e32 v45, 0x3db504f3, v37
	v_fmamk_f32 v38, v38, 0x3db504f3, v46
	v_fmac_f32_e32 v47, 0x3db504f3, v39
	v_mov_b32_e32 v37, v45
	v_mov_b32_e32 v39, v47
	s_mov_b64 exec, s[6:7]
	ds_write_b128 v31, v[36:39]
	s_mov_b64 exec, -1
	ds_read_b32 v20, v25 offset:7168
	ds_read_b32 v21, v25 offset:7232
	ds_read_b32 v22, v25 offset:7296
	ds_read_b32 v23, v25 offset:7360
	s_waitcnt lgkmcnt(3)
	v_add_u32_e32 v26, s42, v20
	v_lshl_add_u32 v26, v26, 9, v24
	global_load_dwordx4 v[210:213], v26, s[44:45]
	global_load_dwordx4 v[214:217], v26, s[44:45] offset:64
	global_load_dwordx4 v[218:221], v26, s[44:45] offset:128
	global_load_dwordx4 v[222:225], v26, s[44:45] offset:192
	s_waitcnt lgkmcnt(2)
	v_add_u32_e32 v27, s42, v21
	v_lshl_add_u32 v27, v27, 9, v24
	global_load_dwordx4 v[226:229], v27, s[44:45]
	global_load_dwordx4 v[230:233], v27, s[44:45] offset:64
	global_load_dwordx4 v[234:237], v27, s[44:45] offset:128
	global_load_dwordx4 v[238:241], v27, s[44:45] offset:192
	s_waitcnt lgkmcnt(1)
	v_add_u32_e32 v28, s42, v22
	v_lshl_add_u32 v28, v28, 9, v24
	global_load_dwordx4 v[70:73], v28, s[44:45]
	global_load_dwordx4 v[74:77], v28, s[44:45] offset:64
	global_load_dwordx4 v[78:81], v28, s[44:45] offset:128
	global_load_dwordx4 v[82:85], v28, s[44:45] offset:192
	s_waitcnt lgkmcnt(0)
	v_add_u32_e32 v29, s42, v23
	v_lshl_add_u32 v29, v29, 9, v24
	global_load_dwordx4 v[196:199], v29, s[44:45]
	global_load_dwordx4 v[200:203], v29, s[44:45] offset:64
	global_load_dwordx4 v[244:247], v29, s[44:45] offset:128
	global_load_dwordx4 v[248:251], v29, s[44:45] offset:192
	v_subrev_u32_e32 v30, s80, v16
	v_max_i32_e32 v30, 0xffffff80, v30
	v_lshl_add_u32 v30, v30, 2, s72
	ds_read2st64_b32 v[40:41], v30 offset0:2 offset1:5
	ds_read2st64_b32 v[42:43], v30 offset0:8 offset1:11
	s_waitcnt vmcnt(31)
	v_mfma_f32_16x16x32_bf16 v[32:35], v[4:7], v[130:133], 0
	s_waitcnt vmcnt(30)
	v_mfma_f32_16x16x32_bf16 v[32:35], v[0:3], v[134:137], v[32:35]
	s_waitcnt vmcnt(29)
	v_mfma_f32_16x16x32_bf16 v[32:35], v[12:15], v[138:141], v[32:35]
	s_waitcnt vmcnt(28)
	v_mfma_f32_16x16x32_bf16 v[32:35], v[8:11], v[142:145], v[32:35]
	s_nop 7
	v_add_u32_e32 v31, 2048, v87
	s_waitcnt lgkmcnt(0)
	v_fmamk_f32 v32, v32, 0x3db504f3, v40
	v_fmac_f32_e32 v41, 0x3db504f3, v33
	v_fmamk_f32 v34, v34, 0x3db504f3, v42
	v_fmac_f32_e32 v43, 0x3db504f3, v35
	v_mov_b32_e32 v33, v41
	v_mov_b32_e32 v35, v43
	s_mov_b64 exec, s[6:7]
	ds_write_b128 v31, v[32:35]
	s_mov_b64 exec, -1
	v_subrev_u32_e32 v30, s80, v17
	v_max_i32_e32 v30, 0xffffff80, v30
	v_lshl_add_u32 v30, v30, 2, s72
	ds_read2st64_b32 v[44:45], v30 offset0:2 offset1:5
	ds_read2st64_b32 v[46:47], v30 offset0:8 offset1:11
	s_waitcnt vmcnt(27)
	v_mfma_f32_16x16x32_bf16 v[36:39], v[4:7], v[146:149], 0
	s_waitcnt vmcnt(26)
	v_mfma_f32_16x16x32_bf16 v[36:39], v[0:3], v[150:153], v[36:39]
	s_waitcnt vmcnt(25)
	v_mfma_f32_16x16x32_bf16 v[36:39], v[12:15], v[154:157], v[36:39]
	s_waitcnt vmcnt(24)
	v_mfma_f32_16x16x32_bf16 v[36:39], v[8:11], v[158:161], v[36:39]
	s_nop 7
	v_add_u32_e32 v31, 2304, v87
	s_waitcnt lgkmcnt(0)
	v_fmamk_f32 v36, v36, 0x3db504f3, v44
	v_fmac_f32_e32 v45, 0x3db504f3, v37
	v_fmamk_f32 v38, v38, 0x3db504f3, v46
	v_fmac_f32_e32 v47, 0x3db504f3, v39
	v_mov_b32_e32 v37, v45
	v_mov_b32_e32 v39, v47
	s_mov_b64 exec, s[6:7]
	ds_write_b128 v31, v[36:39]
	s_mov_b64 exec, -1
	v_subrev_u32_e32 v30, s80, v18
	v_max_i32_e32 v30, 0xffffff80, v30
	v_lshl_add_u32 v30, v30, 2, s72
	ds_read2st64_b32 v[40:41], v30 offset0:2 offset1:5
	ds_read2st64_b32 v[42:43], v30 offset0:8 offset1:11
	s_waitcnt vmcnt(23)
	v_mfma_f32_16x16x32_bf16 v[32:35], v[4:7], v[162:165], 0
	s_waitcnt vmcnt(22)
	v_mfma_f32_16x16x32_bf16 v[32:35], v[0:3], v[166:169], v[32:35]
	s_waitcnt vmcnt(21)
	v_mfma_f32_16x16x32_bf16 v[32:35], v[12:15], v[170:173], v[32:35]
	s_waitcnt vmcnt(20)
	v_mfma_f32_16x16x32_bf16 v[32:35], v[8:11], v[174:177], v[32:35]
	s_nop 7
	v_add_u32_e32 v31, 2560, v87
	s_waitcnt lgkmcnt(0)
	v_fmamk_f32 v32, v32, 0x3db504f3, v40
	v_fmac_f32_e32 v41, 0x3db504f3, v33
	v_fmamk_f32 v34, v34, 0x3db504f3, v42
	v_fmac_f32_e32 v43, 0x3db504f3, v35
	v_mov_b32_e32 v33, v41
	v_mov_b32_e32 v35, v43
	s_mov_b64 exec, s[6:7]
	ds_write_b128 v31, v[32:35]
	s_mov_b64 exec, -1
	v_subrev_u32_e32 v30, s80, v19
	v_max_i32_e32 v30, 0xffffff80, v30
	v_lshl_add_u32 v30, v30, 2, s72
	ds_read2st64_b32 v[44:45], v30 offset0:2 offset1:5
	ds_read2st64_b32 v[46:47], v30 offset0:8 offset1:11
	s_waitcnt vmcnt(19)
	v_mfma_f32_16x16x32_bf16 v[36:39], v[4:7], v[178:181], 0
	s_waitcnt vmcnt(18)
	v_mfma_f32_16x16x32_bf16 v[36:39], v[0:3], v[182:185], v[36:39]
	s_waitcnt vmcnt(17)
	v_mfma_f32_16x16x32_bf16 v[36:39], v[12:15], v[186:189], v[36:39]
	s_waitcnt vmcnt(16)
	v_mfma_f32_16x16x32_bf16 v[36:39], v[8:11], v[190:193], v[36:39]
	s_nop 7
	v_add_u32_e32 v31, 2816, v87
	s_waitcnt lgkmcnt(0)
	v_fmamk_f32 v36, v36, 0x3db504f3, v44
	v_fmac_f32_e32 v45, 0x3db504f3, v37
	v_fmamk_f32 v38, v38, 0x3db504f3, v46
	v_fmac_f32_e32 v47, 0x3db504f3, v39
	v_mov_b32_e32 v37, v45
	v_mov_b32_e32 v39, v47
	s_mov_b64 exec, s[6:7]
	ds_write_b128 v31, v[36:39]
	s_mov_b64 exec, -1
	v_subrev_u32_e32 v30, s80, v20
	v_max_i32_e32 v30, 0xffffff80, v30
	v_lshl_add_u32 v30, v30, 2, s72
	ds_read2st64_b32 v[40:41], v30 offset0:2 offset1:5
	ds_read2st64_b32 v[42:43], v30 offset0:8 offset1:11
	s_waitcnt vmcnt(15)
	v_mfma_f32_16x16x32_bf16 v[32:35], v[4:7], v[210:213], 0
	s_waitcnt vmcnt(14)
	v_mfma_f32_16x16x32_bf16 v[32:35], v[0:3], v[214:217], v[32:35]
	s_waitcnt vmcnt(13)
	v_mfma_f32_16x16x32_bf16 v[32:35], v[12:15], v[218:221], v[32:35]
	s_waitcnt vmcnt(12)
	v_mfma_f32_16x16x32_bf16 v[32:35], v[8:11], v[222:225], v[32:35]
	s_nop 7
	v_add_u32_e32 v31, 3072, v87
	s_waitcnt lgkmcnt(0)
	v_fmamk_f32 v32, v32, 0x3db504f3, v40
	v_fmac_f32_e32 v41, 0x3db504f3, v33
	v_fmamk_f32 v34, v34, 0x3db504f3, v42
	v_fmac_f32_e32 v43, 0x3db504f3, v35
	v_mov_b32_e32 v33, v41
	v_mov_b32_e32 v35, v43
	s_mov_b64 exec, s[6:7]
	ds_write_b128 v31, v[32:35]
	s_mov_b64 exec, -1
	v_subrev_u32_e32 v30, s80, v21
	v_max_i32_e32 v30, 0xffffff80, v30
	v_lshl_add_u32 v30, v30, 2, s72
	ds_read2st64_b32 v[44:45], v30 offset0:2 offset1:5
	ds_read2st64_b32 v[46:47], v30 offset0:8 offset1:11
	s_waitcnt vmcnt(11)
	v_mfma_f32_16x16x32_bf16 v[36:39], v[4:7], v[226:229], 0
	s_waitcnt vmcnt(10)
	v_mfma_f32_16x16x32_bf16 v[36:39], v[0:3], v[230:233], v[36:39]
	s_waitcnt vmcnt(9)
	v_mfma_f32_16x16x32_bf16 v[36:39], v[12:15], v[234:237], v[36:39]
	s_waitcnt vmcnt(8)
	v_mfma_f32_16x16x32_bf16 v[36:39], v[8:11], v[238:241], v[36:39]
	s_nop 7
	v_add_u32_e32 v31, 3328, v87
	s_waitcnt lgkmcnt(0)
	v_fmamk_f32 v36, v36, 0x3db504f3, v44
	v_fmac_f32_e32 v45, 0x3db504f3, v37
	v_fmamk_f32 v38, v38, 0x3db504f3, v46
	v_fmac_f32_e32 v47, 0x3db504f3, v39
	v_mov_b32_e32 v37, v45
	v_mov_b32_e32 v39, v47
	s_mov_b64 exec, s[6:7]
	ds_write_b128 v31, v[36:39]
	s_mov_b64 exec, -1
	v_subrev_u32_e32 v30, s80, v22
	v_max_i32_e32 v30, 0xffffff80, v30
	v_lshl_add_u32 v30, v30, 2, s72
	ds_read2st64_b32 v[40:41], v30 offset0:2 offset1:5
	ds_read2st64_b32 v[42:43], v30 offset0:8 offset1:11
	s_waitcnt vmcnt(7)
	v_mfma_f32_16x16x32_bf16 v[32:35], v[4:7], v[70:73], 0
	s_waitcnt vmcnt(6)
	v_mfma_f32_16x16x32_bf16 v[32:35], v[0:3], v[74:77], v[32:35]
	s_waitcnt vmcnt(5)
	v_mfma_f32_16x16x32_bf16 v[32:35], v[12:15], v[78:81], v[32:35]
	s_waitcnt vmcnt(4)
	v_mfma_f32_16x16x32_bf16 v[32:35], v[8:11], v[82:85], v[32:35]
	s_nop 7
	v_add_u32_e32 v31, 3584, v87
	s_waitcnt lgkmcnt(0)
	v_fmamk_f32 v32, v32, 0x3db504f3, v40
	v_fmac_f32_e32 v41, 0x3db504f3, v33
	v_fmamk_f32 v34, v34, 0x3db504f3, v42
	v_fmac_f32_e32 v43, 0x3db504f3, v35
	v_mov_b32_e32 v33, v41
	v_mov_b32_e32 v35, v43
	s_mov_b64 exec, s[6:7]
	ds_write_b128 v31, v[32:35]
	s_mov_b64 exec, -1
	v_subrev_u32_e32 v30, s80, v23
	v_max_i32_e32 v30, 0xffffff80, v30
	v_lshl_add_u32 v30, v30, 2, s72
	ds_read2st64_b32 v[44:45], v30 offset0:2 offset1:5
	ds_read2st64_b32 v[46:47], v30 offset0:8 offset1:11
	s_waitcnt vmcnt(3)
	v_mfma_f32_16x16x32_bf16 v[36:39], v[4:7], v[196:199], 0
	s_waitcnt vmcnt(2)
	v_mfma_f32_16x16x32_bf16 v[36:39], v[0:3], v[200:203], v[36:39]
	s_waitcnt vmcnt(1)
	v_mfma_f32_16x16x32_bf16 v[36:39], v[12:15], v[244:247], v[36:39]
	s_waitcnt vmcnt(0)
	v_mfma_f32_16x16x32_bf16 v[36:39], v[8:11], v[248:251], v[36:39]
	s_nop 7
	v_add_u32_e32 v31, 3840, v87
	s_waitcnt lgkmcnt(0)
	v_fmamk_f32 v36, v36, 0x3db504f3, v44
	v_fmac_f32_e32 v45, 0x3db504f3, v37
	v_fmamk_f32 v38, v38, 0x3db504f3, v46
	v_fmac_f32_e32 v47, 0x3db504f3, v39
	v_mov_b32_e32 v37, v45
	v_mov_b32_e32 v39, v47
	s_mov_b64 exec, s[6:7]
	ds_write_b128 v31, v[36:39]
	s_mov_b64 exec, -1
	s_branch .LBB0_1532

.LBB0_1598:
	s_cmp_lt_i32 s30, 4
	s_cselect_b64 s[4:5], -1, 0
	s_and_b64 s[0:1], s[4:5], s[0:1]
	s_andn2_b64 vcc, exec, s[0:1]
	v_bfe_u32 v155, v194, 2, 4
	v_bfe_u32 v159, v194, 2, 2
	v_lshlrev_b32_e32 v158, 4, v194
	v_and_b32_e32 v162, 32, v194
	v_and_b32_e32 v154, 64, v194
	v_lshrrev_b32_e32 v163, 5, v194
	v_lshrrev_b32_e32 v161, 1, v194
	v_lshrrev_b32_e32 v160, 3, v194
	v_and_b32_e32 v156, 15, v194
	v_lshlrev_b32_e32 v157, 6, v194
	s_cbranch_vccnz .LBB0_1631
	s_add_u32 s6, s28, 0xb900000
	s_addc_u32 s7, s29, 0
	v_bitop3_b32 v150, v158, v162, 48 bitop3:0x6c
	v_and_b32_e32 v1, 4, v163
	v_and_b32_e32 v153, 24, v161
	s_movk_i32 s3, 0x70
	s_cmpk_lt_i32 s2, 0x210
	v_or_b32_e32 v0, v150, v154
	v_or3_b32 v1, v1, v159, v153
	v_and_or_b32 v2, v160, s3, v155
	s_movk_i32 s3, 0x60
	v_add_u32_e32 v151, 0x2000, v158
	s_cselect_b64 s[10:11], -1, 0
	s_ashr_i32 s23, s2, 31
	v_and_or_b32 v3, v160, s3, v1
	v_lshl_or_b32 v128, v2, 11, v0
	v_lshrrev_b32_e32 v2, 7, v151
	s_movk_i32 s3, 0xf0
	s_lshr_b32 s4, s23, 29
	v_lshl_or_b32 v130, v3, 11, v0
	v_and_or_b32 v3, v2, s3, v155
	s_movk_i32 s3, 0xe0
	s_add_i32 s4, s2, s4
	v_and_or_b32 v1, v2, s3, v1
	s_ashr_i32 s59, s4, 3
	s_and_b32 s4, s4, -8
	v_lshl_or_b32 v134, v1, 11, v0
	v_lshlrev_b32_e32 v1, 2, v194
	s_ashr_i32 s3, s22, 31
	s_sub_i32 s60, s2, s4
	v_lshl_or_b32 v132, v3, 11, v0
	v_lshlrev_b32_e32 v152, 1, v153
	v_and_b32_e32 v0, 0x3c0, v157
	v_and_b32_e32 v1, 32, v1
	s_cmp_lt_i32 s60, 0
	v_mov_b32_e32 v131, 0
	v_bitop3_b32 v164, v152, v1, v0 bitop3:0x36
	s_cselect_b64 s[8:9], -1, 0
	s_cmpk_gt_i32 s2, 0x20f
	v_mov_b32_e32 v135, v131
	v_mov_b32_e32 v129, v131
	v_mov_b32_e32 v133, v131
	v_readfirstlane_b32 s5, v194
	s_cbranch_scc1 .LBB0_1615
	s_add_u32 s33, s28, 0x7700000
	s_addc_u32 s56, s29, 0
	s_add_u32 s57, s28, 0x2700000
	s_addc_u32 s58, s29, 0
	s_lshr_b32 s14, s5, 6
	s_lshr_b32 s16, s5, 8
	s_lshl_b32 s61, s14, 10
	s_movk_i32 s62, 0x43
	s_and_b64 s[12:13], s[8:9], exec
	s_cselect_b32 s4, s62, 0x42
	s_mul_i32 s4, s60, s4
	s_add_i32 s4, s4, s59
	s_ashr_i32 s12, s4, 31
	s_lshr_b32 s12, s12, 26
	s_add_i32 s12, s4, s12
	s_ashr_i32 s13, s12, 6
	s_lshl_b32 s15, s13, 3
	s_sub_i32 s13, 0x42, s15
	s_andn2_b32 s12, s12, 63
	s_min_u32 s17, s13, 8
	s_sub_i32 s18, s4, s12
	s_sext_i32_i8 s4, s18
	v_cvt_f32_ubyte0_e32 v1, s17
	v_cvt_f32_i32_e32 v0, s4
	v_rcp_iflag_f32_e32 v2, v1
	s_ashr_i32 s4, s4, 30
	s_or_b32 s4, s4, 1
	v_mul_f32_e32 v2, v0, v2
	v_trunc_f32_e32 v2, v2
	v_fma_f32 v0, -v2, v1, v0
	v_cvt_i32_f32_e32 v2, v2
	v_cmp_ge_f32_e64 s[12:13], |v0|, v1
	s_and_b64 s[12:13], s[12:13], exec
	s_cselect_b32 s4, s4, 0
	v_readfirstlane_b32 s12, v2
	s_add_i32 s4, s12, s4
	s_mul_i32 s12, s4, s17
	s_sub_i32 s12, s18, s12
	s_sext_i32_i8 s12, s12
	s_waitcnt lgkmcnt(0)
	s_add_i32 s44, s15, s12
	s_ashr_i32 s45, s44, 31
	s_bfe_i64 s[18:19], s[4:5], 0x80000
	s_lshl_b64 s[12:13], s[44:45], 19
	s_lshl_b64 s[18:19], s[18:19], 19
	s_add_u32 s46, s57, s18
	s_addc_u32 s47, s58, s19
	s_add_i32 s63, s61, 0
	s_add_i32 m0, s63, 0x10000
	v_lshl_add_u64 v[0:1], s[46:47], 0, v[130:131]
	global_load_lds_dwordx4 v[0:1], off
	s_add_i32 m0, s63, 0x12000
	s_add_u32 s18, s46, 0x40000
	v_lshl_add_u64 v[2:3], s[46:47], 0, v[134:135]
	s_addc_u32 s19, s47, 0
	global_load_lds_dwordx4 v[2:3], off
	s_add_i32 m0, s63, 0x14000
	s_nop 0
	global_load_lds_dwordx4 v130, s[18:19]
	s_add_i32 m0, s63, 0x16000
	s_add_u32 s20, s33, s12
	s_addc_u32 s21, s56, s13
	s_add_i32 s64, s63, 0x2000
	global_load_lds_dwordx4 v134, s[18:19]
	v_lshl_add_u64 v[6:7], s[20:21], 0, v[128:129]
	s_mov_b32 m0, s63
	s_add_u32 s12, s20, 0x40000
	global_load_lds_dwordx4 v[6:7], off
	v_lshl_add_u64 v[4:5], s[20:21], 0, v[132:133]
	s_mov_b32 m0, s64
	s_addc_u32 s13, s21, 0
	s_add_i32 s65, s63, 0x4000
	global_load_lds_dwordx4 v[4:5], off
	s_mov_b32 m0, s65
	s_add_i32 s66, s63, 0x6000
	global_load_lds_dwordx4 v128, s[12:13]
	v_lshl_add_u64 v[8:9], s[12:13], 0, v[132:133]
	s_mov_b32 m0, s66
	s_cmp_eq_u32 s16, 1
	global_load_lds_dwordx4 v[8:9], off
	s_cselect_b64 s[12:13], -1, 0
	s_cmp_lg_u32 s16, 1
	s_cbranch_scc1 .LBB0_1602
	s_barrier
.LBB0_1602:
	s_lshl_b32 s14, s14, 5
	s_and_b32 s24, s14, 0x60
	s_mov_b64 s[14:15], 0x80
	s_add_i32 m0, s63, 0x18000
	v_lshl_add_u64 v[0:1], v[0:1], 0, s[14:15]
	s_lshl_b32 s17, s16, 13
	s_waitcnt vmcnt(2)
	s_barrier
	global_load_lds_dwordx4 v[0:1], off
	v_lshl_add_u64 v[0:1], v[2:3], 0, s[14:15]
	s_add_i32 m0, s63, 0x1a000
	s_add_i32 s67, s63, 0x8000
	s_add_i32 s68, s63, 0xa000
	global_load_lds_dwordx4 v[0:1], off
	v_lshl_add_u64 v[0:1], v[6:7], 0, s[14:15]
	s_mov_b32 m0, s67
	s_add_u32 s18, s46, 0x40080
	global_load_lds_dwordx4 v[0:1], off
	v_lshl_add_u64 v[0:1], v[4:5], 0, s[14:15]
	s_mov_b32 m0, s68
	s_addc_u32 s19, s47, 0
	global_load_lds_dwordx4 v[0:1], off
	s_add_i32 m0, s63, 0x1c000
	s_nop 0
	global_load_lds_dwordx4 v130, s[18:19]
	s_add_i32 m0, s63, 0x1e000
	v_lshlrev_b32_e32 v2, 11, v155
	global_load_lds_dwordx4 v134, s[18:19]
	v_lshlrev_b32_e32 v1, 2, v156
	v_lshl_or_b32 v0, v156, 6, v152
	v_and_b32_e32 v1, 32, v1
	v_bitop3_b32 v0, v0, s17, v1 bitop3:0xde
	v_lshlrev_b32_e32 v1, 8, v194
	v_and_b32_e32 v1, 0x38000, v1
	v_or3_b32 v1, v150, v1, v2
	v_add_u32_e32 v138, v1, v154
	v_lshlrev_b32_e32 v1, 4, v151
	s_waitcnt vmcnt(6)
	s_cmpk_lt_u32 s5, 0x100
	v_and_b32_e32 v1, 0x78000, v1
	v_lshl_or_b32 v136, s16, 6, v156
	v_lshl_or_b32 v165, s24, 7, v164
	s_cselect_b64 s[16:17], -1, 0
	v_mov_b32_e32 v137, 0
	v_or3_b32 v1, v150, v1, v2
	s_add_i32 s70, 0, 0x10000
	s_add_i32 s71, 0, 0x14000
	s_sext_i32_i8 s72, s4
	s_mov_b32 s69, 0
	v_or_b32_e32 v166, s24, v153
	v_mov_b32_e32 v139, v137
	v_add_u32_e32 v140, v1, v154
	v_mov_b32_e32 v141, v137
	v_mov_b64_e32 v[142:143], 0x210
	v_mov_b64_e32 v[144:145], 0x20f
	v_add_u32_e32 v167, s70, v165
	v_add_u32_e32 v168, s71, v165
	v_add_u32_e32 v169, 0, v0
	s_mov_b64 s[18:19], 0x90
	s_mov_b64 s[24:25], 0xa0
	s_mov_b64 s[34:35], 0xb0
	s_barrier
	s_branch .LBB0_1605

.LBB0_1608:
	ds_read_b128 v[146:149], v167
	ds_read_b128 v[170:173], v167 offset:1024
	ds_read_b128 v[174:177], v167 offset:2048
	ds_read_b128 v[178:181], v167 offset:3072
	ds_read_b128 v[182:185], v168
	ds_read_b128 v[186:189], v168 offset:1024
	ds_read_b128 v[190:193], v168 offset:2048
	ds_read_b128 v[196:199], v168 offset:3072
	s_add_u32 s46, s20, 0xfffc0080
	s_addc_u32 s47, s21, -1
	s_cmp_eq_u32 s76, 12
	s_cselect_b32 s51, s39, s47
	s_cselect_b32 s50, s45, s46
	s_cselect_b32 s47, s37, s75
	s_cselect_b32 s46, s73, s74
	s_add_i32 m0, s63, 0xc000
	ds_read_b128 v[200:203], v169
	ds_read_b128 v[204:207], v169 offset:1024
	ds_read_b128 v[208:211], v169 offset:2048
	ds_read_b128 v[212:215], v169 offset:3072
	ds_read_b128 v[216:219], v169 offset:4096
	ds_read_b128 v[220:223], v169 offset:5120
	ds_read_b128 v[224:227], v169 offset:6144
	ds_read_b128 v[228:231], v169 offset:7168
	global_load_lds_dwordx4 v138, s[20:21]
	s_add_i32 m0, s63, 0xe000
	s_nop 0
	global_load_lds_dwordx4 v140, s[20:21]
	s_waitcnt vmcnt(8)
	s_waitcnt lgkmcnt(0)
	s_barrier
	s_setprio 1
	s_waitcnt lgkmcnt(0)
	v_mfma_f32_16x16x32_bf16 v[124:127], v[146:149], v[200:203], v[124:127]
	v_mfma_f32_16x16x32_bf16 v[120:123], v[174:177], v[200:203], v[120:123]
	v_mfma_f32_16x16x32_bf16 v[108:111], v[146:149], v[208:211], v[108:111]
	v_mfma_f32_16x16x32_bf16 v[104:107], v[174:177], v[208:211], v[104:107]
	v_mfma_f32_16x16x32_bf16 v[92:95], v[146:149], v[216:219], v[92:95]
	v_mfma_f32_16x16x32_bf16 v[88:91], v[174:177], v[216:219], v[88:91]
	v_mfma_f32_16x16x32_bf16 v[76:79], v[146:149], v[224:227], v[76:79]
	v_mfma_f32_16x16x32_bf16 v[72:75], v[174:177], v[224:227], v[72:75]
	v_mfma_f32_16x16x32_bf16 v[124:127], v[170:173], v[204:207], v[124:127]
	v_mfma_f32_16x16x32_bf16 v[120:123], v[178:181], v[204:207], v[120:123]
	v_mfma_f32_16x16x32_bf16 v[108:111], v[170:173], v[212:215], v[108:111]
	v_mfma_f32_16x16x32_bf16 v[104:107], v[178:181], v[212:215], v[104:107]
	v_mfma_f32_16x16x32_bf16 v[92:95], v[170:173], v[220:223], v[92:95]
	v_mfma_f32_16x16x32_bf16 v[88:91], v[178:181], v[220:223], v[88:91]
	v_mfma_f32_16x16x32_bf16 v[76:79], v[170:173], v[228:231], v[76:79]
	v_mfma_f32_16x16x32_bf16 v[72:75], v[178:181], v[228:231], v[72:75]
	s_setprio 0
	s_setprio 1
	v_mfma_f32_16x16x32_bf16 v[116:119], v[182:185], v[200:203], v[116:119]
	v_mfma_f32_16x16x32_bf16 v[112:115], v[190:193], v[200:203], v[112:115]
	v_mfma_f32_16x16x32_bf16 v[100:103], v[182:185], v[208:211], v[100:103]
	v_mfma_f32_16x16x32_bf16 v[96:99], v[190:193], v[208:211], v[96:99]
	v_mfma_f32_16x16x32_bf16 v[84:87], v[182:185], v[216:219], v[84:87]
	v_mfma_f32_16x16x32_bf16 v[80:83], v[190:193], v[216:219], v[80:83]
	v_mfma_f32_16x16x32_bf16 v[68:71], v[182:185], v[224:227], v[68:71]
	v_mfma_f32_16x16x32_bf16 v[64:67], v[190:193], v[224:227], v[64:67]
	v_mfma_f32_16x16x32_bf16 v[116:119], v[186:189], v[204:207], v[116:119]
	v_mfma_f32_16x16x32_bf16 v[112:115], v[196:199], v[204:207], v[112:115]
	v_mfma_f32_16x16x32_bf16 v[100:103], v[186:189], v[212:215], v[100:103]
	v_mfma_f32_16x16x32_bf16 v[96:99], v[196:199], v[212:215], v[96:99]
	v_mfma_f32_16x16x32_bf16 v[84:87], v[186:189], v[220:223], v[84:87]
	v_mfma_f32_16x16x32_bf16 v[80:83], v[196:199], v[220:223], v[80:83]
	v_mfma_f32_16x16x32_bf16 v[68:71], v[186:189], v[228:231], v[68:71]
	v_mfma_f32_16x16x32_bf16 v[64:67], v[196:199], v[228:231], v[64:67]
	s_setprio 0
	s_barrier
	s_add_i32 s77, s70, s61
	v_lshl_add_u64 v[232:233], s[46:47], 0, v[130:131]
	s_mov_b32 m0, s77
	ds_read_b128 v[200:203], v169 offset:16384
	ds_read_b128 v[204:207], v169 offset:17408
	ds_read_b128 v[208:211], v169 offset:18432
	ds_read_b128 v[212:215], v169 offset:19456
	ds_read_b128 v[216:219], v169 offset:20480
	ds_read_b128 v[220:223], v169 offset:21504
	ds_read_b128 v[224:227], v169 offset:22528
	ds_read_b128 v[228:231], v169 offset:23552
	global_load_lds_dwordx4 v[232:233], off
	s_add_i32 m0, s77, 0x2000
	s_add_u32 s78, s46, 0x40000
	v_lshl_add_u64 v[234:235], s[46:47], 0, v[134:135]
	s_addc_u32 s79, s47, 0
	s_add_i32 s77, s71, s61
	global_load_lds_dwordx4 v[234:235], off
	s_mov_b32 m0, s77
	v_lshl_add_u64 v[238:239], s[50:51], 0, v[132:133]
	global_load_lds_dwordx4 v130, s[78:79]
	s_add_i32 m0, s77, 0x2000
	s_nop 0
	global_load_lds_dwordx4 v134, s[78:79]
	v_lshl_add_u64 v[236:237], s[50:51], 0, v[128:129]
	s_mov_b32 m0, s63
	s_nop 0
	global_load_lds_dwordx4 v[236:237], off
	s_mov_b32 m0, s64
	s_nop 0
	global_load_lds_dwordx4 v[238:239], off
	s_waitcnt vmcnt(8)
	s_waitcnt lgkmcnt(0)
	s_barrier
	s_setprio 1
	s_waitcnt lgkmcnt(0)
	v_mfma_f32_16x16x32_bf16 v[60:63], v[146:149], v[200:203], v[60:63]
	v_mfma_f32_16x16x32_bf16 v[56:59], v[174:177], v[200:203], v[56:59]
	v_mfma_f32_16x16x32_bf16 v[44:47], v[146:149], v[208:211], v[44:47]
	v_mfma_f32_16x16x32_bf16 v[40:43], v[174:177], v[208:211], v[40:43]
	v_mfma_f32_16x16x32_bf16 v[28:31], v[146:149], v[216:219], v[28:31]
	v_mfma_f32_16x16x32_bf16 v[24:27], v[174:177], v[216:219], v[24:27]
	v_mfma_f32_16x16x32_bf16 v[12:15], v[146:149], v[224:227], v[12:15]
	v_mfma_f32_16x16x32_bf16 v[8:11], v[174:177], v[224:227], v[8:11]
	v_mfma_f32_16x16x32_bf16 v[60:63], v[170:173], v[204:207], v[60:63]
	v_mfma_f32_16x16x32_bf16 v[56:59], v[178:181], v[204:207], v[56:59]
	v_mfma_f32_16x16x32_bf16 v[44:47], v[170:173], v[212:215], v[44:47]
	v_mfma_f32_16x16x32_bf16 v[40:43], v[178:181], v[212:215], v[40:43]
	v_mfma_f32_16x16x32_bf16 v[28:31], v[170:173], v[220:223], v[28:31]
	v_mfma_f32_16x16x32_bf16 v[24:27], v[178:181], v[220:223], v[24:27]
	v_mfma_f32_16x16x32_bf16 v[12:15], v[170:173], v[228:231], v[12:15]
	v_mfma_f32_16x16x32_bf16 v[8:11], v[178:181], v[228:231], v[8:11]
	s_setprio 0
	s_setprio 1
	v_mfma_f32_16x16x32_bf16 v[52:55], v[182:185], v[200:203], v[52:55]
	v_mfma_f32_16x16x32_bf16 v[48:51], v[190:193], v[200:203], v[48:51]
	v_mfma_f32_16x16x32_bf16 v[36:39], v[182:185], v[208:211], v[36:39]
	v_mfma_f32_16x16x32_bf16 v[32:35], v[190:193], v[208:211], v[32:35]
	v_mfma_f32_16x16x32_bf16 v[20:23], v[182:185], v[216:219], v[20:23]
	v_mfma_f32_16x16x32_bf16 v[16:19], v[190:193], v[216:219], v[16:19]
	v_mfma_f32_16x16x32_bf16 v[4:7], v[182:185], v[224:227], v[4:7]
	v_mfma_f32_16x16x32_bf16 v[0:3], v[190:193], v[224:227], v[0:3]
	v_mfma_f32_16x16x32_bf16 v[52:55], v[186:189], v[204:207], v[52:55]
	v_mfma_f32_16x16x32_bf16 v[48:51], v[196:199], v[204:207], v[48:51]
	v_mfma_f32_16x16x32_bf16 v[36:39], v[186:189], v[212:215], v[36:39]
	v_mfma_f32_16x16x32_bf16 v[32:35], v[196:199], v[212:215], v[32:35]
	v_mfma_f32_16x16x32_bf16 v[20:23], v[186:189], v[220:223], v[20:23]
	v_mfma_f32_16x16x32_bf16 v[16:19], v[196:199], v[220:223], v[16:19]
	v_mfma_f32_16x16x32_bf16 v[4:7], v[186:189], v[228:231], v[4:7]
	v_mfma_f32_16x16x32_bf16 v[0:3], v[196:199], v[228:231], v[0:3]
	s_setprio 0
	s_barrier
	s_add_i32 s77, 0, 0x18000
	s_add_i32 s78, 0, 0x1c000
	v_add_u32_e32 v178, s77, v165
	v_add_u32_e32 v195, s78, v165
	ds_read_b128 v[146:149], v178
	ds_read_b128 v[170:173], v178 offset:1024
	ds_read_b128 v[174:177], v178 offset:2048
	ds_read_b128 v[178:181], v178 offset:3072
	ds_read_b128 v[182:185], v195
	ds_read_b128 v[186:189], v195 offset:1024
	ds_read_b128 v[190:193], v195 offset:2048
	ds_read_b128 v[196:199], v195 offset:3072
	s_add_u32 s50, s50, 0x40000
	s_addc_u32 s51, s51, 0
	s_mov_b32 m0, s65
	ds_read_b128 v[200:203], v169 offset:32768
	ds_read_b128 v[204:207], v169 offset:33792
	ds_read_b128 v[208:211], v169 offset:34816
	ds_read_b128 v[212:215], v169 offset:35840
	ds_read_b128 v[216:219], v169 offset:36864
	ds_read_b128 v[220:223], v169 offset:37888
	ds_read_b128 v[224:227], v169 offset:38912
	ds_read_b128 v[228:231], v169 offset:39936
	global_load_lds_dwordx4 v128, s[50:51]
	v_lshl_add_u64 v[240:241], s[50:51], 0, v[132:133]
	s_mov_b32 m0, s66
	s_nop 0
	global_load_lds_dwordx4 v[240:241], off
	s_waitcnt vmcnt(8)
	s_waitcnt lgkmcnt(0)
	s_barrier
	s_setprio 1
	s_waitcnt lgkmcnt(0)
	v_mfma_f32_16x16x32_bf16 v[124:127], v[146:149], v[200:203], v[124:127]
	v_mfma_f32_16x16x32_bf16 v[120:123], v[174:177], v[200:203], v[120:123]
	v_mfma_f32_16x16x32_bf16 v[108:111], v[146:149], v[208:211], v[108:111]
	v_mfma_f32_16x16x32_bf16 v[104:107], v[174:177], v[208:211], v[104:107]
	v_mfma_f32_16x16x32_bf16 v[92:95], v[146:149], v[216:219], v[92:95]
	v_mfma_f32_16x16x32_bf16 v[88:91], v[174:177], v[216:219], v[88:91]
	v_mfma_f32_16x16x32_bf16 v[76:79], v[146:149], v[224:227], v[76:79]
	v_mfma_f32_16x16x32_bf16 v[72:75], v[174:177], v[224:227], v[72:75]
	v_mfma_f32_16x16x32_bf16 v[124:127], v[170:173], v[204:207], v[124:127]
	v_mfma_f32_16x16x32_bf16 v[120:123], v[178:181], v[204:207], v[120:123]
	v_mfma_f32_16x16x32_bf16 v[108:111], v[170:173], v[212:215], v[108:111]
	v_mfma_f32_16x16x32_bf16 v[104:107], v[178:181], v[212:215], v[104:107]
	v_mfma_f32_16x16x32_bf16 v[92:95], v[170:173], v[220:223], v[92:95]
	v_mfma_f32_16x16x32_bf16 v[88:91], v[178:181], v[220:223], v[88:91]
	v_mfma_f32_16x16x32_bf16 v[76:79], v[170:173], v[228:231], v[76:79]
	v_mfma_f32_16x16x32_bf16 v[72:75], v[178:181], v[228:231], v[72:75]
	s_setprio 0
	s_setprio 1
	v_mfma_f32_16x16x32_bf16 v[116:119], v[182:185], v[200:203], v[116:119]
	v_mfma_f32_16x16x32_bf16 v[112:115], v[190:193], v[200:203], v[112:115]
	v_mfma_f32_16x16x32_bf16 v[100:103], v[182:185], v[208:211], v[100:103]
	v_mfma_f32_16x16x32_bf16 v[96:99], v[190:193], v[208:211], v[96:99]
	v_mfma_f32_16x16x32_bf16 v[84:87], v[182:185], v[216:219], v[84:87]
	v_mfma_f32_16x16x32_bf16 v[80:83], v[190:193], v[216:219], v[80:83]
	v_mfma_f32_16x16x32_bf16 v[68:71], v[182:185], v[224:227], v[68:71]
	v_mfma_f32_16x16x32_bf16 v[64:67], v[190:193], v[224:227], v[64:67]
	v_mfma_f32_16x16x32_bf16 v[116:119], v[186:189], v[204:207], v[116:119]
	v_mfma_f32_16x16x32_bf16 v[112:115], v[196:199], v[204:207], v[112:115]
	v_mfma_f32_16x16x32_bf16 v[100:103], v[186:189], v[212:215], v[100:103]
	v_mfma_f32_16x16x32_bf16 v[96:99], v[196:199], v[212:215], v[96:99]
	v_mfma_f32_16x16x32_bf16 v[84:87], v[186:189], v[220:223], v[84:87]
	v_mfma_f32_16x16x32_bf16 v[80:83], v[196:199], v[220:223], v[80:83]
	v_mfma_f32_16x16x32_bf16 v[68:71], v[186:189], v[228:231], v[68:71]
	v_mfma_f32_16x16x32_bf16 v[64:67], v[196:199], v[228:231], v[64:67]
	s_setprio 0
	s_barrier
	s_add_i32 s50, s77, s61
	v_lshl_add_u64 v[232:233], v[232:233], 0, s[14:15]
	s_mov_b32 m0, s50
	ds_read_b128 v[200:203], v169 offset:49152
	ds_read_b128 v[204:207], v169 offset:50176
	ds_read_b128 v[208:211], v169 offset:51200
	ds_read_b128 v[212:215], v169 offset:52224
	ds_read_b128 v[216:219], v169 offset:53248
	ds_read_b128 v[220:223], v169 offset:54272
	ds_read_b128 v[224:227], v169 offset:55296
	ds_read_b128 v[228:231], v169 offset:56320
	global_load_lds_dwordx4 v[232:233], off
	s_add_i32 m0, s50, 0x2000
	s_add_u32 s46, s46, 0x40080
	v_lshl_add_u64 v[232:233], v[234:235], 0, s[14:15]
	s_addc_u32 s47, s47, 0
	s_add_i32 s50, s78, s61
	global_load_lds_dwordx4 v[232:233], off
	s_mov_b32 m0, s50
	s_nop 0
	global_load_lds_dwordx4 v130, s[46:47]
	s_add_i32 m0, s50, 0x2000
	s_nop 0
	global_load_lds_dwordx4 v134, s[46:47]
	v_lshl_add_u64 v[232:233], v[236:237], 0, s[14:15]
	s_mov_b32 m0, s67
	s_nop 0
	global_load_lds_dwordx4 v[232:233], off
	v_lshl_add_u64 v[232:233], v[238:239], 0, s[14:15]
	s_mov_b32 m0, s68
	s_nop 0
	global_load_lds_dwordx4 v[232:233], off
	s_waitcnt vmcnt(8)
	s_waitcnt lgkmcnt(0)
	s_barrier
	s_setprio 1
	s_waitcnt lgkmcnt(0)
	v_mfma_f32_16x16x32_bf16 v[60:63], v[146:149], v[200:203], v[60:63]
	v_mfma_f32_16x16x32_bf16 v[56:59], v[174:177], v[200:203], v[56:59]
	v_mfma_f32_16x16x32_bf16 v[44:47], v[146:149], v[208:211], v[44:47]
	v_mfma_f32_16x16x32_bf16 v[40:43], v[174:177], v[208:211], v[40:43]
	v_mfma_f32_16x16x32_bf16 v[28:31], v[146:149], v[216:219], v[28:31]
	v_mfma_f32_16x16x32_bf16 v[24:27], v[174:177], v[216:219], v[24:27]
	v_mfma_f32_16x16x32_bf16 v[12:15], v[146:149], v[224:227], v[12:15]
	v_mfma_f32_16x16x32_bf16 v[8:11], v[174:177], v[224:227], v[8:11]
	v_mfma_f32_16x16x32_bf16 v[60:63], v[170:173], v[204:207], v[60:63]
	v_mfma_f32_16x16x32_bf16 v[56:59], v[178:181], v[204:207], v[56:59]
	v_mfma_f32_16x16x32_bf16 v[44:47], v[170:173], v[212:215], v[44:47]
	v_mfma_f32_16x16x32_bf16 v[40:43], v[178:181], v[212:215], v[40:43]
	v_mfma_f32_16x16x32_bf16 v[28:31], v[170:173], v[220:223], v[28:31]
	v_mfma_f32_16x16x32_bf16 v[24:27], v[178:181], v[220:223], v[24:27]
	v_mfma_f32_16x16x32_bf16 v[12:15], v[170:173], v[228:231], v[12:15]
	v_mfma_f32_16x16x32_bf16 v[8:11], v[178:181], v[228:231], v[8:11]
	s_setprio 0
	s_setprio 1
	v_mfma_f32_16x16x32_bf16 v[52:55], v[182:185], v[200:203], v[52:55]
	v_mfma_f32_16x16x32_bf16 v[48:51], v[190:193], v[200:203], v[48:51]
	v_mfma_f32_16x16x32_bf16 v[36:39], v[182:185], v[208:211], v[36:39]
	v_mfma_f32_16x16x32_bf16 v[32:35], v[190:193], v[208:211], v[32:35]
	v_mfma_f32_16x16x32_bf16 v[20:23], v[182:185], v[216:219], v[20:23]
	v_mfma_f32_16x16x32_bf16 v[16:19], v[190:193], v[216:219], v[16:19]
	v_mfma_f32_16x16x32_bf16 v[4:7], v[182:185], v[224:227], v[4:7]
	v_mfma_f32_16x16x32_bf16 v[0:3], v[190:193], v[224:227], v[0:3]
	v_mfma_f32_16x16x32_bf16 v[52:55], v[186:189], v[204:207], v[52:55]
	v_mfma_f32_16x16x32_bf16 v[48:51], v[196:199], v[204:207], v[48:51]
	v_mfma_f32_16x16x32_bf16 v[36:39], v[186:189], v[212:215], v[36:39]
	v_mfma_f32_16x16x32_bf16 v[32:35], v[196:199], v[212:215], v[32:35]
	v_mfma_f32_16x16x32_bf16 v[20:23], v[186:189], v[220:223], v[20:23]
	v_mfma_f32_16x16x32_bf16 v[16:19], v[196:199], v[220:223], v[16:19]
	v_mfma_f32_16x16x32_bf16 v[4:7], v[186:189], v[228:231], v[4:7]
	v_mfma_f32_16x16x32_bf16 v[0:3], v[196:199], v[228:231], v[0:3]
	s_setprio 0
	s_barrier
	s_add_i32 s76, s76, 2
	s_add_u32 s20, s20, 0x100
	s_addc_u32 s21, s21, 0
	s_add_u32 s74, s74, 0x100
	s_addc_u32 s75, s75, 0
	s_cmp_gt_u32 s76, 13
	s_cbranch_scc0 .LBB0_1608
	s_and_b64 vcc, exec, s[16:17]
	s_cbranch_vccz .LBB0_1611
	s_barrier

.LBB0_1615:
	s_andn2_b64 vcc, exec, s[10:11]
	v_readfirstlane_b32 s5, v194
	s_waitcnt vmcnt(0) lgkmcnt(0)
	s_barrier
	s_cbranch_vccnz .LBB0_1631
	s_lshr_b32 s10, s5, 6
	s_lshr_b32 s12, s5, 8
	s_lshl_b32 s33, s10, 10
	s_add_u32 s50, s28, 0x9800000
	s_addc_u32 s51, s29, 0
	s_add_u32 s56, s28, 0x2b00000
	s_addc_u32 s57, s29, 0
	s_movk_i32 s58, 0x43
	s_and_b64 s[8:9], s[8:9], exec
	s_cselect_b32 s4, s58, 0x42
	s_mul_i32 s4, s60, s4
	s_add_i32 s4, s4, s59
	s_ashr_i32 s8, s4, 31
	s_lshr_b32 s8, s8, 26
	s_add_i32 s8, s4, s8
	s_ashr_i32 s9, s8, 6
	s_lshl_b32 s11, s9, 3
	s_sub_i32 s9, 0x42, s11
	s_andn2_b32 s8, s8, 63
	s_min_u32 s13, s9, 8
	s_sub_i32 s14, s4, s8
	s_sext_i32_i8 s4, s14
	v_cvt_f32_ubyte0_e32 v1, s13
	v_cvt_f32_i32_e32 v0, s4
	v_rcp_iflag_f32_e32 v2, v1
	s_ashr_i32 s4, s4, 30
	s_or_b32 s4, s4, 1
	s_mov_b32 s63, 0
	v_mul_f32_e32 v2, v0, v2
	v_trunc_f32_e32 v2, v2
	v_fma_f32 v0, -v2, v1, v0
	v_cvt_i32_f32_e32 v2, v2
	v_cmp_ge_f32_e64 s[8:9], |v0|, v1
	s_and_b64 s[8:9], s[8:9], exec
	s_cselect_b32 s4, s4, 0
	v_readfirstlane_b32 s8, v2
	s_add_i32 s4, s8, s4
	s_mul_i32 s8, s4, s13
	s_sub_i32 s8, s14, s8
	s_sext_i32_i8 s8, s8
	s_add_i32 s42, s11, s8
	s_ashr_i32 s43, s42, 31
	s_bfe_i64 s[14:15], s[4:5], 0x80000
	s_lshl_b64 s[8:9], s[42:43], 19
	s_lshl_b64 s[14:15], s[14:15], 19
	s_add_u32 s44, s56, s14
	s_addc_u32 s45, s57, s15
	s_add_i32 s59, s33, 0
	s_add_i32 m0, s59, 0x10000
	v_lshl_add_u64 v[0:1], s[44:45], 0, v[130:131]
	global_load_lds_dwordx4 v[0:1], off
	s_add_i32 m0, s59, 0x12000
	s_add_u32 s14, s44, 0x40000
	v_lshl_add_u64 v[2:3], s[44:45], 0, v[134:135]
	s_addc_u32 s15, s45, 0
	global_load_lds_dwordx4 v[2:3], off
	s_add_i32 m0, s59, 0x14000
	s_nop 0
	global_load_lds_dwordx4 v130, s[14:15]
	s_add_i32 m0, s59, 0x16000
	s_add_u32 s20, s50, s8
	s_addc_u32 s21, s51, s9
	s_add_i32 s60, s59, 0x2000
	global_load_lds_dwordx4 v134, s[14:15]
	v_lshl_add_u64 v[6:7], s[20:21], 0, v[128:129]
	s_mov_b32 m0, s59
	s_add_u32 s8, s20, 0x40000
	global_load_lds_dwordx4 v[6:7], off
	v_lshl_add_u64 v[4:5], s[20:21], 0, v[132:133]
	s_mov_b32 m0, s60
	s_addc_u32 s9, s21, 0
	s_add_i32 s61, s59, 0x4000
	global_load_lds_dwordx4 v[4:5], off
	s_mov_b32 m0, s61
	s_add_i32 s62, s59, 0x6000
	global_load_lds_dwordx4 v128, s[8:9]
	v_lshl_add_u64 v[8:9], s[8:9], 0, v[132:133]
	s_mov_b32 m0, s62
	s_cmp_eq_u32 s12, 1
	global_load_lds_dwordx4 v[8:9], off
	s_cselect_b64 s[8:9], -1, 0
	s_cmp_lg_u32 s12, 1
	s_cbranch_scc1 .LBB0_1618
	s_barrier
.LBB0_1618:
	s_lshl_b32 s10, s10, 5
	s_and_b32 s16, s10, 0x60
	s_mov_b64 s[10:11], 0x80
	s_add_i32 m0, s59, 0x18000
	v_lshl_add_u64 v[0:1], v[0:1], 0, s[10:11]
	s_lshl_b32 s13, s12, 13
	s_waitcnt vmcnt(2)
	s_barrier
	global_load_lds_dwordx4 v[0:1], off
	v_lshl_add_u64 v[0:1], v[2:3], 0, s[10:11]
	s_add_i32 m0, s59, 0x1a000
	s_add_i32 s64, s59, 0x8000
	s_add_i32 s65, s59, 0xa000
	global_load_lds_dwordx4 v[0:1], off
	v_lshl_add_u64 v[0:1], v[6:7], 0, s[10:11]
	s_mov_b32 m0, s64
	s_add_u32 s14, s44, 0x40080
	global_load_lds_dwordx4 v[0:1], off
	v_lshl_add_u64 v[0:1], v[4:5], 0, s[10:11]
	s_mov_b32 m0, s65
	s_addc_u32 s15, s45, 0
	global_load_lds_dwordx4 v[0:1], off
	s_add_i32 m0, s59, 0x1c000
	s_nop 0
	global_load_lds_dwordx4 v130, s[14:15]
	s_add_i32 m0, s59, 0x1e000
	v_lshlrev_b32_e32 v2, 11, v155
	global_load_lds_dwordx4 v134, s[14:15]
	v_lshlrev_b32_e32 v1, 2, v156
	v_lshl_or_b32 v0, v156, 6, v152
	v_and_b32_e32 v1, 32, v1
	v_bitop3_b32 v0, v0, s13, v1 bitop3:0xde
	v_lshlrev_b32_e32 v1, 8, v194
	v_and_b32_e32 v1, 0x38000, v1
	v_or3_b32 v1, v150, v1, v2
	v_add_u32_e32 v138, v1, v154
	v_lshlrev_b32_e32 v1, 4, v151
	s_waitcnt vmcnt(6)
	s_cmpk_lt_u32 s5, 0x100
	v_and_b32_e32 v1, 0x78000, v1
	v_lshl_or_b32 v136, s12, 6, v156
	v_lshl_or_b32 v152, s16, 7, v164
	s_cselect_b64 s[12:13], -1, 0
	v_mov_b32_e32 v137, 0
	v_or3_b32 v1, v150, v1, v2
	s_add_i32 s66, 0, 0x10000
	s_add_i32 s67, 0, 0x14000
	s_sext_i32_i8 s68, s4
	v_or_b32_e32 v153, s16, v153
	v_mov_b32_e32 v139, v137
	v_add_u32_e32 v140, v1, v154
	v_mov_b32_e32 v141, v137
	v_mov_b64_e32 v[142:143], 0x210
	v_mov_b64_e32 v[144:145], 0x20f
	v_add_u32_e32 v164, s66, v152
	v_add_u32_e32 v165, s67, v152
	v_add_u32_e32 v166, 0, v0
	s_mov_b64 s[14:15], 0x1000
	s_mov_b64 s[16:17], 0x90
	s_mov_b64 s[18:19], 0xa0
	s_mov_b64 s[24:25], 0xb0
	s_barrier
	s_branch .LBB0_1621

.LBB0_1624:
	ds_read_b128 v[146:149], v164
	ds_read_b128 v[168:171], v164 offset:1024
	ds_read_b128 v[172:175], v164 offset:2048
	ds_read_b128 v[176:179], v164 offset:3072
	ds_read_b128 v[180:183], v165
	ds_read_b128 v[184:187], v165 offset:1024
	ds_read_b128 v[188:191], v165 offset:2048
	ds_read_b128 v[196:199], v165 offset:3072
	s_add_u32 s44, s20, 0xfffc0080
	s_addc_u32 s45, s21, -1
	s_cmp_eq_u32 s72, 12
	s_cselect_b32 s47, s37, s45
	s_cselect_b32 s46, s43, s44
	s_cselect_b32 s45, s35, s71
	s_cselect_b32 s44, s69, s70
	s_add_i32 m0, s59, 0xc000
	ds_read_b128 v[200:203], v166
	ds_read_b128 v[204:207], v166 offset:1024
	ds_read_b128 v[208:211], v166 offset:2048
	ds_read_b128 v[212:215], v166 offset:3072
	ds_read_b128 v[216:219], v166 offset:4096
	ds_read_b128 v[220:223], v166 offset:5120
	ds_read_b128 v[224:227], v166 offset:6144
	ds_read_b128 v[228:231], v166 offset:7168
	global_load_lds_dwordx4 v138, s[20:21]
	s_add_i32 m0, s59, 0xe000
	s_nop 0
	global_load_lds_dwordx4 v140, s[20:21]
	s_waitcnt vmcnt(8)
	s_waitcnt lgkmcnt(0)
	s_barrier
	s_setprio 1
	s_waitcnt lgkmcnt(0)
	v_mfma_f32_16x16x32_bf16 v[124:127], v[146:149], v[200:203], v[124:127]
	v_mfma_f32_16x16x32_bf16 v[120:123], v[172:175], v[200:203], v[120:123]
	v_mfma_f32_16x16x32_bf16 v[108:111], v[146:149], v[208:211], v[108:111]
	v_mfma_f32_16x16x32_bf16 v[104:107], v[172:175], v[208:211], v[104:107]
	v_mfma_f32_16x16x32_bf16 v[92:95], v[146:149], v[216:219], v[92:95]
	v_mfma_f32_16x16x32_bf16 v[88:91], v[172:175], v[216:219], v[88:91]
	v_mfma_f32_16x16x32_bf16 v[76:79], v[146:149], v[224:227], v[76:79]
	v_mfma_f32_16x16x32_bf16 v[72:75], v[172:175], v[224:227], v[72:75]
	v_mfma_f32_16x16x32_bf16 v[124:127], v[168:171], v[204:207], v[124:127]
	v_mfma_f32_16x16x32_bf16 v[120:123], v[176:179], v[204:207], v[120:123]
	v_mfma_f32_16x16x32_bf16 v[108:111], v[168:171], v[212:215], v[108:111]
	v_mfma_f32_16x16x32_bf16 v[104:107], v[176:179], v[212:215], v[104:107]
	v_mfma_f32_16x16x32_bf16 v[92:95], v[168:171], v[220:223], v[92:95]
	v_mfma_f32_16x16x32_bf16 v[88:91], v[176:179], v[220:223], v[88:91]
	v_mfma_f32_16x16x32_bf16 v[76:79], v[168:171], v[228:231], v[76:79]
	v_mfma_f32_16x16x32_bf16 v[72:75], v[176:179], v[228:231], v[72:75]
	s_setprio 0
	s_setprio 1
	v_mfma_f32_16x16x32_bf16 v[116:119], v[180:183], v[200:203], v[116:119]
	v_mfma_f32_16x16x32_bf16 v[112:115], v[188:191], v[200:203], v[112:115]
	v_mfma_f32_16x16x32_bf16 v[100:103], v[180:183], v[208:211], v[100:103]
	v_mfma_f32_16x16x32_bf16 v[96:99], v[188:191], v[208:211], v[96:99]
	v_mfma_f32_16x16x32_bf16 v[84:87], v[180:183], v[216:219], v[84:87]
	v_mfma_f32_16x16x32_bf16 v[80:83], v[188:191], v[216:219], v[80:83]
	v_mfma_f32_16x16x32_bf16 v[68:71], v[180:183], v[224:227], v[68:71]
	v_mfma_f32_16x16x32_bf16 v[64:67], v[188:191], v[224:227], v[64:67]
	v_mfma_f32_16x16x32_bf16 v[116:119], v[184:187], v[204:207], v[116:119]
	v_mfma_f32_16x16x32_bf16 v[112:115], v[196:199], v[204:207], v[112:115]
	v_mfma_f32_16x16x32_bf16 v[100:103], v[184:187], v[212:215], v[100:103]
	v_mfma_f32_16x16x32_bf16 v[96:99], v[196:199], v[212:215], v[96:99]
	v_mfma_f32_16x16x32_bf16 v[84:87], v[184:187], v[220:223], v[84:87]
	v_mfma_f32_16x16x32_bf16 v[80:83], v[196:199], v[220:223], v[80:83]
	v_mfma_f32_16x16x32_bf16 v[68:71], v[184:187], v[228:231], v[68:71]
	v_mfma_f32_16x16x32_bf16 v[64:67], v[196:199], v[228:231], v[64:67]
	s_setprio 0
	s_barrier
	s_add_i32 s73, s66, s33
	v_lshl_add_u64 v[150:151], s[44:45], 0, v[130:131]
	s_mov_b32 m0, s73
	ds_read_b128 v[200:203], v166 offset:16384
	ds_read_b128 v[204:207], v166 offset:17408
	ds_read_b128 v[208:211], v166 offset:18432
	ds_read_b128 v[212:215], v166 offset:19456
	ds_read_b128 v[216:219], v166 offset:20480
	ds_read_b128 v[220:223], v166 offset:21504
	ds_read_b128 v[224:227], v166 offset:22528
	ds_read_b128 v[228:231], v166 offset:23552
	global_load_lds_dwordx4 v[150:151], off
	s_add_i32 m0, s73, 0x2000
	s_add_u32 s74, s44, 0x40000
	v_lshl_add_u64 v[192:193], s[44:45], 0, v[134:135]
	s_addc_u32 s75, s45, 0
	s_add_i32 s73, s67, s33
	global_load_lds_dwordx4 v[192:193], off
	s_mov_b32 m0, s73
	v_lshl_add_u64 v[234:235], s[46:47], 0, v[132:133]
	global_load_lds_dwordx4 v130, s[74:75]
	s_add_i32 m0, s73, 0x2000
	s_nop 0
	global_load_lds_dwordx4 v134, s[74:75]
	v_lshl_add_u64 v[232:233], s[46:47], 0, v[128:129]
	s_mov_b32 m0, s59
	s_nop 0
	global_load_lds_dwordx4 v[232:233], off
	s_mov_b32 m0, s60
	s_nop 0
	global_load_lds_dwordx4 v[234:235], off
	s_waitcnt vmcnt(8)
	s_waitcnt lgkmcnt(0)
	s_barrier
	s_setprio 1
	s_waitcnt lgkmcnt(0)
	v_mfma_f32_16x16x32_bf16 v[60:63], v[146:149], v[200:203], v[60:63]
	v_mfma_f32_16x16x32_bf16 v[56:59], v[172:175], v[200:203], v[56:59]
	v_mfma_f32_16x16x32_bf16 v[44:47], v[146:149], v[208:211], v[44:47]
	v_mfma_f32_16x16x32_bf16 v[40:43], v[172:175], v[208:211], v[40:43]
	v_mfma_f32_16x16x32_bf16 v[28:31], v[146:149], v[216:219], v[28:31]
	v_mfma_f32_16x16x32_bf16 v[24:27], v[172:175], v[216:219], v[24:27]
	v_mfma_f32_16x16x32_bf16 v[12:15], v[146:149], v[224:227], v[12:15]
	v_mfma_f32_16x16x32_bf16 v[8:11], v[172:175], v[224:227], v[8:11]
	v_mfma_f32_16x16x32_bf16 v[60:63], v[168:171], v[204:207], v[60:63]
	v_mfma_f32_16x16x32_bf16 v[56:59], v[176:179], v[204:207], v[56:59]
	v_mfma_f32_16x16x32_bf16 v[44:47], v[168:171], v[212:215], v[44:47]
	v_mfma_f32_16x16x32_bf16 v[40:43], v[176:179], v[212:215], v[40:43]
	v_mfma_f32_16x16x32_bf16 v[28:31], v[168:171], v[220:223], v[28:31]
	v_mfma_f32_16x16x32_bf16 v[24:27], v[176:179], v[220:223], v[24:27]
	v_mfma_f32_16x16x32_bf16 v[12:15], v[168:171], v[228:231], v[12:15]
	v_mfma_f32_16x16x32_bf16 v[8:11], v[176:179], v[228:231], v[8:11]
	s_setprio 0
	s_setprio 1
	v_mfma_f32_16x16x32_bf16 v[52:55], v[180:183], v[200:203], v[52:55]
	v_mfma_f32_16x16x32_bf16 v[48:51], v[188:191], v[200:203], v[48:51]
	v_mfma_f32_16x16x32_bf16 v[36:39], v[180:183], v[208:211], v[36:39]
	v_mfma_f32_16x16x32_bf16 v[32:35], v[188:191], v[208:211], v[32:35]
	v_mfma_f32_16x16x32_bf16 v[20:23], v[180:183], v[216:219], v[20:23]
	v_mfma_f32_16x16x32_bf16 v[16:19], v[188:191], v[216:219], v[16:19]
	v_mfma_f32_16x16x32_bf16 v[4:7], v[180:183], v[224:227], v[4:7]
	v_mfma_f32_16x16x32_bf16 v[0:3], v[188:191], v[224:227], v[0:3]
	v_mfma_f32_16x16x32_bf16 v[52:55], v[184:187], v[204:207], v[52:55]
	v_mfma_f32_16x16x32_bf16 v[48:51], v[196:199], v[204:207], v[48:51]
	v_mfma_f32_16x16x32_bf16 v[36:39], v[184:187], v[212:215], v[36:39]
	v_mfma_f32_16x16x32_bf16 v[32:35], v[196:199], v[212:215], v[32:35]
	v_mfma_f32_16x16x32_bf16 v[20:23], v[184:187], v[220:223], v[20:23]
	v_mfma_f32_16x16x32_bf16 v[16:19], v[196:199], v[220:223], v[16:19]
	v_mfma_f32_16x16x32_bf16 v[4:7], v[184:187], v[228:231], v[4:7]
	v_mfma_f32_16x16x32_bf16 v[0:3], v[196:199], v[228:231], v[0:3]
	s_setprio 0
	s_barrier
	s_add_i32 s73, 0, 0x18000
	v_add_u32_e32 v167, s73, v152
	s_add_i32 s74, 0, 0x1c000
	ds_read_b128 v[146:149], v167
	ds_read_b128 v[168:171], v167 offset:1024
	ds_read_b128 v[172:175], v167 offset:2048
	ds_read_b128 v[176:179], v167 offset:3072
	v_add_u32_e32 v167, s74, v152
	ds_read_b128 v[180:183], v167
	ds_read_b128 v[184:187], v167 offset:1024
	ds_read_b128 v[188:191], v167 offset:2048
	ds_read_b128 v[196:199], v167 offset:3072
	s_add_u32 s46, s46, 0x40000
	s_addc_u32 s47, s47, 0
	s_mov_b32 m0, s61
	ds_read_b128 v[200:203], v166 offset:32768
	ds_read_b128 v[204:207], v166 offset:33792
	ds_read_b128 v[208:211], v166 offset:34816
	ds_read_b128 v[212:215], v166 offset:35840
	ds_read_b128 v[216:219], v166 offset:36864
	ds_read_b128 v[220:223], v166 offset:37888
	ds_read_b128 v[224:227], v166 offset:38912
	ds_read_b128 v[228:231], v166 offset:39936
	global_load_lds_dwordx4 v128, s[46:47]
	v_lshl_add_u64 v[236:237], s[46:47], 0, v[132:133]
	s_mov_b32 m0, s62
	s_nop 0
	global_load_lds_dwordx4 v[236:237], off
	s_waitcnt vmcnt(8)
	s_waitcnt lgkmcnt(0)
	s_barrier
	s_setprio 1
	s_waitcnt lgkmcnt(0)
	v_mfma_f32_16x16x32_bf16 v[124:127], v[146:149], v[200:203], v[124:127]
	v_mfma_f32_16x16x32_bf16 v[120:123], v[172:175], v[200:203], v[120:123]
	v_mfma_f32_16x16x32_bf16 v[108:111], v[146:149], v[208:211], v[108:111]
	v_mfma_f32_16x16x32_bf16 v[104:107], v[172:175], v[208:211], v[104:107]
	v_mfma_f32_16x16x32_bf16 v[92:95], v[146:149], v[216:219], v[92:95]
	v_mfma_f32_16x16x32_bf16 v[88:91], v[172:175], v[216:219], v[88:91]
	v_mfma_f32_16x16x32_bf16 v[76:79], v[146:149], v[224:227], v[76:79]
	v_mfma_f32_16x16x32_bf16 v[72:75], v[172:175], v[224:227], v[72:75]
	v_mfma_f32_16x16x32_bf16 v[124:127], v[168:171], v[204:207], v[124:127]
	v_mfma_f32_16x16x32_bf16 v[120:123], v[176:179], v[204:207], v[120:123]
	v_mfma_f32_16x16x32_bf16 v[108:111], v[168:171], v[212:215], v[108:111]
	v_mfma_f32_16x16x32_bf16 v[104:107], v[176:179], v[212:215], v[104:107]
	v_mfma_f32_16x16x32_bf16 v[92:95], v[168:171], v[220:223], v[92:95]
	v_mfma_f32_16x16x32_bf16 v[88:91], v[176:179], v[220:223], v[88:91]
	v_mfma_f32_16x16x32_bf16 v[76:79], v[168:171], v[228:231], v[76:79]
	v_mfma_f32_16x16x32_bf16 v[72:75], v[176:179], v[228:231], v[72:75]
	s_setprio 0
	s_setprio 1
	v_mfma_f32_16x16x32_bf16 v[116:119], v[180:183], v[200:203], v[116:119]
	v_mfma_f32_16x16x32_bf16 v[112:115], v[188:191], v[200:203], v[112:115]
	v_mfma_f32_16x16x32_bf16 v[100:103], v[180:183], v[208:211], v[100:103]
	v_mfma_f32_16x16x32_bf16 v[96:99], v[188:191], v[208:211], v[96:99]
	v_mfma_f32_16x16x32_bf16 v[84:87], v[180:183], v[216:219], v[84:87]
	v_mfma_f32_16x16x32_bf16 v[80:83], v[188:191], v[216:219], v[80:83]
	v_mfma_f32_16x16x32_bf16 v[68:71], v[180:183], v[224:227], v[68:71]
	v_mfma_f32_16x16x32_bf16 v[64:67], v[188:191], v[224:227], v[64:67]
	v_mfma_f32_16x16x32_bf16 v[116:119], v[184:187], v[204:207], v[116:119]
	v_mfma_f32_16x16x32_bf16 v[112:115], v[196:199], v[204:207], v[112:115]
	v_mfma_f32_16x16x32_bf16 v[100:103], v[184:187], v[212:215], v[100:103]
	v_mfma_f32_16x16x32_bf16 v[96:99], v[196:199], v[212:215], v[96:99]
	v_mfma_f32_16x16x32_bf16 v[84:87], v[184:187], v[220:223], v[84:87]
	v_mfma_f32_16x16x32_bf16 v[80:83], v[196:199], v[220:223], v[80:83]
	v_mfma_f32_16x16x32_bf16 v[68:71], v[184:187], v[228:231], v[68:71]
	v_mfma_f32_16x16x32_bf16 v[64:67], v[196:199], v[228:231], v[64:67]
	s_setprio 0
	s_barrier
	s_add_i32 s46, s73, s33
	v_lshl_add_u64 v[150:151], v[150:151], 0, s[10:11]
	s_mov_b32 m0, s46
	ds_read_b128 v[200:203], v166 offset:49152
	ds_read_b128 v[204:207], v166 offset:50176
	ds_read_b128 v[208:211], v166 offset:51200
	ds_read_b128 v[212:215], v166 offset:52224
	ds_read_b128 v[216:219], v166 offset:53248
	ds_read_b128 v[220:223], v166 offset:54272
	ds_read_b128 v[224:227], v166 offset:55296
	ds_read_b128 v[228:231], v166 offset:56320
	global_load_lds_dwordx4 v[150:151], off
	s_add_i32 m0, s46, 0x2000
	s_add_u32 s44, s44, 0x40080
	v_lshl_add_u64 v[150:151], v[192:193], 0, s[10:11]
	s_addc_u32 s45, s45, 0
	s_add_i32 s46, s74, s33
	global_load_lds_dwordx4 v[150:151], off
	s_mov_b32 m0, s46
	s_nop 0
	global_load_lds_dwordx4 v130, s[44:45]
	s_add_i32 m0, s46, 0x2000
	s_nop 0
	global_load_lds_dwordx4 v134, s[44:45]
	v_lshl_add_u64 v[150:151], v[232:233], 0, s[10:11]
	s_mov_b32 m0, s64
	s_nop 0
	global_load_lds_dwordx4 v[150:151], off
	v_lshl_add_u64 v[150:151], v[234:235], 0, s[10:11]
	s_mov_b32 m0, s65
	s_nop 0
	global_load_lds_dwordx4 v[150:151], off
	s_waitcnt vmcnt(8)
	s_waitcnt lgkmcnt(0)
	s_barrier
	s_setprio 1
	s_waitcnt lgkmcnt(0)
	v_mfma_f32_16x16x32_bf16 v[60:63], v[146:149], v[200:203], v[60:63]
	v_mfma_f32_16x16x32_bf16 v[56:59], v[172:175], v[200:203], v[56:59]
	v_mfma_f32_16x16x32_bf16 v[44:47], v[146:149], v[208:211], v[44:47]
	v_mfma_f32_16x16x32_bf16 v[40:43], v[172:175], v[208:211], v[40:43]
	v_mfma_f32_16x16x32_bf16 v[28:31], v[146:149], v[216:219], v[28:31]
	v_mfma_f32_16x16x32_bf16 v[24:27], v[172:175], v[216:219], v[24:27]
	v_mfma_f32_16x16x32_bf16 v[12:15], v[146:149], v[224:227], v[12:15]
	v_mfma_f32_16x16x32_bf16 v[8:11], v[172:175], v[224:227], v[8:11]
	v_mfma_f32_16x16x32_bf16 v[60:63], v[168:171], v[204:207], v[60:63]
	v_mfma_f32_16x16x32_bf16 v[56:59], v[176:179], v[204:207], v[56:59]
	v_mfma_f32_16x16x32_bf16 v[44:47], v[168:171], v[212:215], v[44:47]
	v_mfma_f32_16x16x32_bf16 v[40:43], v[176:179], v[212:215], v[40:43]
	v_mfma_f32_16x16x32_bf16 v[28:31], v[168:171], v[220:223], v[28:31]
	v_mfma_f32_16x16x32_bf16 v[24:27], v[176:179], v[220:223], v[24:27]
	v_mfma_f32_16x16x32_bf16 v[12:15], v[168:171], v[228:231], v[12:15]
	v_mfma_f32_16x16x32_bf16 v[8:11], v[176:179], v[228:231], v[8:11]
	s_setprio 0
	s_setprio 1
	v_mfma_f32_16x16x32_bf16 v[52:55], v[180:183], v[200:203], v[52:55]
	v_mfma_f32_16x16x32_bf16 v[48:51], v[188:191], v[200:203], v[48:51]
	v_mfma_f32_16x16x32_bf16 v[36:39], v[180:183], v[208:211], v[36:39]
	v_mfma_f32_16x16x32_bf16 v[32:35], v[188:191], v[208:211], v[32:35]
	v_mfma_f32_16x16x32_bf16 v[20:23], v[180:183], v[216:219], v[20:23]
	v_mfma_f32_16x16x32_bf16 v[16:19], v[188:191], v[216:219], v[16:19]
	v_mfma_f32_16x16x32_bf16 v[4:7], v[180:183], v[224:227], v[4:7]
	v_mfma_f32_16x16x32_bf16 v[0:3], v[188:191], v[224:227], v[0:3]
	v_mfma_f32_16x16x32_bf16 v[52:55], v[184:187], v[204:207], v[52:55]
	v_mfma_f32_16x16x32_bf16 v[48:51], v[196:199], v[204:207], v[48:51]
	v_mfma_f32_16x16x32_bf16 v[36:39], v[184:187], v[212:215], v[36:39]
	v_mfma_f32_16x16x32_bf16 v[32:35], v[196:199], v[212:215], v[32:35]
	v_mfma_f32_16x16x32_bf16 v[20:23], v[184:187], v[220:223], v[20:23]
	v_mfma_f32_16x16x32_bf16 v[16:19], v[196:199], v[220:223], v[16:19]
	v_mfma_f32_16x16x32_bf16 v[4:7], v[184:187], v[228:231], v[4:7]
	v_mfma_f32_16x16x32_bf16 v[0:3], v[196:199], v[228:231], v[0:3]
	s_setprio 0
	s_barrier
	s_add_i32 s72, s72, 2
	s_add_u32 s20, s20, 0x100
	s_addc_u32 s21, s21, 0
	s_add_u32 s70, s70, 0x100
	s_addc_u32 s71, s71, 0
	s_cmp_gt_u32 s72, 13
	s_cbranch_scc0 .LBB0_1624
	s_and_b64 vcc, exec, s[12:13]
	s_cbranch_vccz .LBB0_1627
	s_barrier

.LBB0_1691:
	s_lshl_b32 s5, s5, 5
	s_mov_b64 s[8:9], 0x80
	s_and_b32 s5, s5, 0x60
	s_add_i32 m0, s25, 0x18000
	v_lshl_add_u64 v[6:7], v[6:7], 0, s[8:9]
	s_ashr_i32 s45, s22, 31
	s_ashr_i32 s46, s2, 31
	s_lshl_b32 s11, s4, 13
	s_lshl_b32 s14, s5, 7
	s_waitcnt vmcnt(2)
	s_barrier
	global_load_lds_dwordx4 v[6:7], off
	v_lshl_add_u64 v[4:5], v[4:5], 0, s[8:9]
	s_add_i32 m0, s25, 0x1a000
	s_add_i32 s47, s25, 0x8000
	s_add_i32 s50, s25, 0xa000
	global_load_lds_dwordx4 v[4:5], off
	v_lshl_add_u64 v[0:1], v[0:1], 0, s[8:9]
	s_mov_b32 m0, s47
	s_add_u32 s12, s36, 0x80080
	global_load_lds_dwordx4 v[0:1], off
	v_lshl_add_u64 v[0:1], v[2:3], 0, s[8:9]
	s_mov_b32 m0, s50
	s_addc_u32 s13, s37, 0
	global_load_lds_dwordx4 v[0:1], off
	s_add_i32 m0, s25, 0x1c000
	s_nop 0
	global_load_lds_dwordx4 v130, s[12:13]
	v_lshl_add_u64 v[0:1], s[12:13], 0, v[134:135]
	s_add_i32 m0, s25, 0x1e000
	s_movk_i32 s12, 0x3c0
	global_load_lds_dwordx4 v[0:1], off
	v_lshlrev_b32_e32 v0, 1, v9
	v_lshlrev_b32_e32 v2, 2, v194
	v_and_or_b32 v1, v157, s12, v0
	v_and_b32_e32 v2, 32, v2
	v_lshl_or_b32 v0, v156, 6, v0
	v_bitop3_b32 v165, s14, v1, v2 bitop3:0xf6
	v_lshlrev_b32_e32 v1, 9, v194
	v_bitop3_b32 v0, v0, s11, v2 bitop3:0xde
	v_and_b32_e32 v1, 0x70000, v1
	v_lshlrev_b32_e32 v2, 12, v155
	v_or3_b32 v1, v8, v1, v2
	v_add_u32_e32 v138, v1, v154
	v_lshlrev_b32_e32 v1, 5, v10
	s_waitcnt vmcnt(6)
	s_cmpk_lt_u32 s10, 0x100
	v_and_b32_e32 v1, 0xf0000, v1
	s_cselect_b64 s[10:11], -1, 0
	v_or3_b32 v1, v8, v1, v2
	s_add_i32 s56, 0, 0x10000
	s_add_i32 s57, 0, 0x14000
	v_lshl_or_b32 v164, s4, 6, v156
	v_or_b32_e32 v166, s5, v9
	v_mov_b32_e32 v139, v137
	v_add_u32_e32 v140, v1, v154
	v_mov_b32_e32 v141, v137
	v_mov_b64_e32 v[142:143], 0x210
	v_mov_b64_e32 v[144:145], 0x20f
	s_movk_i32 s51, 0x43
	v_add_u32_e32 v167, s56, v165
	v_add_u32_e32 v168, s57, v165
	v_add_u32_e32 v169, 0, v0
	s_movk_i32 s58, 0x3fff
	s_barrier
	s_branch .LBB0_1694

.LBB0_1697:
	ds_read_b128 v[146:149], v167
	ds_read_b128 v[150:153], v167 offset:1024
	ds_read_b128 v[170:173], v167 offset:2048
	ds_read_b128 v[174:177], v167 offset:3072
	ds_read_b128 v[178:181], v168
	ds_read_b128 v[182:185], v168 offset:1024
	ds_read_b128 v[186:189], v168 offset:2048
	ds_read_b128 v[190:193], v168 offset:3072
	s_add_u32 s36, s20, 0xfff80080
	s_addc_u32 s37, s21, -1
	s_cmp_eq_u32 s63, 28
	s_cselect_b32 s39, s15, s37
	s_cselect_b32 s38, s59, s36
	s_cselect_b32 s37, s13, s62
	s_cselect_b32 s36, s60, s61
	s_add_i32 m0, s25, 0xc000
	ds_read_b128 v[196:199], v169
	ds_read_b128 v[200:203], v169 offset:1024
	ds_read_b128 v[204:207], v169 offset:2048
	ds_read_b128 v[208:211], v169 offset:3072
	ds_read_b128 v[212:215], v169 offset:4096
	ds_read_b128 v[216:219], v169 offset:5120
	ds_read_b128 v[220:223], v169 offset:6144
	ds_read_b128 v[224:227], v169 offset:7168
	global_load_lds_dwordx4 v138, s[20:21]
	s_add_i32 m0, s25, 0xe000
	s_nop 0
	global_load_lds_dwordx4 v140, s[20:21]
	s_waitcnt vmcnt(8)
	s_waitcnt lgkmcnt(0)
	s_barrier
	s_setprio 1
	s_waitcnt lgkmcnt(0)
	v_mfma_f32_16x16x32_bf16 v[124:127], v[146:149], v[196:199], v[124:127]
	v_mfma_f32_16x16x32_bf16 v[120:123], v[170:173], v[196:199], v[120:123]
	v_mfma_f32_16x16x32_bf16 v[108:111], v[146:149], v[204:207], v[108:111]
	v_mfma_f32_16x16x32_bf16 v[104:107], v[170:173], v[204:207], v[104:107]
	v_mfma_f32_16x16x32_bf16 v[92:95], v[146:149], v[212:215], v[92:95]
	v_mfma_f32_16x16x32_bf16 v[88:91], v[170:173], v[212:215], v[88:91]
	v_mfma_f32_16x16x32_bf16 v[76:79], v[146:149], v[220:223], v[76:79]
	v_mfma_f32_16x16x32_bf16 v[72:75], v[170:173], v[220:223], v[72:75]
	v_mfma_f32_16x16x32_bf16 v[124:127], v[150:153], v[200:203], v[124:127]
	v_mfma_f32_16x16x32_bf16 v[120:123], v[174:177], v[200:203], v[120:123]
	v_mfma_f32_16x16x32_bf16 v[108:111], v[150:153], v[208:211], v[108:111]
	v_mfma_f32_16x16x32_bf16 v[104:107], v[174:177], v[208:211], v[104:107]
	v_mfma_f32_16x16x32_bf16 v[92:95], v[150:153], v[216:219], v[92:95]
	v_mfma_f32_16x16x32_bf16 v[88:91], v[174:177], v[216:219], v[88:91]
	v_mfma_f32_16x16x32_bf16 v[76:79], v[150:153], v[224:227], v[76:79]
	v_mfma_f32_16x16x32_bf16 v[72:75], v[174:177], v[224:227], v[72:75]
	s_setprio 0
	s_setprio 1
	v_mfma_f32_16x16x32_bf16 v[116:119], v[178:181], v[196:199], v[116:119]
	v_mfma_f32_16x16x32_bf16 v[112:115], v[186:189], v[196:199], v[112:115]
	v_mfma_f32_16x16x32_bf16 v[100:103], v[178:181], v[204:207], v[100:103]
	v_mfma_f32_16x16x32_bf16 v[96:99], v[186:189], v[204:207], v[96:99]
	v_mfma_f32_16x16x32_bf16 v[84:87], v[178:181], v[212:215], v[84:87]
	v_mfma_f32_16x16x32_bf16 v[80:83], v[186:189], v[212:215], v[80:83]
	v_mfma_f32_16x16x32_bf16 v[68:71], v[178:181], v[220:223], v[68:71]
	v_mfma_f32_16x16x32_bf16 v[64:67], v[186:189], v[220:223], v[64:67]
	v_mfma_f32_16x16x32_bf16 v[116:119], v[182:185], v[200:203], v[116:119]
	v_mfma_f32_16x16x32_bf16 v[112:115], v[190:193], v[200:203], v[112:115]
	v_mfma_f32_16x16x32_bf16 v[100:103], v[182:185], v[208:211], v[100:103]
	v_mfma_f32_16x16x32_bf16 v[96:99], v[190:193], v[208:211], v[96:99]
	v_mfma_f32_16x16x32_bf16 v[84:87], v[182:185], v[216:219], v[84:87]
	v_mfma_f32_16x16x32_bf16 v[80:83], v[190:193], v[216:219], v[80:83]
	v_mfma_f32_16x16x32_bf16 v[68:71], v[182:185], v[224:227], v[68:71]
	v_mfma_f32_16x16x32_bf16 v[64:67], v[190:193], v[224:227], v[64:67]
	s_setprio 0
	s_barrier
	s_add_i32 s64, s56, s41
	v_lshl_add_u64 v[228:229], s[36:37], 0, v[130:131]
	s_mov_b32 m0, s64
	ds_read_b128 v[196:199], v169 offset:16384
	ds_read_b128 v[200:203], v169 offset:17408
	ds_read_b128 v[204:207], v169 offset:18432
	ds_read_b128 v[208:211], v169 offset:19456
	ds_read_b128 v[212:215], v169 offset:20480
	ds_read_b128 v[216:219], v169 offset:21504
	ds_read_b128 v[220:223], v169 offset:22528
	ds_read_b128 v[224:227], v169 offset:23552
	global_load_lds_dwordx4 v[228:229], off
	s_add_i32 m0, s64, 0x2000
	s_add_u32 s64, s36, 0x80000
	v_lshl_add_u64 v[230:231], s[36:37], 0, v[134:135]
	s_addc_u32 s65, s37, 0
	s_add_i32 s66, s57, s41
	global_load_lds_dwordx4 v[230:231], off
	s_mov_b32 m0, s66
	v_lshl_add_u64 v[234:235], s[38:39], 0, v[132:133]
	global_load_lds_dwordx4 v130, s[64:65]
	s_add_i32 m0, s66, 0x2000
	s_nop 0
	global_load_lds_dwordx4 v134, s[64:65]
	v_lshl_add_u64 v[232:233], s[38:39], 0, v[128:129]
	s_mov_b32 m0, s25
	s_nop 0
	global_load_lds_dwordx4 v[232:233], off
	s_mov_b32 m0, s35
	s_nop 0
	global_load_lds_dwordx4 v[234:235], off
	s_waitcnt vmcnt(8)
	s_waitcnt lgkmcnt(0)
	s_barrier
	s_setprio 1
	s_waitcnt lgkmcnt(0)
	v_mfma_f32_16x16x32_bf16 v[60:63], v[146:149], v[196:199], v[60:63]
	v_mfma_f32_16x16x32_bf16 v[56:59], v[170:173], v[196:199], v[56:59]
	v_mfma_f32_16x16x32_bf16 v[44:47], v[146:149], v[204:207], v[44:47]
	v_mfma_f32_16x16x32_bf16 v[40:43], v[170:173], v[204:207], v[40:43]
	v_mfma_f32_16x16x32_bf16 v[28:31], v[146:149], v[212:215], v[28:31]
	v_mfma_f32_16x16x32_bf16 v[24:27], v[170:173], v[212:215], v[24:27]
	v_mfma_f32_16x16x32_bf16 v[12:15], v[146:149], v[220:223], v[12:15]
	v_mfma_f32_16x16x32_bf16 v[8:11], v[170:173], v[220:223], v[8:11]
	v_mfma_f32_16x16x32_bf16 v[60:63], v[150:153], v[200:203], v[60:63]
	v_mfma_f32_16x16x32_bf16 v[56:59], v[174:177], v[200:203], v[56:59]
	v_mfma_f32_16x16x32_bf16 v[44:47], v[150:153], v[208:211], v[44:47]
	v_mfma_f32_16x16x32_bf16 v[40:43], v[174:177], v[208:211], v[40:43]
	v_mfma_f32_16x16x32_bf16 v[28:31], v[150:153], v[216:219], v[28:31]
	v_mfma_f32_16x16x32_bf16 v[24:27], v[174:177], v[216:219], v[24:27]
	v_mfma_f32_16x16x32_bf16 v[12:15], v[150:153], v[224:227], v[12:15]
	v_mfma_f32_16x16x32_bf16 v[8:11], v[174:177], v[224:227], v[8:11]
	s_setprio 0
	s_setprio 1
	v_mfma_f32_16x16x32_bf16 v[52:55], v[178:181], v[196:199], v[52:55]
	v_mfma_f32_16x16x32_bf16 v[48:51], v[186:189], v[196:199], v[48:51]
	v_mfma_f32_16x16x32_bf16 v[36:39], v[178:181], v[204:207], v[36:39]
	v_mfma_f32_16x16x32_bf16 v[32:35], v[186:189], v[204:207], v[32:35]
	v_mfma_f32_16x16x32_bf16 v[20:23], v[178:181], v[212:215], v[20:23]
	v_mfma_f32_16x16x32_bf16 v[16:19], v[186:189], v[212:215], v[16:19]
	v_mfma_f32_16x16x32_bf16 v[4:7], v[178:181], v[220:223], v[4:7]
	v_mfma_f32_16x16x32_bf16 v[0:3], v[186:189], v[220:223], v[0:3]
	v_mfma_f32_16x16x32_bf16 v[52:55], v[182:185], v[200:203], v[52:55]
	v_mfma_f32_16x16x32_bf16 v[48:51], v[190:193], v[200:203], v[48:51]
	v_mfma_f32_16x16x32_bf16 v[36:39], v[182:185], v[208:211], v[36:39]
	v_mfma_f32_16x16x32_bf16 v[32:35], v[190:193], v[208:211], v[32:35]
	v_mfma_f32_16x16x32_bf16 v[20:23], v[182:185], v[216:219], v[20:23]
	v_mfma_f32_16x16x32_bf16 v[16:19], v[190:193], v[216:219], v[16:19]
	v_mfma_f32_16x16x32_bf16 v[4:7], v[182:185], v[224:227], v[4:7]
	v_mfma_f32_16x16x32_bf16 v[0:3], v[190:193], v[224:227], v[0:3]
	s_setprio 0
	s_barrier
	s_add_i32 s64, 0, 0x18000
	v_add_u32_e32 v136, s64, v165
	s_add_i32 s65, 0, 0x1c000
	ds_read_b128 v[146:149], v136
	ds_read_b128 v[150:153], v136 offset:1024
	ds_read_b128 v[170:173], v136 offset:2048
	ds_read_b128 v[174:177], v136 offset:3072
	v_add_u32_e32 v136, s65, v165
	ds_read_b128 v[178:181], v136
	ds_read_b128 v[182:185], v136 offset:1024
	ds_read_b128 v[186:189], v136 offset:2048
	ds_read_b128 v[190:193], v136 offset:3072
	s_add_u32 s38, s38, 0x80000
	s_addc_u32 s39, s39, 0
	s_mov_b32 m0, s42
	ds_read_b128 v[196:199], v169 offset:32768
	ds_read_b128 v[200:203], v169 offset:33792
	ds_read_b128 v[204:207], v169 offset:34816
	ds_read_b128 v[208:211], v169 offset:35840
	ds_read_b128 v[212:215], v169 offset:36864
	ds_read_b128 v[216:219], v169 offset:37888
	ds_read_b128 v[220:223], v169 offset:38912
	ds_read_b128 v[224:227], v169 offset:39936
	global_load_lds_dwordx4 v128, s[38:39]
	v_lshl_add_u64 v[236:237], s[38:39], 0, v[132:133]
	s_mov_b32 m0, s43
	s_nop 0
	global_load_lds_dwordx4 v[236:237], off
	s_waitcnt vmcnt(8)
	s_waitcnt lgkmcnt(0)
	s_barrier
	s_setprio 1
	s_waitcnt lgkmcnt(0)
	v_mfma_f32_16x16x32_bf16 v[124:127], v[146:149], v[196:199], v[124:127]
	v_mfma_f32_16x16x32_bf16 v[120:123], v[170:173], v[196:199], v[120:123]
	v_mfma_f32_16x16x32_bf16 v[108:111], v[146:149], v[204:207], v[108:111]
	v_mfma_f32_16x16x32_bf16 v[104:107], v[170:173], v[204:207], v[104:107]
	v_mfma_f32_16x16x32_bf16 v[92:95], v[146:149], v[212:215], v[92:95]
	v_mfma_f32_16x16x32_bf16 v[88:91], v[170:173], v[212:215], v[88:91]
	v_mfma_f32_16x16x32_bf16 v[76:79], v[146:149], v[220:223], v[76:79]
	v_mfma_f32_16x16x32_bf16 v[72:75], v[170:173], v[220:223], v[72:75]
	v_mfma_f32_16x16x32_bf16 v[124:127], v[150:153], v[200:203], v[124:127]
	v_mfma_f32_16x16x32_bf16 v[120:123], v[174:177], v[200:203], v[120:123]
	v_mfma_f32_16x16x32_bf16 v[108:111], v[150:153], v[208:211], v[108:111]
	v_mfma_f32_16x16x32_bf16 v[104:107], v[174:177], v[208:211], v[104:107]
	v_mfma_f32_16x16x32_bf16 v[92:95], v[150:153], v[216:219], v[92:95]
	v_mfma_f32_16x16x32_bf16 v[88:91], v[174:177], v[216:219], v[88:91]
	v_mfma_f32_16x16x32_bf16 v[76:79], v[150:153], v[224:227], v[76:79]
	v_mfma_f32_16x16x32_bf16 v[72:75], v[174:177], v[224:227], v[72:75]
	s_setprio 0
	s_setprio 1
	v_mfma_f32_16x16x32_bf16 v[116:119], v[178:181], v[196:199], v[116:119]
	v_mfma_f32_16x16x32_bf16 v[112:115], v[186:189], v[196:199], v[112:115]
	v_mfma_f32_16x16x32_bf16 v[100:103], v[178:181], v[204:207], v[100:103]
	v_mfma_f32_16x16x32_bf16 v[96:99], v[186:189], v[204:207], v[96:99]
	v_mfma_f32_16x16x32_bf16 v[84:87], v[178:181], v[212:215], v[84:87]
	v_mfma_f32_16x16x32_bf16 v[80:83], v[186:189], v[212:215], v[80:83]
	v_mfma_f32_16x16x32_bf16 v[68:71], v[178:181], v[220:223], v[68:71]
	v_mfma_f32_16x16x32_bf16 v[64:67], v[186:189], v[220:223], v[64:67]
	v_mfma_f32_16x16x32_bf16 v[116:119], v[182:185], v[200:203], v[116:119]
	v_mfma_f32_16x16x32_bf16 v[112:115], v[190:193], v[200:203], v[112:115]
	v_mfma_f32_16x16x32_bf16 v[100:103], v[182:185], v[208:211], v[100:103]
	v_mfma_f32_16x16x32_bf16 v[96:99], v[190:193], v[208:211], v[96:99]
	v_mfma_f32_16x16x32_bf16 v[84:87], v[182:185], v[216:219], v[84:87]
	v_mfma_f32_16x16x32_bf16 v[80:83], v[190:193], v[216:219], v[80:83]
	v_mfma_f32_16x16x32_bf16 v[68:71], v[182:185], v[224:227], v[68:71]
	v_mfma_f32_16x16x32_bf16 v[64:67], v[190:193], v[224:227], v[64:67]
	s_setprio 0
	s_barrier
	s_add_i32 s38, s64, s41
	v_lshl_add_u64 v[228:229], v[228:229], 0, s[8:9]
	s_mov_b32 m0, s38
	ds_read_b128 v[196:199], v169 offset:49152
	ds_read_b128 v[200:203], v169 offset:50176
	ds_read_b128 v[204:207], v169 offset:51200
	ds_read_b128 v[208:211], v169 offset:52224
	ds_read_b128 v[212:215], v169 offset:53248
	ds_read_b128 v[216:219], v169 offset:54272
	ds_read_b128 v[220:223], v169 offset:55296
	ds_read_b128 v[224:227], v169 offset:56320
	global_load_lds_dwordx4 v[228:229], off
	s_add_i32 m0, s38, 0x2000
	s_add_u32 s36, s36, 0x80080
	v_lshl_add_u64 v[228:229], v[230:231], 0, s[8:9]
	s_addc_u32 s37, s37, 0
	s_add_i32 s38, s65, s41
	global_load_lds_dwordx4 v[228:229], off
	s_mov_b32 m0, s38
	s_nop 0
	global_load_lds_dwordx4 v130, s[36:37]
	s_add_i32 m0, s38, 0x2000
	s_nop 0
	global_load_lds_dwordx4 v134, s[36:37]
	v_lshl_add_u64 v[228:229], v[232:233], 0, s[8:9]
	s_mov_b32 m0, s47
	s_nop 0
	global_load_lds_dwordx4 v[228:229], off
	v_lshl_add_u64 v[228:229], v[234:235], 0, s[8:9]
	s_mov_b32 m0, s50
	s_nop 0
	global_load_lds_dwordx4 v[228:229], off
	s_waitcnt vmcnt(8)
	s_waitcnt lgkmcnt(0)
	s_barrier
	s_setprio 1
	s_waitcnt lgkmcnt(0)
	v_mfma_f32_16x16x32_bf16 v[60:63], v[146:149], v[196:199], v[60:63]
	v_mfma_f32_16x16x32_bf16 v[56:59], v[170:173], v[196:199], v[56:59]
	v_mfma_f32_16x16x32_bf16 v[44:47], v[146:149], v[204:207], v[44:47]
	v_mfma_f32_16x16x32_bf16 v[40:43], v[170:173], v[204:207], v[40:43]
	v_mfma_f32_16x16x32_bf16 v[28:31], v[146:149], v[212:215], v[28:31]
	v_mfma_f32_16x16x32_bf16 v[24:27], v[170:173], v[212:215], v[24:27]
	v_mfma_f32_16x16x32_bf16 v[12:15], v[146:149], v[220:223], v[12:15]
	v_mfma_f32_16x16x32_bf16 v[8:11], v[170:173], v[220:223], v[8:11]
	v_mfma_f32_16x16x32_bf16 v[60:63], v[150:153], v[200:203], v[60:63]
	v_mfma_f32_16x16x32_bf16 v[56:59], v[174:177], v[200:203], v[56:59]
	v_mfma_f32_16x16x32_bf16 v[44:47], v[150:153], v[208:211], v[44:47]
	v_mfma_f32_16x16x32_bf16 v[40:43], v[174:177], v[208:211], v[40:43]
	v_mfma_f32_16x16x32_bf16 v[28:31], v[150:153], v[216:219], v[28:31]
	v_mfma_f32_16x16x32_bf16 v[24:27], v[174:177], v[216:219], v[24:27]
	v_mfma_f32_16x16x32_bf16 v[12:15], v[150:153], v[224:227], v[12:15]
	v_mfma_f32_16x16x32_bf16 v[8:11], v[174:177], v[224:227], v[8:11]
	s_setprio 0
	s_setprio 1
	v_mfma_f32_16x16x32_bf16 v[52:55], v[178:181], v[196:199], v[52:55]
	v_mfma_f32_16x16x32_bf16 v[48:51], v[186:189], v[196:199], v[48:51]
	v_mfma_f32_16x16x32_bf16 v[36:39], v[178:181], v[204:207], v[36:39]
	v_mfma_f32_16x16x32_bf16 v[32:35], v[186:189], v[204:207], v[32:35]
	v_mfma_f32_16x16x32_bf16 v[20:23], v[178:181], v[212:215], v[20:23]
	v_mfma_f32_16x16x32_bf16 v[16:19], v[186:189], v[212:215], v[16:19]
	v_mfma_f32_16x16x32_bf16 v[4:7], v[178:181], v[220:223], v[4:7]
	v_mfma_f32_16x16x32_bf16 v[0:3], v[186:189], v[220:223], v[0:3]
	v_mfma_f32_16x16x32_bf16 v[52:55], v[182:185], v[200:203], v[52:55]
	v_mfma_f32_16x16x32_bf16 v[48:51], v[190:193], v[200:203], v[48:51]
	v_mfma_f32_16x16x32_bf16 v[36:39], v[182:185], v[208:211], v[36:39]
	v_mfma_f32_16x16x32_bf16 v[32:35], v[190:193], v[208:211], v[32:35]
	v_mfma_f32_16x16x32_bf16 v[20:23], v[182:185], v[216:219], v[20:23]
	v_mfma_f32_16x16x32_bf16 v[16:19], v[190:193], v[216:219], v[16:19]
	v_mfma_f32_16x16x32_bf16 v[4:7], v[182:185], v[224:227], v[4:7]
	v_mfma_f32_16x16x32_bf16 v[0:3], v[190:193], v[224:227], v[0:3]
	s_setprio 0
	s_barrier
	s_add_i32 s63, s63, 2
	s_add_u32 s20, s20, 0x100
	s_addc_u32 s21, s21, 0
	s_add_u32 s61, s61, 0x100
	s_addc_u32 s62, s62, 0
	s_cmp_gt_u32 s63, 29
	s_cbranch_scc0 .LBB0_1697
	s_and_b64 vcc, exec, s[10:11]
	s_cbranch_vccz .LBB0_1700
	s_barrier

.LBB0_1854:
	s_lshl_b32 s10, s10, 5
	s_and_b32 s16, s10, 0x60
	s_mov_b64 s[10:11], 0x80
	s_add_i32 m0, s56, 0x18000
	v_lshl_add_u64 v[6:7], v[6:7], 0, s[10:11]
	s_ashr_i32 s61, s22, 31
	s_lshl_b32 s13, s12, 13
	s_lshl_b32 s17, s16, 7
	s_waitcnt vmcnt(2)
	s_barrier
	global_load_lds_dwordx4 v[6:7], off
	v_lshl_add_u64 v[4:5], v[4:5], 0, s[10:11]
	s_add_i32 m0, s56, 0x1a000
	s_add_i32 s62, s56, 0x8000
	s_add_i32 s63, s56, 0xa000
	global_load_lds_dwordx4 v[4:5], off
	v_lshl_add_u64 v[0:1], v[0:1], 0, s[10:11]
	s_mov_b32 m0, s62
	s_add_u32 s14, s48, 0x80080
	global_load_lds_dwordx4 v[0:1], off
	v_lshl_add_u64 v[0:1], v[2:3], 0, s[10:11]
	s_mov_b32 m0, s63
	s_addc_u32 s15, s49, 0
	global_load_lds_dwordx4 v[0:1], off
	s_add_i32 m0, s56, 0x1c000
	s_nop 0
	global_load_lds_dwordx4 v130, s[14:15]
	s_add_i32 m0, s56, 0x1e000
	s_sext_i32_i16 s66, s4
	global_load_lds_dwordx4 v134, s[14:15]
	v_lshlrev_b32_e32 v1, 1, v9
	s_movk_i32 s4, 0x3c0
	v_lshlrev_b32_e32 v0, 2, v194
	v_and_or_b32 v2, v157, s4, v1
	v_and_b32_e32 v3, 32, v0
	v_lshl_or_b32 v1, v156, 6, v1
	v_lshl_or_b32 v0, s12, 6, v156
	v_bitop3_b32 v4, v1, s13, v3 bitop3:0xde
	v_mov_b32_e32 v1, v131
	v_lshlrev_b64 v[0:1], 14, v[0:1]
	s_cmpk_lt_u32 s5, 0x100
	v_lshl_add_u64 v[0:1], s[28:29], 0, v[0:1]
	s_mov_b64 s[4:5], 0xb900000
	v_lshl_add_u64 v[136:137], v[0:1], 0, s[4:5]
	v_lshlrev_b32_e32 v0, 9, v194
	v_and_b32_e32 v0, 0x70000, v0
	v_lshlrev_b32_e32 v1, 12, v155
	v_or3_b32 v0, v8, v0, v1
	v_add_u32_e32 v138, v0, v154
	v_lshlrev_b32_e32 v0, 5, v10
	s_waitcnt vmcnt(6)
	v_and_b32_e32 v0, 0xf0000, v0
	v_bitop3_b32 v146, s17, v2, v3 bitop3:0xf6
	s_cselect_b64 s[12:13], -1, 0
	v_or3_b32 v0, v8, v0, v1
	s_add_i32 s64, 0, 0x10000
	s_add_i32 s65, 0, 0x14000
	v_or_b32_e32 v147, s16, v9
	v_mov_b32_e32 v139, v131
	v_add_u32_e32 v140, v0, v154
	v_mov_b32_e32 v141, v131
	v_mov_b64_e32 v[142:143], 0x840
	v_mov_b64_e32 v[144:145], 0x83f
	v_add_u32_e32 v148, s64, v146
	v_add_u32_e32 v149, s65, v146
	v_add_u32_e32 v150, 0, v4
	s_mov_b64 s[14:15], 0x40000
	s_mov_b64 s[16:17], 0xc0000
	s_mov_b64 s[18:19], 0x200000
	s_mov_b64 s[24:25], 0x240000
	s_mov_b64 s[34:35], 0x280000
	s_mov_b64 s[36:37], 0x2c0000
	s_barrier
	s_waitcnt vmcnt(0)
	s_branch .LBB0_1857

.LBB0_1860:
	ds_read_b128 v[164:167], v148
	ds_read_b128 v[168:171], v148 offset:1024
	ds_read_b128 v[172:175], v148 offset:2048
	ds_read_b128 v[176:179], v148 offset:3072
	ds_read_b128 v[180:183], v149
	ds_read_b128 v[184:187], v149 offset:1024
	ds_read_b128 v[188:191], v149 offset:2048
	ds_read_b128 v[196:199], v149 offset:3072
	s_add_u32 s48, s20, 0xfff80080
	s_addc_u32 s49, s21, -1
	s_cmp_eq_u32 s70, 28
	s_cselect_b32 s51, s41, s49
	s_cselect_b32 s50, s47, s48
	s_cselect_b32 s49, s39, s69
	s_cselect_b32 s48, s67, s68
	s_add_i32 m0, s56, 0xc000
	ds_read_b128 v[200:203], v150
	ds_read_b128 v[204:207], v150 offset:1024
	ds_read_b128 v[208:211], v150 offset:2048
	ds_read_b128 v[212:215], v150 offset:3072
	ds_read_b128 v[216:219], v150 offset:4096
	ds_read_b128 v[220:223], v150 offset:5120
	ds_read_b128 v[224:227], v150 offset:6144
	ds_read_b128 v[228:231], v150 offset:7168
	global_load_lds_dwordx4 v138, s[20:21]
	s_add_i32 m0, s56, 0xe000
	s_nop 0
	global_load_lds_dwordx4 v140, s[20:21]
	s_waitcnt vmcnt(8)
	s_waitcnt lgkmcnt(0)
	s_barrier
	s_setprio 1
	s_waitcnt lgkmcnt(0)
	v_mfma_f32_16x16x32_bf16 v[124:127], v[164:167], v[200:203], v[124:127]
	v_mfma_f32_16x16x32_bf16 v[120:123], v[172:175], v[200:203], v[120:123]
	v_mfma_f32_16x16x32_bf16 v[108:111], v[164:167], v[208:211], v[108:111]
	v_mfma_f32_16x16x32_bf16 v[104:107], v[172:175], v[208:211], v[104:107]
	v_mfma_f32_16x16x32_bf16 v[92:95], v[164:167], v[216:219], v[92:95]
	v_mfma_f32_16x16x32_bf16 v[88:91], v[172:175], v[216:219], v[88:91]
	v_mfma_f32_16x16x32_bf16 v[76:79], v[164:167], v[224:227], v[76:79]
	v_mfma_f32_16x16x32_bf16 v[72:75], v[172:175], v[224:227], v[72:75]
	v_mfma_f32_16x16x32_bf16 v[124:127], v[168:171], v[204:207], v[124:127]
	v_mfma_f32_16x16x32_bf16 v[120:123], v[176:179], v[204:207], v[120:123]
	v_mfma_f32_16x16x32_bf16 v[108:111], v[168:171], v[212:215], v[108:111]
	v_mfma_f32_16x16x32_bf16 v[104:107], v[176:179], v[212:215], v[104:107]
	v_mfma_f32_16x16x32_bf16 v[92:95], v[168:171], v[220:223], v[92:95]
	v_mfma_f32_16x16x32_bf16 v[88:91], v[176:179], v[220:223], v[88:91]
	v_mfma_f32_16x16x32_bf16 v[76:79], v[168:171], v[228:231], v[76:79]
	v_mfma_f32_16x16x32_bf16 v[72:75], v[176:179], v[228:231], v[72:75]
	s_setprio 0
	s_setprio 1
	v_mfma_f32_16x16x32_bf16 v[116:119], v[180:183], v[200:203], v[116:119]
	v_mfma_f32_16x16x32_bf16 v[112:115], v[188:191], v[200:203], v[112:115]
	v_mfma_f32_16x16x32_bf16 v[100:103], v[180:183], v[208:211], v[100:103]
	v_mfma_f32_16x16x32_bf16 v[96:99], v[188:191], v[208:211], v[96:99]
	v_mfma_f32_16x16x32_bf16 v[84:87], v[180:183], v[216:219], v[84:87]
	v_mfma_f32_16x16x32_bf16 v[80:83], v[188:191], v[216:219], v[80:83]
	v_mfma_f32_16x16x32_bf16 v[68:71], v[180:183], v[224:227], v[68:71]
	v_mfma_f32_16x16x32_bf16 v[64:67], v[188:191], v[224:227], v[64:67]
	v_mfma_f32_16x16x32_bf16 v[116:119], v[184:187], v[204:207], v[116:119]
	v_mfma_f32_16x16x32_bf16 v[112:115], v[196:199], v[204:207], v[112:115]
	v_mfma_f32_16x16x32_bf16 v[100:103], v[184:187], v[212:215], v[100:103]
	v_mfma_f32_16x16x32_bf16 v[96:99], v[196:199], v[212:215], v[96:99]
	v_mfma_f32_16x16x32_bf16 v[84:87], v[184:187], v[220:223], v[84:87]
	v_mfma_f32_16x16x32_bf16 v[80:83], v[196:199], v[220:223], v[80:83]
	v_mfma_f32_16x16x32_bf16 v[68:71], v[184:187], v[228:231], v[68:71]
	v_mfma_f32_16x16x32_bf16 v[64:67], v[196:199], v[228:231], v[64:67]
	s_setprio 0
	s_barrier
	s_add_i32 s71, s64, s53
	v_lshl_add_u64 v[152:153], s[48:49], 0, v[130:131]
	s_mov_b32 m0, s71
	ds_read_b128 v[200:203], v150 offset:16384
	ds_read_b128 v[204:207], v150 offset:17408
	ds_read_b128 v[208:211], v150 offset:18432
	ds_read_b128 v[212:215], v150 offset:19456
	ds_read_b128 v[216:219], v150 offset:20480
	ds_read_b128 v[220:223], v150 offset:21504
	ds_read_b128 v[224:227], v150 offset:22528
	ds_read_b128 v[228:231], v150 offset:23552
	global_load_lds_dwordx4 v[152:153], off
	s_add_i32 m0, s71, 0x2000
	s_add_u32 s72, s48, 0x80000
	v_lshl_add_u64 v[192:193], s[48:49], 0, v[134:135]
	s_addc_u32 s73, s49, 0
	s_add_i32 s71, s65, s53
	global_load_lds_dwordx4 v[192:193], off
	s_mov_b32 m0, s71
	v_lshl_add_u64 v[234:235], s[50:51], 0, v[132:133]
	global_load_lds_dwordx4 v130, s[72:73]
	s_add_i32 m0, s71, 0x2000
	s_nop 0
	global_load_lds_dwordx4 v134, s[72:73]
	v_lshl_add_u64 v[232:233], s[50:51], 0, v[128:129]
	s_mov_b32 m0, s56
	s_nop 0
	global_load_lds_dwordx4 v[232:233], off
	s_mov_b32 m0, s57
	s_nop 0
	global_load_lds_dwordx4 v[234:235], off
	s_waitcnt vmcnt(8)
	s_waitcnt lgkmcnt(0)
	s_barrier
	s_setprio 1
	s_waitcnt lgkmcnt(0)
	v_mfma_f32_16x16x32_bf16 v[60:63], v[164:167], v[200:203], v[60:63]
	v_mfma_f32_16x16x32_bf16 v[56:59], v[172:175], v[200:203], v[56:59]
	v_mfma_f32_16x16x32_bf16 v[44:47], v[164:167], v[208:211], v[44:47]
	v_mfma_f32_16x16x32_bf16 v[40:43], v[172:175], v[208:211], v[40:43]
	v_mfma_f32_16x16x32_bf16 v[28:31], v[164:167], v[216:219], v[28:31]
	v_mfma_f32_16x16x32_bf16 v[24:27], v[172:175], v[216:219], v[24:27]
	v_mfma_f32_16x16x32_bf16 v[12:15], v[164:167], v[224:227], v[12:15]
	v_mfma_f32_16x16x32_bf16 v[8:11], v[172:175], v[224:227], v[8:11]
	v_mfma_f32_16x16x32_bf16 v[60:63], v[168:171], v[204:207], v[60:63]
	v_mfma_f32_16x16x32_bf16 v[56:59], v[176:179], v[204:207], v[56:59]
	v_mfma_f32_16x16x32_bf16 v[44:47], v[168:171], v[212:215], v[44:47]
	v_mfma_f32_16x16x32_bf16 v[40:43], v[176:179], v[212:215], v[40:43]
	v_mfma_f32_16x16x32_bf16 v[28:31], v[168:171], v[220:223], v[28:31]
	v_mfma_f32_16x16x32_bf16 v[24:27], v[176:179], v[220:223], v[24:27]
	v_mfma_f32_16x16x32_bf16 v[12:15], v[168:171], v[228:231], v[12:15]
	v_mfma_f32_16x16x32_bf16 v[8:11], v[176:179], v[228:231], v[8:11]
	s_setprio 0
	s_setprio 1
	v_mfma_f32_16x16x32_bf16 v[52:55], v[180:183], v[200:203], v[52:55]
	v_mfma_f32_16x16x32_bf16 v[48:51], v[188:191], v[200:203], v[48:51]
	v_mfma_f32_16x16x32_bf16 v[36:39], v[180:183], v[208:211], v[36:39]
	v_mfma_f32_16x16x32_bf16 v[32:35], v[188:191], v[208:211], v[32:35]
	v_mfma_f32_16x16x32_bf16 v[20:23], v[180:183], v[216:219], v[20:23]
	v_mfma_f32_16x16x32_bf16 v[16:19], v[188:191], v[216:219], v[16:19]
	v_mfma_f32_16x16x32_bf16 v[4:7], v[180:183], v[224:227], v[4:7]
	v_mfma_f32_16x16x32_bf16 v[0:3], v[188:191], v[224:227], v[0:3]
	v_mfma_f32_16x16x32_bf16 v[52:55], v[184:187], v[204:207], v[52:55]
	v_mfma_f32_16x16x32_bf16 v[48:51], v[196:199], v[204:207], v[48:51]
	v_mfma_f32_16x16x32_bf16 v[36:39], v[184:187], v[212:215], v[36:39]
	v_mfma_f32_16x16x32_bf16 v[32:35], v[196:199], v[212:215], v[32:35]
	v_mfma_f32_16x16x32_bf16 v[20:23], v[184:187], v[220:223], v[20:23]
	v_mfma_f32_16x16x32_bf16 v[16:19], v[196:199], v[220:223], v[16:19]
	v_mfma_f32_16x16x32_bf16 v[4:7], v[184:187], v[228:231], v[4:7]
	v_mfma_f32_16x16x32_bf16 v[0:3], v[196:199], v[228:231], v[0:3]
	s_setprio 0
	s_barrier
	s_add_i32 s71, 0, 0x18000
	v_add_u32_e32 v151, s71, v146
	s_add_i32 s72, 0, 0x1c000
	ds_read_b128 v[164:167], v151
	ds_read_b128 v[168:171], v151 offset:1024
	ds_read_b128 v[172:175], v151 offset:2048
	ds_read_b128 v[176:179], v151 offset:3072
	v_add_u32_e32 v151, s72, v146
	ds_read_b128 v[180:183], v151
	ds_read_b128 v[184:187], v151 offset:1024
	ds_read_b128 v[188:191], v151 offset:2048
	ds_read_b128 v[196:199], v151 offset:3072
	s_add_u32 s50, s50, 0x80000
	s_addc_u32 s51, s51, 0
	s_mov_b32 m0, s58
	ds_read_b128 v[200:203], v150 offset:32768
	ds_read_b128 v[204:207], v150 offset:33792
	ds_read_b128 v[208:211], v150 offset:34816
	ds_read_b128 v[212:215], v150 offset:35840
	ds_read_b128 v[216:219], v150 offset:36864
	ds_read_b128 v[220:223], v150 offset:37888
	ds_read_b128 v[224:227], v150 offset:38912
	ds_read_b128 v[228:231], v150 offset:39936
	global_load_lds_dwordx4 v128, s[50:51]
	v_lshl_add_u64 v[236:237], s[50:51], 0, v[132:133]
	s_mov_b32 m0, s59
	s_nop 0
	global_load_lds_dwordx4 v[236:237], off
	s_waitcnt vmcnt(8)
	s_waitcnt lgkmcnt(0)
	s_barrier
	s_setprio 1
	s_waitcnt lgkmcnt(0)
	v_mfma_f32_16x16x32_bf16 v[124:127], v[164:167], v[200:203], v[124:127]
	v_mfma_f32_16x16x32_bf16 v[120:123], v[172:175], v[200:203], v[120:123]
	v_mfma_f32_16x16x32_bf16 v[108:111], v[164:167], v[208:211], v[108:111]
	v_mfma_f32_16x16x32_bf16 v[104:107], v[172:175], v[208:211], v[104:107]
	v_mfma_f32_16x16x32_bf16 v[92:95], v[164:167], v[216:219], v[92:95]
	v_mfma_f32_16x16x32_bf16 v[88:91], v[172:175], v[216:219], v[88:91]
	v_mfma_f32_16x16x32_bf16 v[76:79], v[164:167], v[224:227], v[76:79]
	v_mfma_f32_16x16x32_bf16 v[72:75], v[172:175], v[224:227], v[72:75]
	v_mfma_f32_16x16x32_bf16 v[124:127], v[168:171], v[204:207], v[124:127]
	v_mfma_f32_16x16x32_bf16 v[120:123], v[176:179], v[204:207], v[120:123]
	v_mfma_f32_16x16x32_bf16 v[108:111], v[168:171], v[212:215], v[108:111]
	v_mfma_f32_16x16x32_bf16 v[104:107], v[176:179], v[212:215], v[104:107]
	v_mfma_f32_16x16x32_bf16 v[92:95], v[168:171], v[220:223], v[92:95]
	v_mfma_f32_16x16x32_bf16 v[88:91], v[176:179], v[220:223], v[88:91]
	v_mfma_f32_16x16x32_bf16 v[76:79], v[168:171], v[228:231], v[76:79]
	v_mfma_f32_16x16x32_bf16 v[72:75], v[176:179], v[228:231], v[72:75]
	s_setprio 0
	s_setprio 1
	v_mfma_f32_16x16x32_bf16 v[116:119], v[180:183], v[200:203], v[116:119]
	v_mfma_f32_16x16x32_bf16 v[112:115], v[188:191], v[200:203], v[112:115]
	v_mfma_f32_16x16x32_bf16 v[100:103], v[180:183], v[208:211], v[100:103]
	v_mfma_f32_16x16x32_bf16 v[96:99], v[188:191], v[208:211], v[96:99]
	v_mfma_f32_16x16x32_bf16 v[84:87], v[180:183], v[216:219], v[84:87]
	v_mfma_f32_16x16x32_bf16 v[80:83], v[188:191], v[216:219], v[80:83]
	v_mfma_f32_16x16x32_bf16 v[68:71], v[180:183], v[224:227], v[68:71]
	v_mfma_f32_16x16x32_bf16 v[64:67], v[188:191], v[224:227], v[64:67]
	v_mfma_f32_16x16x32_bf16 v[116:119], v[184:187], v[204:207], v[116:119]
	v_mfma_f32_16x16x32_bf16 v[112:115], v[196:199], v[204:207], v[112:115]
	v_mfma_f32_16x16x32_bf16 v[100:103], v[184:187], v[212:215], v[100:103]
	v_mfma_f32_16x16x32_bf16 v[96:99], v[196:199], v[212:215], v[96:99]
	v_mfma_f32_16x16x32_bf16 v[84:87], v[184:187], v[220:223], v[84:87]
	v_mfma_f32_16x16x32_bf16 v[80:83], v[196:199], v[220:223], v[80:83]
	v_mfma_f32_16x16x32_bf16 v[68:71], v[184:187], v[228:231], v[68:71]
	v_mfma_f32_16x16x32_bf16 v[64:67], v[196:199], v[228:231], v[64:67]
	s_setprio 0
	s_barrier
	s_add_i32 s50, s71, s53
	v_lshl_add_u64 v[152:153], v[152:153], 0, s[10:11]
	s_mov_b32 m0, s50
	ds_read_b128 v[200:203], v150 offset:49152
	ds_read_b128 v[204:207], v150 offset:50176
	ds_read_b128 v[208:211], v150 offset:51200
	ds_read_b128 v[212:215], v150 offset:52224
	ds_read_b128 v[216:219], v150 offset:53248
	ds_read_b128 v[220:223], v150 offset:54272
	ds_read_b128 v[224:227], v150 offset:55296
	ds_read_b128 v[228:231], v150 offset:56320
	global_load_lds_dwordx4 v[152:153], off
	s_add_i32 m0, s50, 0x2000
	s_add_u32 s48, s48, 0x80080
	v_lshl_add_u64 v[152:153], v[192:193], 0, s[10:11]
	s_addc_u32 s49, s49, 0
	s_add_i32 s50, s72, s53
	global_load_lds_dwordx4 v[152:153], off
	s_mov_b32 m0, s50
	s_nop 0
	global_load_lds_dwordx4 v130, s[48:49]
	s_add_i32 m0, s50, 0x2000
	s_nop 0
	global_load_lds_dwordx4 v134, s[48:49]
	v_lshl_add_u64 v[152:153], v[232:233], 0, s[10:11]
	s_mov_b32 m0, s62
	s_nop 0
	global_load_lds_dwordx4 v[152:153], off
	v_lshl_add_u64 v[152:153], v[234:235], 0, s[10:11]
	s_mov_b32 m0, s63
	s_nop 0
	global_load_lds_dwordx4 v[152:153], off
	s_waitcnt vmcnt(8)
	s_waitcnt lgkmcnt(0)
	s_barrier
	s_setprio 1
	s_waitcnt lgkmcnt(0)
	v_mfma_f32_16x16x32_bf16 v[60:63], v[164:167], v[200:203], v[60:63]
	v_mfma_f32_16x16x32_bf16 v[56:59], v[172:175], v[200:203], v[56:59]
	v_mfma_f32_16x16x32_bf16 v[44:47], v[164:167], v[208:211], v[44:47]
	v_mfma_f32_16x16x32_bf16 v[40:43], v[172:175], v[208:211], v[40:43]
	v_mfma_f32_16x16x32_bf16 v[28:31], v[164:167], v[216:219], v[28:31]
	v_mfma_f32_16x16x32_bf16 v[24:27], v[172:175], v[216:219], v[24:27]
	v_mfma_f32_16x16x32_bf16 v[12:15], v[164:167], v[224:227], v[12:15]
	v_mfma_f32_16x16x32_bf16 v[8:11], v[172:175], v[224:227], v[8:11]
	v_mfma_f32_16x16x32_bf16 v[60:63], v[168:171], v[204:207], v[60:63]
	v_mfma_f32_16x16x32_bf16 v[56:59], v[176:179], v[204:207], v[56:59]
	v_mfma_f32_16x16x32_bf16 v[44:47], v[168:171], v[212:215], v[44:47]
	v_mfma_f32_16x16x32_bf16 v[40:43], v[176:179], v[212:215], v[40:43]
	v_mfma_f32_16x16x32_bf16 v[28:31], v[168:171], v[220:223], v[28:31]
	v_mfma_f32_16x16x32_bf16 v[24:27], v[176:179], v[220:223], v[24:27]
	v_mfma_f32_16x16x32_bf16 v[12:15], v[168:171], v[228:231], v[12:15]
	v_mfma_f32_16x16x32_bf16 v[8:11], v[176:179], v[228:231], v[8:11]
	s_setprio 0
	s_setprio 1
	v_mfma_f32_16x16x32_bf16 v[52:55], v[180:183], v[200:203], v[52:55]
	v_mfma_f32_16x16x32_bf16 v[48:51], v[188:191], v[200:203], v[48:51]
	v_mfma_f32_16x16x32_bf16 v[36:39], v[180:183], v[208:211], v[36:39]
	v_mfma_f32_16x16x32_bf16 v[32:35], v[188:191], v[208:211], v[32:35]
	v_mfma_f32_16x16x32_bf16 v[20:23], v[180:183], v[216:219], v[20:23]
	v_mfma_f32_16x16x32_bf16 v[16:19], v[188:191], v[216:219], v[16:19]
	v_mfma_f32_16x16x32_bf16 v[4:7], v[180:183], v[224:227], v[4:7]
	v_mfma_f32_16x16x32_bf16 v[0:3], v[188:191], v[224:227], v[0:3]
	v_mfma_f32_16x16x32_bf16 v[52:55], v[184:187], v[204:207], v[52:55]
	v_mfma_f32_16x16x32_bf16 v[48:51], v[196:199], v[204:207], v[48:51]
	v_mfma_f32_16x16x32_bf16 v[36:39], v[184:187], v[212:215], v[36:39]
	v_mfma_f32_16x16x32_bf16 v[32:35], v[196:199], v[212:215], v[32:35]
	v_mfma_f32_16x16x32_bf16 v[20:23], v[184:187], v[220:223], v[20:23]
	v_mfma_f32_16x16x32_bf16 v[16:19], v[196:199], v[220:223], v[16:19]
	v_mfma_f32_16x16x32_bf16 v[4:7], v[184:187], v[228:231], v[4:7]
	v_mfma_f32_16x16x32_bf16 v[0:3], v[196:199], v[228:231], v[0:3]
	s_setprio 0
	s_barrier
	s_add_i32 s70, s70, 2
	s_add_u32 s20, s20, 0x100
	s_addc_u32 s21, s21, 0
	s_add_u32 s68, s68, 0x100
	s_addc_u32 s69, s69, 0
	s_cmp_gt_u32 s70, 29
	s_cbranch_scc0 .LBB0_1860
	s_and_b64 vcc, exec, s[12:13]
	s_cbranch_vccz .LBB0_1863
	s_barrier

.LBB0_1925:
	s_lshl_b32 s6, s6, 5
	s_and_b32 s14, s6, 0x60
	s_mov_b64 s[6:7], 0x80
	s_add_i32 m0, s58, 0x18000
	v_lshl_add_u64 v[6:7], v[6:7], 0, s[6:7]
	s_lshl_b32 s11, s10, 13
	s_waitcnt vmcnt(2)
	s_barrier
	global_load_lds_dwordx4 v[6:7], off
	v_lshl_add_u64 v[4:5], v[4:5], 0, s[6:7]
	s_add_i32 m0, s58, 0x1a000
	s_add_i32 s62, s58, 0x8000
	s_add_i32 s63, s58, 0xa000
	global_load_lds_dwordx4 v[4:5], off
	v_lshl_add_u64 v[0:1], v[0:1], 0, s[6:7]
	s_mov_b32 m0, s62
	s_add_u32 s12, s48, 0x200080
	global_load_lds_dwordx4 v[0:1], off
	v_lshl_add_u64 v[0:1], v[2:3], 0, s[6:7]
	s_mov_b32 m0, s63
	s_addc_u32 s13, s49, 0
	global_load_lds_dwordx4 v[0:1], off
	s_add_i32 m0, s58, 0x1c000
	s_nop 0
	global_load_lds_dwordx4 v130, s[12:13]
	s_add_i32 m0, s58, 0x1e000
	v_lshlrev_b32_e32 v2, 2, v156
	global_load_lds_dwordx4 v134, s[12:13]
	v_lshl_or_b32 v1, v156, 6, v150
	v_and_b32_e32 v2, 32, v2
	v_lshl_or_b32 v0, s10, 6, v156
	v_bitop3_b32 v2, v1, s11, v2 bitop3:0xde
	v_mov_b32_e32 v1, v131
	v_lshlrev_b64 v[0:1], 13, v[0:1]
	v_lshl_add_u64 v[136:137], s[26:27], 0, v[0:1]
	v_lshlrev_b32_e32 v0, 11, v194
	v_and_b32_e32 v0, 0x1c0000, v0
	v_lshlrev_b32_e32 v1, 14, v155
	v_or3_b32 v0, v148, v0, v1
	v_add_u32_e32 v138, v0, v154
	v_lshlrev_b32_e32 v0, 7, v149
	s_waitcnt vmcnt(6)
	s_cmpk_lt_u32 s9, 0x100
	v_and_b32_e32 v0, 0x3c0000, v0
	s_sext_i32_i8 s74, s8
	v_lshl_or_b32 v152, s14, 7, v147
	s_cselect_b64 s[8:9], -1, 0
	v_or3_b32 v0, v148, v0, v1
	s_add_i32 s65, 0, 0x10000
	s_add_i32 s66, 0, 0x14000
	s_mov_b32 s64, 0
	v_or_b32_e32 v153, s14, v146
	v_mov_b32_e32 v139, v131
	v_add_u32_e32 v140, v0, v154
	v_mov_b32_e32 v141, v131
	v_add_u32_e32 v157, s65, v152
	v_add_u32_e32 v158, s66, v152
	v_add_u32_e32 v159, 0, v2
	s_mov_b64 s[10:11], 0x20000
	s_mov_b32 s67, 0x20000
	s_mov_b64 s[12:13], 0x40000
	s_mov_b32 s68, 0x40000
	s_mov_b64 s[14:15], 0x60000
	s_mov_b32 s69, 0x60000
	s_mov_b64 s[16:17], 0x100000
	s_mov_b32 s70, 0x100000
	s_mov_b64 s[18:19], 0x120000
	s_mov_b32 s71, 0x120000
	s_mov_b64 s[24:25], 0x140000
	s_mov_b32 s72, 0x140000
	s_mov_b64 s[34:35], 0x160000
	s_mov_b32 s73, 0x160000
	v_mov_b64_e32 v[142:143], 0x20f
	s_barrier
	s_branch .LBB0_1928

.LBB0_1932:
	ds_read_b128 v[160:163], v157
	ds_read_b128 v[164:167], v157 offset:1024
	ds_read_b128 v[168:171], v157 offset:2048
	ds_read_b128 v[172:175], v157 offset:3072
	ds_read_b128 v[176:179], v158
	ds_read_b128 v[180:183], v158 offset:1024
	ds_read_b128 v[184:187], v158 offset:2048
	ds_read_b128 v[188:191], v158 offset:3072
	s_add_u32 s48, s20, 0xffe00080
	s_addc_u32 s49, s21, -1
	s_cmpk_eq_i32 s78, 0x7c
	s_cselect_b32 s51, s39, s49
	s_cselect_b32 s50, s47, s48
	s_cselect_b32 s49, s37, s77
	s_cselect_b32 s48, s75, s76
	s_add_i32 m0, s58, 0xc000
	ds_read_b128 v[196:199], v159
	ds_read_b128 v[200:203], v159 offset:1024
	ds_read_b128 v[204:207], v159 offset:2048
	ds_read_b128 v[208:211], v159 offset:3072
	ds_read_b128 v[212:215], v159 offset:4096
	ds_read_b128 v[216:219], v159 offset:5120
	ds_read_b128 v[220:223], v159 offset:6144
	ds_read_b128 v[224:227], v159 offset:7168
	global_load_lds_dwordx4 v138, s[20:21]
	s_add_i32 m0, s58, 0xe000
	s_nop 0
	global_load_lds_dwordx4 v140, s[20:21]
	s_waitcnt vmcnt(8)
	s_waitcnt lgkmcnt(0)
	s_barrier
	s_setprio 1
	s_waitcnt lgkmcnt(0)
	v_mfma_f32_16x16x32_bf16 v[124:127], v[160:163], v[196:199], v[124:127]
	v_mfma_f32_16x16x32_bf16 v[120:123], v[168:171], v[196:199], v[120:123]
	v_mfma_f32_16x16x32_bf16 v[108:111], v[160:163], v[204:207], v[108:111]
	v_mfma_f32_16x16x32_bf16 v[104:107], v[168:171], v[204:207], v[104:107]
	v_mfma_f32_16x16x32_bf16 v[92:95], v[160:163], v[212:215], v[92:95]
	v_mfma_f32_16x16x32_bf16 v[88:91], v[168:171], v[212:215], v[88:91]
	v_mfma_f32_16x16x32_bf16 v[76:79], v[160:163], v[220:223], v[76:79]
	v_mfma_f32_16x16x32_bf16 v[72:75], v[168:171], v[220:223], v[72:75]
	v_mfma_f32_16x16x32_bf16 v[124:127], v[164:167], v[200:203], v[124:127]
	v_mfma_f32_16x16x32_bf16 v[120:123], v[172:175], v[200:203], v[120:123]
	v_mfma_f32_16x16x32_bf16 v[108:111], v[164:167], v[208:211], v[108:111]
	v_mfma_f32_16x16x32_bf16 v[104:107], v[172:175], v[208:211], v[104:107]
	v_mfma_f32_16x16x32_bf16 v[92:95], v[164:167], v[216:219], v[92:95]
	v_mfma_f32_16x16x32_bf16 v[88:91], v[172:175], v[216:219], v[88:91]
	v_mfma_f32_16x16x32_bf16 v[76:79], v[164:167], v[224:227], v[76:79]
	v_mfma_f32_16x16x32_bf16 v[72:75], v[172:175], v[224:227], v[72:75]
	s_setprio 0
	s_setprio 1
	v_mfma_f32_16x16x32_bf16 v[116:119], v[176:179], v[196:199], v[116:119]
	v_mfma_f32_16x16x32_bf16 v[112:115], v[184:187], v[196:199], v[112:115]
	v_mfma_f32_16x16x32_bf16 v[100:103], v[176:179], v[204:207], v[100:103]
	v_mfma_f32_16x16x32_bf16 v[96:99], v[184:187], v[204:207], v[96:99]
	v_mfma_f32_16x16x32_bf16 v[84:87], v[176:179], v[212:215], v[84:87]
	v_mfma_f32_16x16x32_bf16 v[80:83], v[184:187], v[212:215], v[80:83]
	v_mfma_f32_16x16x32_bf16 v[68:71], v[176:179], v[220:223], v[68:71]
	v_mfma_f32_16x16x32_bf16 v[64:67], v[184:187], v[220:223], v[64:67]
	v_mfma_f32_16x16x32_bf16 v[116:119], v[180:183], v[200:203], v[116:119]
	v_mfma_f32_16x16x32_bf16 v[112:115], v[188:191], v[200:203], v[112:115]
	v_mfma_f32_16x16x32_bf16 v[100:103], v[180:183], v[208:211], v[100:103]
	v_mfma_f32_16x16x32_bf16 v[96:99], v[188:191], v[208:211], v[96:99]
	v_mfma_f32_16x16x32_bf16 v[84:87], v[180:183], v[216:219], v[84:87]
	v_mfma_f32_16x16x32_bf16 v[80:83], v[188:191], v[216:219], v[80:83]
	v_mfma_f32_16x16x32_bf16 v[68:71], v[180:183], v[224:227], v[68:71]
	v_mfma_f32_16x16x32_bf16 v[64:67], v[188:191], v[224:227], v[64:67]
	s_setprio 0
	s_barrier
	s_add_i32 s79, s65, s55
	v_lshl_add_u64 v[144:145], s[48:49], 0, v[130:131]
	s_mov_b32 m0, s79
	ds_read_b128 v[196:199], v159 offset:16384
	ds_read_b128 v[200:203], v159 offset:17408
	ds_read_b128 v[204:207], v159 offset:18432
	ds_read_b128 v[208:211], v159 offset:19456
	ds_read_b128 v[212:215], v159 offset:20480
	ds_read_b128 v[216:219], v159 offset:21504
	ds_read_b128 v[220:223], v159 offset:22528
	ds_read_b128 v[224:227], v159 offset:23552
	global_load_lds_dwordx4 v[144:145], off
	s_add_i32 m0, s79, 0x2000
	s_add_u32 s80, s48, 0x200000
	v_lshl_add_u64 v[192:193], s[48:49], 0, v[134:135]
	s_addc_u32 s81, s49, 0
	s_add_i32 s79, s66, s55
	global_load_lds_dwordx4 v[192:193], off
	s_mov_b32 m0, s79
	v_lshl_add_u64 v[230:231], s[50:51], 0, v[132:133]
	global_load_lds_dwordx4 v130, s[80:81]
	s_add_i32 m0, s79, 0x2000
	s_nop 0
	global_load_lds_dwordx4 v134, s[80:81]
	v_lshl_add_u64 v[228:229], s[50:51], 0, v[128:129]
	s_mov_b32 m0, s58
	s_nop 0
	global_load_lds_dwordx4 v[228:229], off
	s_mov_b32 m0, s59
	s_nop 0
	global_load_lds_dwordx4 v[230:231], off
	s_waitcnt vmcnt(8)
	s_waitcnt lgkmcnt(0)
	s_barrier
	s_setprio 1
	s_waitcnt lgkmcnt(0)
	v_mfma_f32_16x16x32_bf16 v[60:63], v[160:163], v[196:199], v[60:63]
	v_mfma_f32_16x16x32_bf16 v[56:59], v[168:171], v[196:199], v[56:59]
	v_mfma_f32_16x16x32_bf16 v[44:47], v[160:163], v[204:207], v[44:47]
	v_mfma_f32_16x16x32_bf16 v[40:43], v[168:171], v[204:207], v[40:43]
	v_mfma_f32_16x16x32_bf16 v[28:31], v[160:163], v[212:215], v[28:31]
	v_mfma_f32_16x16x32_bf16 v[24:27], v[168:171], v[212:215], v[24:27]
	v_mfma_f32_16x16x32_bf16 v[12:15], v[160:163], v[220:223], v[12:15]
	v_mfma_f32_16x16x32_bf16 v[8:11], v[168:171], v[220:223], v[8:11]
	v_mfma_f32_16x16x32_bf16 v[60:63], v[164:167], v[200:203], v[60:63]
	v_mfma_f32_16x16x32_bf16 v[56:59], v[172:175], v[200:203], v[56:59]
	v_mfma_f32_16x16x32_bf16 v[44:47], v[164:167], v[208:211], v[44:47]
	v_mfma_f32_16x16x32_bf16 v[40:43], v[172:175], v[208:211], v[40:43]
	v_mfma_f32_16x16x32_bf16 v[28:31], v[164:167], v[216:219], v[28:31]
	v_mfma_f32_16x16x32_bf16 v[24:27], v[172:175], v[216:219], v[24:27]
	v_mfma_f32_16x16x32_bf16 v[12:15], v[164:167], v[224:227], v[12:15]
	v_mfma_f32_16x16x32_bf16 v[8:11], v[172:175], v[224:227], v[8:11]
	s_setprio 0
	s_setprio 1
	v_mfma_f32_16x16x32_bf16 v[52:55], v[176:179], v[196:199], v[52:55]
	v_mfma_f32_16x16x32_bf16 v[48:51], v[184:187], v[196:199], v[48:51]
	v_mfma_f32_16x16x32_bf16 v[36:39], v[176:179], v[204:207], v[36:39]
	v_mfma_f32_16x16x32_bf16 v[32:35], v[184:187], v[204:207], v[32:35]
	v_mfma_f32_16x16x32_bf16 v[20:23], v[176:179], v[212:215], v[20:23]
	v_mfma_f32_16x16x32_bf16 v[16:19], v[184:187], v[212:215], v[16:19]
	v_mfma_f32_16x16x32_bf16 v[4:7], v[176:179], v[220:223], v[4:7]
	v_mfma_f32_16x16x32_bf16 v[0:3], v[184:187], v[220:223], v[0:3]
	v_mfma_f32_16x16x32_bf16 v[52:55], v[180:183], v[200:203], v[52:55]
	v_mfma_f32_16x16x32_bf16 v[48:51], v[188:191], v[200:203], v[48:51]
	v_mfma_f32_16x16x32_bf16 v[36:39], v[180:183], v[208:211], v[36:39]
	v_mfma_f32_16x16x32_bf16 v[32:35], v[188:191], v[208:211], v[32:35]
	v_mfma_f32_16x16x32_bf16 v[20:23], v[180:183], v[216:219], v[20:23]
	v_mfma_f32_16x16x32_bf16 v[16:19], v[188:191], v[216:219], v[16:19]
	v_mfma_f32_16x16x32_bf16 v[4:7], v[180:183], v[224:227], v[4:7]
	v_mfma_f32_16x16x32_bf16 v[0:3], v[188:191], v[224:227], v[0:3]
	s_setprio 0
	s_barrier
	s_add_i32 s79, 0, 0x18000
	s_add_i32 s80, 0, 0x1c000
	v_add_u32_e32 v172, s79, v152
	v_add_u32_e32 v188, s80, v152
	ds_read_b128 v[160:163], v172
	ds_read_b128 v[164:167], v172 offset:1024
	ds_read_b128 v[168:171], v172 offset:2048
	ds_read_b128 v[172:175], v172 offset:3072
	ds_read_b128 v[176:179], v188
	ds_read_b128 v[180:183], v188 offset:1024
	ds_read_b128 v[184:187], v188 offset:2048
	ds_read_b128 v[188:191], v188 offset:3072
	s_add_u32 s50, s50, 0x200000
	s_addc_u32 s51, s51, 0
	s_mov_b32 m0, s60
	ds_read_b128 v[196:199], v159 offset:32768
	ds_read_b128 v[200:203], v159 offset:33792
	ds_read_b128 v[204:207], v159 offset:34816
	ds_read_b128 v[208:211], v159 offset:35840
	ds_read_b128 v[212:215], v159 offset:36864
	ds_read_b128 v[216:219], v159 offset:37888
	ds_read_b128 v[220:223], v159 offset:38912
	ds_read_b128 v[224:227], v159 offset:39936
	global_load_lds_dwordx4 v128, s[50:51]
	v_lshl_add_u64 v[232:233], s[50:51], 0, v[132:133]
	s_mov_b32 m0, s61
	s_nop 0
	global_load_lds_dwordx4 v[232:233], off
	s_waitcnt vmcnt(8)
	s_waitcnt lgkmcnt(0)
	s_barrier
	s_setprio 1
	s_waitcnt lgkmcnt(0)
	v_mfma_f32_16x16x32_bf16 v[124:127], v[160:163], v[196:199], v[124:127]
	v_mfma_f32_16x16x32_bf16 v[120:123], v[168:171], v[196:199], v[120:123]
	v_mfma_f32_16x16x32_bf16 v[108:111], v[160:163], v[204:207], v[108:111]
	v_mfma_f32_16x16x32_bf16 v[104:107], v[168:171], v[204:207], v[104:107]
	v_mfma_f32_16x16x32_bf16 v[92:95], v[160:163], v[212:215], v[92:95]
	v_mfma_f32_16x16x32_bf16 v[88:91], v[168:171], v[212:215], v[88:91]
	v_mfma_f32_16x16x32_bf16 v[76:79], v[160:163], v[220:223], v[76:79]
	v_mfma_f32_16x16x32_bf16 v[72:75], v[168:171], v[220:223], v[72:75]
	v_mfma_f32_16x16x32_bf16 v[124:127], v[164:167], v[200:203], v[124:127]
	v_mfma_f32_16x16x32_bf16 v[120:123], v[172:175], v[200:203], v[120:123]
	v_mfma_f32_16x16x32_bf16 v[108:111], v[164:167], v[208:211], v[108:111]
	v_mfma_f32_16x16x32_bf16 v[104:107], v[172:175], v[208:211], v[104:107]
	v_mfma_f32_16x16x32_bf16 v[92:95], v[164:167], v[216:219], v[92:95]
	v_mfma_f32_16x16x32_bf16 v[88:91], v[172:175], v[216:219], v[88:91]
	v_mfma_f32_16x16x32_bf16 v[76:79], v[164:167], v[224:227], v[76:79]
	v_mfma_f32_16x16x32_bf16 v[72:75], v[172:175], v[224:227], v[72:75]
	s_setprio 0
	s_setprio 1
	v_mfma_f32_16x16x32_bf16 v[116:119], v[176:179], v[196:199], v[116:119]
	v_mfma_f32_16x16x32_bf16 v[112:115], v[184:187], v[196:199], v[112:115]
	v_mfma_f32_16x16x32_bf16 v[100:103], v[176:179], v[204:207], v[100:103]
	v_mfma_f32_16x16x32_bf16 v[96:99], v[184:187], v[204:207], v[96:99]
	v_mfma_f32_16x16x32_bf16 v[84:87], v[176:179], v[212:215], v[84:87]
	v_mfma_f32_16x16x32_bf16 v[80:83], v[184:187], v[212:215], v[80:83]
	v_mfma_f32_16x16x32_bf16 v[68:71], v[176:179], v[220:223], v[68:71]
	v_mfma_f32_16x16x32_bf16 v[64:67], v[184:187], v[220:223], v[64:67]
	v_mfma_f32_16x16x32_bf16 v[116:119], v[180:183], v[200:203], v[116:119]
	v_mfma_f32_16x16x32_bf16 v[112:115], v[188:191], v[200:203], v[112:115]
	v_mfma_f32_16x16x32_bf16 v[100:103], v[180:183], v[208:211], v[100:103]
	v_mfma_f32_16x16x32_bf16 v[96:99], v[188:191], v[208:211], v[96:99]
	v_mfma_f32_16x16x32_bf16 v[84:87], v[180:183], v[216:219], v[84:87]
	v_mfma_f32_16x16x32_bf16 v[80:83], v[188:191], v[216:219], v[80:83]
	v_mfma_f32_16x16x32_bf16 v[68:71], v[180:183], v[224:227], v[68:71]
	v_mfma_f32_16x16x32_bf16 v[64:67], v[188:191], v[224:227], v[64:67]
	s_setprio 0
	s_barrier
	s_add_i32 s50, s79, s55
	v_lshl_add_u64 v[144:145], v[144:145], 0, s[6:7]
	s_mov_b32 m0, s50
	ds_read_b128 v[196:199], v159 offset:49152
	ds_read_b128 v[200:203], v159 offset:50176
	ds_read_b128 v[204:207], v159 offset:51200
	ds_read_b128 v[208:211], v159 offset:52224
	ds_read_b128 v[212:215], v159 offset:53248
	ds_read_b128 v[216:219], v159 offset:54272
	ds_read_b128 v[220:223], v159 offset:55296
	ds_read_b128 v[224:227], v159 offset:56320
	global_load_lds_dwordx4 v[144:145], off
	s_add_i32 m0, s50, 0x2000
	s_add_u32 s48, s48, 0x200080
	v_lshl_add_u64 v[144:145], v[192:193], 0, s[6:7]
	s_addc_u32 s49, s49, 0
	s_add_i32 s50, s80, s55
	global_load_lds_dwordx4 v[144:145], off
	s_mov_b32 m0, s50
	s_nop 0
	global_load_lds_dwordx4 v130, s[48:49]
	s_add_i32 m0, s50, 0x2000
	s_nop 0
	global_load_lds_dwordx4 v134, s[48:49]
	v_lshl_add_u64 v[144:145], v[228:229], 0, s[6:7]
	s_mov_b32 m0, s62
	s_nop 0
	global_load_lds_dwordx4 v[144:145], off
	v_lshl_add_u64 v[144:145], v[230:231], 0, s[6:7]
	s_mov_b32 m0, s63
	s_nop 0
	global_load_lds_dwordx4 v[144:145], off
	s_waitcnt vmcnt(8)
	s_waitcnt lgkmcnt(0)
	s_barrier
	s_setprio 1
	s_waitcnt lgkmcnt(0)
	v_mfma_f32_16x16x32_bf16 v[60:63], v[160:163], v[196:199], v[60:63]
	v_mfma_f32_16x16x32_bf16 v[56:59], v[168:171], v[196:199], v[56:59]
	v_mfma_f32_16x16x32_bf16 v[44:47], v[160:163], v[204:207], v[44:47]
	v_mfma_f32_16x16x32_bf16 v[40:43], v[168:171], v[204:207], v[40:43]
	v_mfma_f32_16x16x32_bf16 v[28:31], v[160:163], v[212:215], v[28:31]
	v_mfma_f32_16x16x32_bf16 v[24:27], v[168:171], v[212:215], v[24:27]
	v_mfma_f32_16x16x32_bf16 v[12:15], v[160:163], v[220:223], v[12:15]
	v_mfma_f32_16x16x32_bf16 v[8:11], v[168:171], v[220:223], v[8:11]
	v_mfma_f32_16x16x32_bf16 v[60:63], v[164:167], v[200:203], v[60:63]
	v_mfma_f32_16x16x32_bf16 v[56:59], v[172:175], v[200:203], v[56:59]
	v_mfma_f32_16x16x32_bf16 v[44:47], v[164:167], v[208:211], v[44:47]
	v_mfma_f32_16x16x32_bf16 v[40:43], v[172:175], v[208:211], v[40:43]
	v_mfma_f32_16x16x32_bf16 v[28:31], v[164:167], v[216:219], v[28:31]
	v_mfma_f32_16x16x32_bf16 v[24:27], v[172:175], v[216:219], v[24:27]
	v_mfma_f32_16x16x32_bf16 v[12:15], v[164:167], v[224:227], v[12:15]
	v_mfma_f32_16x16x32_bf16 v[8:11], v[172:175], v[224:227], v[8:11]
	s_setprio 0
	s_setprio 1
	v_mfma_f32_16x16x32_bf16 v[52:55], v[176:179], v[196:199], v[52:55]
	v_mfma_f32_16x16x32_bf16 v[48:51], v[184:187], v[196:199], v[48:51]
	v_mfma_f32_16x16x32_bf16 v[36:39], v[176:179], v[204:207], v[36:39]
	v_mfma_f32_16x16x32_bf16 v[32:35], v[184:187], v[204:207], v[32:35]
	v_mfma_f32_16x16x32_bf16 v[20:23], v[176:179], v[212:215], v[20:23]
	v_mfma_f32_16x16x32_bf16 v[16:19], v[184:187], v[212:215], v[16:19]
	v_mfma_f32_16x16x32_bf16 v[4:7], v[176:179], v[220:223], v[4:7]
	v_mfma_f32_16x16x32_bf16 v[0:3], v[184:187], v[220:223], v[0:3]
	v_mfma_f32_16x16x32_bf16 v[52:55], v[180:183], v[200:203], v[52:55]
	v_mfma_f32_16x16x32_bf16 v[48:51], v[188:191], v[200:203], v[48:51]
	v_mfma_f32_16x16x32_bf16 v[36:39], v[180:183], v[208:211], v[36:39]
	v_mfma_f32_16x16x32_bf16 v[32:35], v[188:191], v[208:211], v[32:35]
	v_mfma_f32_16x16x32_bf16 v[20:23], v[180:183], v[216:219], v[20:23]
	v_mfma_f32_16x16x32_bf16 v[16:19], v[188:191], v[216:219], v[16:19]
	v_mfma_f32_16x16x32_bf16 v[4:7], v[180:183], v[224:227], v[4:7]
	v_mfma_f32_16x16x32_bf16 v[0:3], v[188:191], v[224:227], v[0:3]
	s_setprio 0
	s_barrier
	s_add_i32 s78, s78, 2
	s_add_u32 s20, s20, 0x100
	s_addc_u32 s21, s21, 0
	s_add_u32 s76, s76, 0x100
	s_addc_u32 s77, s77, 0
	s_cmpk_gt_u32 s78, 0x7d
	s_cbranch_scc0 .LBB0_1932
	s_and_b64 vcc, exec, s[8:9]
	s_cbranch_vccz .LBB0_1935
	s_barrier

.LBB0_1943:
	s_abs_i32 s21, s18
	s_mul_hi_u32 s24, s21, s46
	s_mul_i32 s25, s24, s44
	s_ashr_i32 s19, s18, 31
	s_sub_i32 s21, s21, s25
	s_xor_b32 s20, s19, s45
	s_add_i32 s25, s24, 1
	s_sub_i32 s34, s21, s44
	s_cmp_ge_u32 s21, s44
	s_cselect_b32 s24, s25, s24
	s_cselect_b32 s21, s34, s21
	s_add_i32 s25, s24, 1
	s_cmp_ge_u32 s21, s44
	s_cselect_b32 s21, s25, s24
	s_xor_b32 s21, s21, s20
	s_sub_i32 s21, s21, s20
	s_mul_i32 s20, s21, s40
	s_sub_i32 s20, s18, s20
	s_add_i32 s20, s20, s54
	s_cmpk_gt_i32 s20, 0x20f
	v_readfirstlane_b32 s56, v194
	s_barrier
	s_cbranch_scc1 .LBB0_1942
	s_lshl_b32 s24, s21, 9
	s_lshr_b32 s61, s56, 6
	s_ashr_i32 s25, s24, 31
	s_lshr_b32 s55, s56, 8
	s_lshl_b32 s57, s61, 10
	s_lshl_b64 s[34:35], s[24:25], 1
	s_add_u32 s58, s33, s34
	s_addc_u32 s59, s52, s35
	s_add_u32 s60, s3, s34
	s_addc_u32 s64, s23, s35
	s_ashr_i32 s21, s20, 31
	s_lshr_b32 s21, s21, 29
	s_add_i32 s21, s20, s21
	s_ashr_i32 s24, s21, 3
	s_and_b32 s21, s21, -8
	s_sub_i32 s20, s20, s21
	s_cmp_lt_i32 s20, 0
	s_cselect_b32 s21, s49, 0x42
	s_mul_i32 s38, s20, s21
	s_add_i32 s38, s38, s24
	s_ashr_i32 s20, s38, 31
	s_lshr_b32 s20, s20, 26
	s_add_i32 s20, s38, s20
	s_ashr_i32 s65, s20, 6
	s_lshl_b32 s39, s65, 3
	s_sub_i32 s21, 0x42, s39
	s_min_u32 s24, s21, 8
	s_andn2_b32 s20, s20, 63
	s_sub_i32 s25, s38, s20
	v_cvt_f32_ubyte0_e32 v1, s24
	v_cvt_f32_i32_e32 v0, s25
	v_rcp_iflag_f32_e32 v2, v1
	s_ashr_i32 s20, s25, 30
	s_or_b32 s36, s20, 1
	v_mul_f32_e32 v2, v0, v2
	v_trunc_f32_e32 v2, v2
	v_fma_f32 v0, -v2, v1, v0
	v_cvt_i32_f32_e32 v2, v2
	v_cmp_ge_f32_e64 s[20:21], |v0|, v1
	s_and_b64 s[20:21], s[20:21], exec
	s_cselect_b32 s20, s36, 0
	v_readfirstlane_b32 s21, v2
	s_add_i32 s20, s21, s20
	s_mul_i32 s66, s20, s24
	s_sub_i32 s21, s25, s66
	s_sext_i32_i8 s21, s21
	s_add_i32 s24, s39, s21
	s_ashr_i32 s25, s24, 31
	s_bfe_i64 s[20:21], s[20:21], 0x80000
	s_lshl_b64 s[24:25], s[24:25], 22
	s_lshl_b64 s[36:37], s[20:21], 22
	s_add_u32 s20, s58, s36
	s_addc_u32 s21, s59, s37
	s_add_i32 s58, s57, 0
	s_add_i32 m0, s58, 0x10000
	v_lshl_add_u64 v[0:1], s[20:21], 0, v[130:131]
	global_load_lds_dwordx4 v[0:1], off
	s_add_i32 m0, s58, 0x12000
	s_add_u32 s62, s20, 0x200000
	v_lshl_add_u64 v[2:3], s[20:21], 0, v[134:135]
	s_addc_u32 s63, s21, 0
	global_load_lds_dwordx4 v[2:3], off
	s_add_i32 m0, s58, 0x14000
	s_nop 0
	global_load_lds_dwordx4 v130, s[62:63]
	s_add_i32 m0, s58, 0x16000
	s_add_u32 s24, s60, s24
	s_addc_u32 s25, s64, s25
	s_add_i32 s59, s58, 0x2000
	global_load_lds_dwordx4 v134, s[62:63]
	v_lshl_add_u64 v[6:7], s[24:25], 0, v[128:129]
	s_mov_b32 m0, s58
	s_add_u32 s62, s24, 0x200000
	global_load_lds_dwordx4 v[6:7], off
	v_lshl_add_u64 v[4:5], s[24:25], 0, v[132:133]
	s_mov_b32 m0, s59
	s_addc_u32 s63, s25, 0
	s_add_i32 s60, s58, 0x4000
	global_load_lds_dwordx4 v[4:5], off
	s_mov_b32 m0, s60
	s_nop 0
	global_load_lds_dwordx4 v128, s[62:63]
	v_lshl_add_u64 v[8:9], s[62:63], 0, v[132:133]
	s_add_i32 s62, s58, 0x6000
	s_mov_b32 m0, s62
	s_cmp_lg_u32 s55, 1
	global_load_lds_dwordx4 v[8:9], off
	s_cbranch_scc1 .LBB0_1946
	s_barrier
.LBB0_1946:
	s_lshl_b32 s61, s61, 5
	s_add_i32 m0, s58, 0x18000
	v_lshl_add_u64 v[0:1], v[0:1], 0, s[4:5]
	s_and_b32 s61, s61, 0x60
	s_waitcnt vmcnt(2)
	s_barrier
	global_load_lds_dwordx4 v[0:1], off
	v_lshl_add_u64 v[0:1], v[2:3], 0, s[4:5]
	s_add_i32 m0, s58, 0x1a000
	s_add_i32 s63, s58, 0x8000
	s_add_i32 s64, s58, 0xa000
	global_load_lds_dwordx4 v[0:1], off
	v_lshl_add_u64 v[0:1], v[6:7], 0, s[4:5]
	s_mov_b32 m0, s63
	s_add_u32 s68, s20, 0x200080
	global_load_lds_dwordx4 v[0:1], off
	v_lshl_add_u64 v[0:1], v[4:5], 0, s[4:5]
	s_mov_b32 m0, s64
	s_addc_u32 s69, s21, 0
	global_load_lds_dwordx4 v[0:1], off
	s_add_i32 m0, s58, 0x1c000
	s_nop 0
	global_load_lds_dwordx4 v130, s[68:69]
	s_add_i32 m0, s58, 0x1e000
	s_sub_i32 s38, s38, s66
	global_load_lds_dwordx4 v134, s[68:69]
	s_lshl_b32 s65, s65, 6
	s_sub_i32 s38, s38, s65
	s_sext_i32_i8 s38, s38
	s_add_i32 s38, s39, s38
	s_ashr_i32 s39, s38, 31
	s_lshl_b64 s[38:39], s[38:39], 22
	s_add_u32 s38, s38, s34
	s_addc_u32 s39, s39, s35
	s_add_u32 s65, s28, s38
	s_addc_u32 s66, s29, s39
	s_add_u32 s34, s36, s34
	s_waitcnt vmcnt(6)
	s_addc_u32 s35, s37, s35
	v_lshl_or_b32 v8, s55, 13, v150
	s_add_u32 s67, s47, s34
	v_mov_b32_e32 v0, 0
	v_lshl_or_b32 v136, s61, 7, v147
	v_lshl_add_u64 v[142:143], v[138:139], 0, s[38:39]
	v_lshl_add_u64 v[144:145], v[140:141], 0, s[38:39]
	s_addc_u32 s68, s48, s35
	s_mov_b32 s69, -2
	s_mov_b64 s[34:35], 0
	v_add_u32_e32 v148, 0, v8
	v_mov_b32_e32 v1, v0
	v_mov_b32_e32 v2, v0
	v_mov_b32_e32 v3, v0
	v_mov_b32_e32 v4, v0
	v_mov_b32_e32 v5, v0
	v_mov_b32_e32 v6, v0
	v_mov_b32_e32 v7, v0
	v_mov_b32_e32 v8, v0
	v_mov_b32_e32 v9, v0
	v_mov_b32_e32 v10, v0
	v_mov_b32_e32 v11, v0
	v_mov_b32_e32 v12, v0
	v_mov_b32_e32 v13, v0
	v_mov_b32_e32 v14, v0
	v_mov_b32_e32 v15, v0
	v_mov_b32_e32 v16, v0
	v_mov_b32_e32 v17, v0
	v_mov_b32_e32 v18, v0
	v_mov_b32_e32 v19, v0
	v_mov_b32_e32 v20, v0
	v_mov_b32_e32 v21, v0
	v_mov_b32_e32 v22, v0
	v_mov_b32_e32 v23, v0
	v_mov_b32_e32 v28, v0
	v_mov_b32_e32 v29, v0
	v_mov_b32_e32 v30, v0
	v_mov_b32_e32 v31, v0
	v_mov_b32_e32 v36, v0
	v_mov_b32_e32 v37, v0
	v_mov_b32_e32 v38, v0
	v_mov_b32_e32 v39, v0
	v_mov_b32_e32 v24, v0
	v_mov_b32_e32 v25, v0
	v_mov_b32_e32 v26, v0
	v_mov_b32_e32 v27, v0
	v_mov_b32_e32 v32, v0
	v_mov_b32_e32 v33, v0
	v_mov_b32_e32 v34, v0
	v_mov_b32_e32 v35, v0
	v_mov_b32_e32 v40, v0
	v_mov_b32_e32 v41, v0
	v_mov_b32_e32 v42, v0
	v_mov_b32_e32 v43, v0
	v_mov_b32_e32 v44, v0
	v_mov_b32_e32 v45, v0
	v_mov_b32_e32 v46, v0
	v_mov_b32_e32 v47, v0
	v_mov_b32_e32 v48, v0
	v_mov_b32_e32 v49, v0
	v_mov_b32_e32 v50, v0
	v_mov_b32_e32 v51, v0
	v_mov_b32_e32 v52, v0
	v_mov_b32_e32 v53, v0
	v_mov_b32_e32 v54, v0
	v_mov_b32_e32 v55, v0
	v_mov_b32_e32 v56, v0
	v_mov_b32_e32 v57, v0
	v_mov_b32_e32 v58, v0
	v_mov_b32_e32 v59, v0
	v_mov_b32_e32 v60, v0
	v_mov_b32_e32 v61, v0
	v_mov_b32_e32 v62, v0
	v_mov_b32_e32 v63, v0
	v_mov_b32_e32 v64, v0
	v_mov_b32_e32 v65, v0
	v_mov_b32_e32 v66, v0
	v_mov_b32_e32 v67, v0
	v_mov_b32_e32 v68, v0
	v_mov_b32_e32 v69, v0
	v_mov_b32_e32 v70, v0
	v_mov_b32_e32 v71, v0
	v_mov_b32_e32 v72, v0
	v_mov_b32_e32 v73, v0
	v_mov_b32_e32 v74, v0
	v_mov_b32_e32 v75, v0
	v_mov_b32_e32 v76, v0
	v_mov_b32_e32 v77, v0
	v_mov_b32_e32 v78, v0
	v_mov_b32_e32 v79, v0
	v_mov_b32_e32 v80, v0
	v_mov_b32_e32 v81, v0
	v_mov_b32_e32 v82, v0
	v_mov_b32_e32 v83, v0
	v_mov_b32_e32 v88, v0
	v_mov_b32_e32 v89, v0
	v_mov_b32_e32 v90, v0
	v_mov_b32_e32 v91, v0
	v_mov_b32_e32 v96, v0
	v_mov_b32_e32 v97, v0
	v_mov_b32_e32 v98, v0
	v_mov_b32_e32 v99, v0
	v_mov_b32_e32 v104, v0
	v_mov_b32_e32 v105, v0
	v_mov_b32_e32 v106, v0
	v_mov_b32_e32 v107, v0
	v_mov_b32_e32 v84, v0
	v_mov_b32_e32 v85, v0
	v_mov_b32_e32 v86, v0
	v_mov_b32_e32 v87, v0
	v_mov_b32_e32 v92, v0
	v_mov_b32_e32 v93, v0
	v_mov_b32_e32 v94, v0
	v_mov_b32_e32 v95, v0
	v_mov_b32_e32 v100, v0
	v_mov_b32_e32 v101, v0
	v_mov_b32_e32 v102, v0
	v_mov_b32_e32 v103, v0
	v_mov_b32_e32 v108, v0
	v_mov_b32_e32 v109, v0
	v_mov_b32_e32 v110, v0
	v_mov_b32_e32 v111, v0
	v_mov_b32_e32 v112, v0
	v_mov_b32_e32 v113, v0
	v_mov_b32_e32 v114, v0
	v_mov_b32_e32 v115, v0
	v_mov_b32_e32 v116, v0
	v_mov_b32_e32 v117, v0
	v_mov_b32_e32 v118, v0
	v_mov_b32_e32 v119, v0
	v_mov_b32_e32 v120, v0
	v_mov_b32_e32 v121, v0
	v_mov_b32_e32 v122, v0
	v_mov_b32_e32 v123, v0
	v_mov_b32_e32 v124, v0
	v_mov_b32_e32 v125, v0
	v_mov_b32_e32 v126, v0
	v_mov_b32_e32 v127, v0
	s_barrier
.LBB0_1947:
	s_add_u32 s36, s65, s34
	s_addc_u32 s37, s66, s35
	s_add_u32 s36, s36, 0xb900100
	s_addc_u32 s37, s37, 0
	s_add_u32 s70, s67, s34
	s_addc_u32 s71, s68, s35
	s_add_i32 s72, 0, 0x10000
	s_cmpk_eq_i32 s34, 0x300
	s_cselect_b32 s39, s25, s37
	s_cselect_b32 s38, s24, s36
	v_add_u32_e32 v149, s72, v136
	s_cselect_b32 s37, s21, s71
	s_cselect_b32 s36, s20, s70
	s_add_i32 s73, 0, 0x14000
	ds_read_b128 v[152:155], v149
	ds_read_b128 v[156:159], v149 offset:1024
	ds_read_b128 v[160:163], v149 offset:2048
	ds_read_b128 v[164:167], v149 offset:3072
	v_add_u32_e32 v149, s73, v136
	ds_read_b128 v[168:171], v149
	ds_read_b128 v[172:175], v149 offset:1024
	ds_read_b128 v[176:179], v149 offset:2048
	ds_read_b128 v[180:183], v149 offset:3072
	v_lshl_add_u64 v[192:193], v[142:143], 0, s[34:35]
	s_add_i32 m0, s58, 0xc000
	ds_read_b128 v[184:187], v148
	ds_read_b128 v[188:191], v148 offset:1024
	ds_read_b128 v[196:199], v148 offset:2048
	ds_read_b128 v[200:203], v148 offset:3072
	ds_read_b128 v[204:207], v148 offset:4096
	ds_read_b128 v[208:211], v148 offset:5120
	ds_read_b128 v[212:215], v148 offset:6144
	ds_read_b128 v[216:219], v148 offset:7168
	global_load_lds_dwordx4 v[192:193], off
	v_lshl_add_u64 v[192:193], v[144:145], 0, s[34:35]
	s_add_i32 m0, s58, 0xe000
	s_nop 0
	global_load_lds_dwordx4 v[192:193], off
	s_waitcnt vmcnt(8)
	s_waitcnt lgkmcnt(0)
	s_barrier
	s_setprio 1
	s_waitcnt lgkmcnt(0)
	v_mfma_f32_16x16x32_bf16 v[124:127], v[152:155], v[184:187], v[124:127]
	v_mfma_f32_16x16x32_bf16 v[120:123], v[160:163], v[184:187], v[120:123]
	v_mfma_f32_16x16x32_bf16 v[116:119], v[152:155], v[196:199], v[116:119]
	v_mfma_f32_16x16x32_bf16 v[112:115], v[160:163], v[196:199], v[112:115]
	v_mfma_f32_16x16x32_bf16 v[108:111], v[152:155], v[204:207], v[108:111]
	v_mfma_f32_16x16x32_bf16 v[100:103], v[160:163], v[204:207], v[100:103]
	v_mfma_f32_16x16x32_bf16 v[92:95], v[152:155], v[212:215], v[92:95]
	v_mfma_f32_16x16x32_bf16 v[84:87], v[160:163], v[212:215], v[84:87]
	v_mfma_f32_16x16x32_bf16 v[124:127], v[156:159], v[188:191], v[124:127]
	v_mfma_f32_16x16x32_bf16 v[120:123], v[164:167], v[188:191], v[120:123]
	v_mfma_f32_16x16x32_bf16 v[116:119], v[156:159], v[200:203], v[116:119]
	v_mfma_f32_16x16x32_bf16 v[112:115], v[164:167], v[200:203], v[112:115]
	v_mfma_f32_16x16x32_bf16 v[108:111], v[156:159], v[208:211], v[108:111]
	v_mfma_f32_16x16x32_bf16 v[100:103], v[164:167], v[208:211], v[100:103]
	v_mfma_f32_16x16x32_bf16 v[92:95], v[156:159], v[216:219], v[92:95]
	v_mfma_f32_16x16x32_bf16 v[84:87], v[164:167], v[216:219], v[84:87]
	s_setprio 0
	s_setprio 1
	v_mfma_f32_16x16x32_bf16 v[104:107], v[168:171], v[184:187], v[104:107]
	v_mfma_f32_16x16x32_bf16 v[96:99], v[176:179], v[184:187], v[96:99]
	v_mfma_f32_16x16x32_bf16 v[88:91], v[168:171], v[196:199], v[88:91]
	v_mfma_f32_16x16x32_bf16 v[80:83], v[176:179], v[196:199], v[80:83]
	v_mfma_f32_16x16x32_bf16 v[76:79], v[168:171], v[204:207], v[76:79]
	v_mfma_f32_16x16x32_bf16 v[72:75], v[176:179], v[204:207], v[72:75]
	v_mfma_f32_16x16x32_bf16 v[68:71], v[168:171], v[212:215], v[68:71]
	v_mfma_f32_16x16x32_bf16 v[64:67], v[176:179], v[212:215], v[64:67]
	v_mfma_f32_16x16x32_bf16 v[104:107], v[172:175], v[188:191], v[104:107]
	v_mfma_f32_16x16x32_bf16 v[96:99], v[180:183], v[188:191], v[96:99]
	v_mfma_f32_16x16x32_bf16 v[88:91], v[172:175], v[200:203], v[88:91]
	v_mfma_f32_16x16x32_bf16 v[80:83], v[180:183], v[200:203], v[80:83]
	v_mfma_f32_16x16x32_bf16 v[76:79], v[172:175], v[208:211], v[76:79]
	v_mfma_f32_16x16x32_bf16 v[72:75], v[180:183], v[208:211], v[72:75]
	v_mfma_f32_16x16x32_bf16 v[68:71], v[172:175], v[216:219], v[68:71]
	v_mfma_f32_16x16x32_bf16 v[64:67], v[180:183], v[216:219], v[64:67]
	s_setprio 0
	s_barrier
	s_add_i32 s70, s72, s57
	v_lshl_add_u64 v[192:193], s[36:37], 0, v[130:131]
	s_mov_b32 m0, s70
	ds_read_b128 v[184:187], v148 offset:16384
	ds_read_b128 v[188:191], v148 offset:17408
	ds_read_b128 v[196:199], v148 offset:18432
	ds_read_b128 v[200:203], v148 offset:19456
	ds_read_b128 v[204:207], v148 offset:20480
	ds_read_b128 v[208:211], v148 offset:21504
	ds_read_b128 v[212:215], v148 offset:22528
	ds_read_b128 v[216:219], v148 offset:23552
	global_load_lds_dwordx4 v[192:193], off
	s_add_i32 m0, s70, 0x2000
	s_add_u32 s70, s36, 0x200000
	v_lshl_add_u64 v[220:221], s[36:37], 0, v[134:135]
	s_addc_u32 s71, s37, 0
	s_add_i32 s72, s73, s57
	global_load_lds_dwordx4 v[220:221], off
	s_mov_b32 m0, s72
	v_lshl_add_u64 v[224:225], s[38:39], 0, v[132:133]
	global_load_lds_dwordx4 v130, s[70:71]
	s_add_i32 m0, s72, 0x2000
	s_nop 0
	global_load_lds_dwordx4 v134, s[70:71]
	v_lshl_add_u64 v[222:223], s[38:39], 0, v[128:129]
	s_mov_b32 m0, s58
	s_nop 0
	global_load_lds_dwordx4 v[222:223], off
	s_mov_b32 m0, s59
	s_nop 0
	global_load_lds_dwordx4 v[224:225], off
	s_waitcnt vmcnt(8)
	s_waitcnt lgkmcnt(0)
	s_barrier
	s_setprio 1
	s_waitcnt lgkmcnt(0)
	v_mfma_f32_16x16x32_bf16 v[60:63], v[152:155], v[184:187], v[60:63]
	v_mfma_f32_16x16x32_bf16 v[56:59], v[160:163], v[184:187], v[56:59]
	v_mfma_f32_16x16x32_bf16 v[52:55], v[152:155], v[196:199], v[52:55]
	v_mfma_f32_16x16x32_bf16 v[48:51], v[160:163], v[196:199], v[48:51]
	v_mfma_f32_16x16x32_bf16 v[44:47], v[152:155], v[204:207], v[44:47]
	v_mfma_f32_16x16x32_bf16 v[40:43], v[160:163], v[204:207], v[40:43]
	v_mfma_f32_16x16x32_bf16 v[32:35], v[152:155], v[212:215], v[32:35]
	v_mfma_f32_16x16x32_bf16 v[24:27], v[160:163], v[212:215], v[24:27]
	v_mfma_f32_16x16x32_bf16 v[60:63], v[156:159], v[188:191], v[60:63]
	v_mfma_f32_16x16x32_bf16 v[56:59], v[164:167], v[188:191], v[56:59]
	v_mfma_f32_16x16x32_bf16 v[52:55], v[156:159], v[200:203], v[52:55]
	v_mfma_f32_16x16x32_bf16 v[48:51], v[164:167], v[200:203], v[48:51]
	v_mfma_f32_16x16x32_bf16 v[44:47], v[156:159], v[208:211], v[44:47]
	v_mfma_f32_16x16x32_bf16 v[40:43], v[164:167], v[208:211], v[40:43]
	v_mfma_f32_16x16x32_bf16 v[32:35], v[156:159], v[216:219], v[32:35]
	v_mfma_f32_16x16x32_bf16 v[24:27], v[164:167], v[216:219], v[24:27]
	s_setprio 0
	s_setprio 1
	v_mfma_f32_16x16x32_bf16 v[36:39], v[168:171], v[184:187], v[36:39]
	v_mfma_f32_16x16x32_bf16 v[28:31], v[176:179], v[184:187], v[28:31]
	v_mfma_f32_16x16x32_bf16 v[20:23], v[168:171], v[196:199], v[20:23]
	v_mfma_f32_16x16x32_bf16 v[16:19], v[176:179], v[196:199], v[16:19]
	v_mfma_f32_16x16x32_bf16 v[12:15], v[168:171], v[204:207], v[12:15]
	v_mfma_f32_16x16x32_bf16 v[8:11], v[176:179], v[204:207], v[8:11]
	v_mfma_f32_16x16x32_bf16 v[4:7], v[168:171], v[212:215], v[4:7]
	v_mfma_f32_16x16x32_bf16 v[0:3], v[176:179], v[212:215], v[0:3]
	v_mfma_f32_16x16x32_bf16 v[36:39], v[172:175], v[188:191], v[36:39]
	v_mfma_f32_16x16x32_bf16 v[28:31], v[180:183], v[188:191], v[28:31]
	v_mfma_f32_16x16x32_bf16 v[20:23], v[172:175], v[200:203], v[20:23]
	v_mfma_f32_16x16x32_bf16 v[16:19], v[180:183], v[200:203], v[16:19]
	v_mfma_f32_16x16x32_bf16 v[12:15], v[172:175], v[208:211], v[12:15]
	v_mfma_f32_16x16x32_bf16 v[8:11], v[180:183], v[208:211], v[8:11]
	v_mfma_f32_16x16x32_bf16 v[4:7], v[172:175], v[216:219], v[4:7]
	v_mfma_f32_16x16x32_bf16 v[0:3], v[180:183], v[216:219], v[0:3]
	s_setprio 0
	s_barrier
	s_add_i32 s70, 0, 0x18000
	v_add_u32_e32 v149, s70, v136
	s_add_i32 s71, 0, 0x1c000
	ds_read_b128 v[152:155], v149
	ds_read_b128 v[156:159], v149 offset:1024
	ds_read_b128 v[160:163], v149 offset:2048
	ds_read_b128 v[164:167], v149 offset:3072
	v_add_u32_e32 v149, s71, v136
	ds_read_b128 v[168:171], v149
	ds_read_b128 v[172:175], v149 offset:1024
	ds_read_b128 v[176:179], v149 offset:2048
	ds_read_b128 v[180:183], v149 offset:3072
	s_add_u32 s38, s38, 0x200000
	s_addc_u32 s39, s39, 0
	s_mov_b32 m0, s60
	ds_read_b128 v[184:187], v148 offset:32768
	ds_read_b128 v[188:191], v148 offset:33792
	ds_read_b128 v[196:199], v148 offset:34816
	ds_read_b128 v[200:203], v148 offset:35840
	ds_read_b128 v[204:207], v148 offset:36864
	ds_read_b128 v[208:211], v148 offset:37888
	ds_read_b128 v[212:215], v148 offset:38912
	ds_read_b128 v[216:219], v148 offset:39936
	global_load_lds_dwordx4 v128, s[38:39]
	v_lshl_add_u64 v[226:227], s[38:39], 0, v[132:133]
	s_mov_b32 m0, s62
	s_nop 0
	global_load_lds_dwordx4 v[226:227], off
	s_waitcnt vmcnt(8)
	s_waitcnt lgkmcnt(0)
	s_barrier
	s_setprio 1
	s_waitcnt lgkmcnt(0)
	v_mfma_f32_16x16x32_bf16 v[124:127], v[152:155], v[184:187], v[124:127]
	v_mfma_f32_16x16x32_bf16 v[120:123], v[160:163], v[184:187], v[120:123]
	v_mfma_f32_16x16x32_bf16 v[116:119], v[152:155], v[196:199], v[116:119]
	v_mfma_f32_16x16x32_bf16 v[112:115], v[160:163], v[196:199], v[112:115]
	v_mfma_f32_16x16x32_bf16 v[108:111], v[152:155], v[204:207], v[108:111]
	v_mfma_f32_16x16x32_bf16 v[100:103], v[160:163], v[204:207], v[100:103]
	v_mfma_f32_16x16x32_bf16 v[92:95], v[152:155], v[212:215], v[92:95]
	v_mfma_f32_16x16x32_bf16 v[84:87], v[160:163], v[212:215], v[84:87]
	v_mfma_f32_16x16x32_bf16 v[124:127], v[156:159], v[188:191], v[124:127]
	v_mfma_f32_16x16x32_bf16 v[120:123], v[164:167], v[188:191], v[120:123]
	v_mfma_f32_16x16x32_bf16 v[116:119], v[156:159], v[200:203], v[116:119]
	v_mfma_f32_16x16x32_bf16 v[112:115], v[164:167], v[200:203], v[112:115]
	v_mfma_f32_16x16x32_bf16 v[108:111], v[156:159], v[208:211], v[108:111]
	v_mfma_f32_16x16x32_bf16 v[100:103], v[164:167], v[208:211], v[100:103]
	v_mfma_f32_16x16x32_bf16 v[92:95], v[156:159], v[216:219], v[92:95]
	v_mfma_f32_16x16x32_bf16 v[84:87], v[164:167], v[216:219], v[84:87]
	s_setprio 0
	s_setprio 1
	v_mfma_f32_16x16x32_bf16 v[104:107], v[168:171], v[184:187], v[104:107]
	v_mfma_f32_16x16x32_bf16 v[96:99], v[176:179], v[184:187], v[96:99]
	v_mfma_f32_16x16x32_bf16 v[88:91], v[168:171], v[196:199], v[88:91]
	v_mfma_f32_16x16x32_bf16 v[80:83], v[176:179], v[196:199], v[80:83]
	v_mfma_f32_16x16x32_bf16 v[76:79], v[168:171], v[204:207], v[76:79]
	v_mfma_f32_16x16x32_bf16 v[72:75], v[176:179], v[204:207], v[72:75]
	v_mfma_f32_16x16x32_bf16 v[68:71], v[168:171], v[212:215], v[68:71]
	v_mfma_f32_16x16x32_bf16 v[64:67], v[176:179], v[212:215], v[64:67]
	v_mfma_f32_16x16x32_bf16 v[104:107], v[172:175], v[188:191], v[104:107]
	v_mfma_f32_16x16x32_bf16 v[96:99], v[180:183], v[188:191], v[96:99]
	v_mfma_f32_16x16x32_bf16 v[88:91], v[172:175], v[200:203], v[88:91]
	v_mfma_f32_16x16x32_bf16 v[80:83], v[180:183], v[200:203], v[80:83]
	v_mfma_f32_16x16x32_bf16 v[76:79], v[172:175], v[208:211], v[76:79]
	v_mfma_f32_16x16x32_bf16 v[72:75], v[180:183], v[208:211], v[72:75]
	v_mfma_f32_16x16x32_bf16 v[68:71], v[172:175], v[216:219], v[68:71]
	v_mfma_f32_16x16x32_bf16 v[64:67], v[180:183], v[216:219], v[64:67]
	s_setprio 0
	s_barrier
	s_add_i32 s38, s70, s57
	v_lshl_add_u64 v[192:193], v[192:193], 0, s[4:5]
	s_mov_b32 m0, s38
	ds_read_b128 v[184:187], v148 offset:49152
	ds_read_b128 v[188:191], v148 offset:50176
	ds_read_b128 v[196:199], v148 offset:51200
	ds_read_b128 v[200:203], v148 offset:52224
	ds_read_b128 v[204:207], v148 offset:53248
	ds_read_b128 v[208:211], v148 offset:54272
	ds_read_b128 v[212:215], v148 offset:55296
	ds_read_b128 v[216:219], v148 offset:56320
	global_load_lds_dwordx4 v[192:193], off
	s_add_i32 m0, s38, 0x2000
	s_add_u32 s36, s36, 0x200080
	v_lshl_add_u64 v[192:193], v[220:221], 0, s[4:5]
	s_addc_u32 s37, s37, 0
	s_add_i32 s38, s71, s57
	global_load_lds_dwordx4 v[192:193], off
	s_mov_b32 m0, s38
	s_nop 0
	global_load_lds_dwordx4 v130, s[36:37]
	s_add_i32 m0, s38, 0x2000
	s_nop 0
	global_load_lds_dwordx4 v134, s[36:37]
	v_lshl_add_u64 v[192:193], v[222:223], 0, s[4:5]
	s_mov_b32 m0, s63
	s_nop 0
	global_load_lds_dwordx4 v[192:193], off
	v_lshl_add_u64 v[192:193], v[224:225], 0, s[4:5]
	s_mov_b32 m0, s64
	s_nop 0
	global_load_lds_dwordx4 v[192:193], off
	s_waitcnt vmcnt(8)
	s_waitcnt lgkmcnt(0)
	s_barrier
	s_setprio 1
	s_waitcnt lgkmcnt(0)
	v_mfma_f32_16x16x32_bf16 v[60:63], v[152:155], v[184:187], v[60:63]
	v_mfma_f32_16x16x32_bf16 v[56:59], v[160:163], v[184:187], v[56:59]
	v_mfma_f32_16x16x32_bf16 v[52:55], v[152:155], v[196:199], v[52:55]
	v_mfma_f32_16x16x32_bf16 v[48:51], v[160:163], v[196:199], v[48:51]
	v_mfma_f32_16x16x32_bf16 v[44:47], v[152:155], v[204:207], v[44:47]
	v_mfma_f32_16x16x32_bf16 v[40:43], v[160:163], v[204:207], v[40:43]
	v_mfma_f32_16x16x32_bf16 v[32:35], v[152:155], v[212:215], v[32:35]
	v_mfma_f32_16x16x32_bf16 v[24:27], v[160:163], v[212:215], v[24:27]
	v_mfma_f32_16x16x32_bf16 v[60:63], v[156:159], v[188:191], v[60:63]
	v_mfma_f32_16x16x32_bf16 v[56:59], v[164:167], v[188:191], v[56:59]
	v_mfma_f32_16x16x32_bf16 v[52:55], v[156:159], v[200:203], v[52:55]
	v_mfma_f32_16x16x32_bf16 v[48:51], v[164:167], v[200:203], v[48:51]
	v_mfma_f32_16x16x32_bf16 v[44:47], v[156:159], v[208:211], v[44:47]
	v_mfma_f32_16x16x32_bf16 v[40:43], v[164:167], v[208:211], v[40:43]
	v_mfma_f32_16x16x32_bf16 v[32:35], v[156:159], v[216:219], v[32:35]
	v_mfma_f32_16x16x32_bf16 v[24:27], v[164:167], v[216:219], v[24:27]
	s_setprio 0
	s_setprio 1
	v_mfma_f32_16x16x32_bf16 v[36:39], v[168:171], v[184:187], v[36:39]
	v_mfma_f32_16x16x32_bf16 v[28:31], v[176:179], v[184:187], v[28:31]
	v_mfma_f32_16x16x32_bf16 v[20:23], v[168:171], v[196:199], v[20:23]
	v_mfma_f32_16x16x32_bf16 v[16:19], v[176:179], v[196:199], v[16:19]
	v_mfma_f32_16x16x32_bf16 v[12:15], v[168:171], v[204:207], v[12:15]
	v_mfma_f32_16x16x32_bf16 v[8:11], v[176:179], v[204:207], v[8:11]
	v_mfma_f32_16x16x32_bf16 v[4:7], v[168:171], v[212:215], v[4:7]
	v_mfma_f32_16x16x32_bf16 v[0:3], v[176:179], v[212:215], v[0:3]
	v_mfma_f32_16x16x32_bf16 v[36:39], v[172:175], v[188:191], v[36:39]
	v_mfma_f32_16x16x32_bf16 v[28:31], v[180:183], v[188:191], v[28:31]
	v_mfma_f32_16x16x32_bf16 v[20:23], v[172:175], v[200:203], v[20:23]
	v_mfma_f32_16x16x32_bf16 v[16:19], v[180:183], v[200:203], v[16:19]
	v_mfma_f32_16x16x32_bf16 v[12:15], v[172:175], v[208:211], v[12:15]
	v_mfma_f32_16x16x32_bf16 v[8:11], v[180:183], v[208:211], v[8:11]
	v_mfma_f32_16x16x32_bf16 v[4:7], v[172:175], v[216:219], v[4:7]
	v_mfma_f32_16x16x32_bf16 v[0:3], v[180:183], v[216:219], v[0:3]
	s_setprio 0
	s_barrier
	s_add_i32 s69, s69, 2
	s_add_u32 s34, s34, 0x100
	s_addc_u32 s35, s35, 0
	s_cmp_gt_u32 s69, 5
	s_cbranch_scc0 .LBB0_1947
	s_cmpk_lt_u32 s56, 0x100
	s_cbranch_scc0 .LBB0_1941
	s_barrier
	s_branch .LBB0_1941
